# adds: P2 column tiles rotated across workgroups for epilogue balance, flat->global memory ops, v_rsq_f32 instead of IEEE sqrt+divide expansion for the 1/sqrt row scales
# speedup vs baseline: 1.0057x; 1.0057x over previous
;     __host__ __device__ bool next(int i, Unit& u) const {
;         const long L = (long)i * G + c; if (L >= (long)nwg * rep) return false;
;         int wgid = (int)(L % nwg); { const int q = nwg / NXCD, r = nwg % NXCD, xcd = wgid % NXCD, off = wgid / NXCD; wgid = (xcd < r ? xcd * (q + 1) : r * (q + 1) + (xcd - r) * q) + off; }
;         const int nig = WGM * nN, gid = wgid / nig, fm = gid * WGM, gsz = (nM - fm) < WGM ? (nM - fm) : WGM;
;         u.pm = fm + ((wgid % nig) % gsz); u.pn = (wgid % nig) / gsz; return true;
;     }
.LBB0_420:
	s_sext_i32_i16 s2, s4
	s_lshr_b32 s2, s2, 3
	s_add_i32 s2, s5, s2
	s_sext_i32_i16 s3, s2
	s_bfe_u32 s3, s3, 0x60019
	s_add_i32 s3, s2, s3
	s_sext_i32_i16 s4, s3
	s_and_b32 s3, s3, 0xffc0
	s_sub_i32 s2, s2, s3
	s_bfe_i32 s3, s2, 0x80000
	s_bfe_u32 s3, s3, 0x3000c
	s_add_i32 s3, s2, s3
	s_bfe_i32 s5, s3, 0x80000
	s_and_b32 s3, s3, 0xf8
	s_ashr_i32 s4, s4, 6
	s_sub_i32 s2, s2, s3
	s_lshl_b32 s4, s4, 3
	s_sext_i32_i16 s5, s5
	s_sext_i32_i8 s2, s2
	s_add_i32 s34, s4, s2
	s_ashr_i32 s36, s5, 3
	s_lshr_b32 s2, s67, 1
	s_add_i32 s2, s2, s36
	s_and_b32 s2, s2, 3
	s_and_b32 s36, s36, -4
	s_or_b32 s36, s36, s2

; __device__ __forceinline__ float ssq_val(ssq_t v) { return (float)v * SSQ_IFX; }
;     __device__ __forceinline__ void operator()(const f32x4 (&acc)[2][2][4][2], const Unit& u, int wr, int wc, int fr, int fq) const {
;         const int row0 = u.pm * BM + wr * 64 + fr; const int b = (u.pm * BM) >> 12;
;         ssq_t sv[8]; float rsv[8];
; #pragma unroll
;         for (int i = 0; i < 8; ++i) sv[i] = ssqx[row0 + (i >> 2) * HALF + (i & 3) * 16];
; #pragma unroll
;         for (int i = 0; i < 8; ++i) rsv[i] = 1.0f / sqrtf(ssq_val(sv[i]) * (1.0f / DM) + EPS);
; #pragma unroll
;         for (int bj = 0; bj < 2; ++bj) {
;             const int colw = u.pn * BM + bj * HALF + wc * 32, col0 = colw + 8 * fq;
;             const int mode = colw < 512 ? 1 : (colw < 640 ? 0 : (colw < 672 ? 2 : (colw < 1536 ? 0 : 3)));
;             const int stat = (colw >= PC_CQ && colw < PC_CKV) ? 1 : ((colw >= PC_CKV && colw < PC_CKV + 256) ? 2 : 0);
;             const float sc = colw < 384 ? QS_A : 1.f;
;             const f32x4 s0 = *(const f32x4*)(shw + (size_t)b * 7680 + col0), s1 = *(const f32x4*)(shw + (size_t)b * 7680 + col0 + 4);
; #pragma unroll
;             for (int ai = 0; ai < 2; ++ai)
; #pragma unroll
;                 for (int m = 0; m < 4; ++m) {
;                     const int row = row0 + ai * HALF + m * 16;
;                     const float rs = rsv[ai * 4 + m];
;                     f32x4 v0 = acc[ai][bj][m][0] * rs + s0, v1 = acc[ai][bj][m][1] * rs + s1;
.LBB0_425:
	s_lshl_b32 s2, s12, 8
	v_mbcnt_lo_u32_b32 v0, -1, 0
	v_mbcnt_hi_u32_b32 v0, -1, v0
	s_add_i32 s2, s2, s83
	v_and_b32_e32 v203, 15, v0
	v_or_b32_e32 v152, s2, v203
	v_ashrrev_i32_e32 v153, 31, v152
	v_lshl_add_u64 v[86:87], v[152:153], 3, s[28:29]
	global_load_dwordx2 v[88:89], v[86:87], off
	global_load_dwordx2 v[170:171], v[86:87], off offset:128
	global_load_dwordx2 v[168:169], v[86:87], off offset:256
	global_load_dwordx2 v[166:167], v[86:87], off offset:384
	global_load_dwordx2 v[164:165], v[86:87], off offset:1024
	global_load_dwordx2 v[162:163], v[86:87], off offset:1152
	global_load_dwordx2 v[160:161], v[86:87], off offset:1280
	global_load_dwordx2 v[158:159], v[86:87], off offset:1408
	v_bfe_u32 v202, v0, 4, 2
	s_lshl_b32 s35, s10, 8
	s_waitcnt vmcnt(0) lgkmcnt(0)
	v_ffbh_u32_e32 v0, v89
	v_min_u32_e32 v0, 32, v0
	v_lshlrev_b64 v[86:87], v0, v[88:89]
	v_min_u32_e32 v86, 1, v86
	v_or_b32_e32 v86, v87, v86
	v_cvt_f32_u32_e32 v86, v86
	v_sub_u32_e32 v0, 32, v0
	v_ldexp_f32 v0, v86, v0
	v_mul_f32_e32 v0, 0x33800000, v0
	v_fmamk_f32 v0, v0, 0x3a800000, v226
	s_ashr_i32 s2, s12, 4
	s_mul_hi_i32 s3, s2, 0x7800
	s_mul_i32 s11, s2, 0x7800
	s_or_b32 s2, s35, s66
	s_cmpk_lt_u32 s35, 0x600
	s_cselect_b32 s37, 0, 3
	s_cmpk_gt_u32 s2, 0x29f
	s_cselect_b32 s4, s37, 2
	s_cmpk_gt_u32 s35, 0x27f
	s_cselect_b32 s8, s4, 0
	s_cmpk_gt_i32 s2, 0x1ff
	s_cselect_b64 s[16:17], -1, 0
	s_and_b64 s[4:5], s[16:17], exec
	v_rsq_f32_e32 v154, v0
	s_nop 0
	v_lshlrev_b32_e32 v0, 3, v202
	s_cselect_b32 s4, s8, 1
	s_cmpk_lt_i32 s2, 0x180
	v_or_b32_e32 v156, s2, v0
	s_cselect_b64 s[8:9], -1, 0
	s_add_u32 s86, s96, s11
	s_addc_u32 s87, s97, s3
	v_ashrrev_i32_e32 v157, 31, v156
	v_lshl_add_u64 v[90:91], v[156:157], 2, s[86:87]
	global_load_dwordx4 v[86:89], v[90:91], off
	s_nop 0
	global_load_dwordx4 v[90:93], v[90:91], off offset:16
	s_add_i32 s3, s4, -1
	s_cmp_gt_u32 s3, 1
	s_cselect_b64 s[18:19], -1, 0
	s_cmp_eq_u32 s4, 3
	s_cselect_b64 s[10:11], -1, 0
	s_mov_b64 s[4:5], -1
	s_and_b64 vcc, exec, s[18:19]
	s_waitcnt vmcnt(0) lgkmcnt(0)
	v_pk_fma_f32 v[176:177], v[140:141], v[154:155], v[88:89] op_sel_hi:[1,0,1]
	v_pk_fma_f32 v[174:175], v[136:137], v[154:155], v[92:93] op_sel_hi:[1,0,1]
	v_cndmask_b32_e64 v136, 0, 1, s[10:11]
	v_pk_fma_f32 v[194:195], v[138:139], v[154:155], v[86:87] op_sel_hi:[1,0,1]
	v_pk_fma_f32 v[134:135], v[134:135], v[154:155], v[90:91] op_sel_hi:[1,0,1]
	v_cmp_ne_u32_e64 s[10:11], 1, v136
	s_cbranch_vccz .LBB0_429
	s_and_b64 vcc, exec, s[10:11]
	v_mov_b32_e32 v173, v177
	v_mov_b32_e32 v172, v176
	v_mov_b32_e32 v141, v195
	v_mov_b32_e32 v140, v194
	v_mov_b32_e32 v199, v175
	v_mov_b32_e32 v198, v174
	v_mov_b32_e32 v197, v135
	v_mov_b32_e32 v196, v134
	s_cbranch_vccnz .LBB0_428
; __device__ __forceinline__ f32x2 gelu_pk(f32x2 v) {
;     const f32x2 av = __builtin_elementwise_abs(v), d = av * 0.2316418882f + 1.0f;
;     f32x2 t; t.x = __builtin_amdgcn_rcpf(d.x); t.y = __builtin_amdgcn_rcpf(d.y);
;     f32x2 q = t * 0.5307027145f + (-0.7265760135f); q = q * t + 0.7107068705f; q = q * t + (-0.142248368f); q = q * t + 0.127414796f; q = q * t;
;     const f32x2 s = (v * v) * (-0.72134752044f);
;     f32x2 e; e.x = __builtin_amdgcn_exp2f(s.x); e.y = __builtin_amdgcn_exp2f(s.y);
;     const f32x2 m = v * (q * e), r = v - m;
;     f32x2 o; o.x = v.x < 0.f ? m.x : r.x; o.y = v.y < 0.f ? m.y : r.y; return o;
; }
;     __device__ __forceinline__ void operator()(const f32x4 (&acc)[2][2][4][2], const Unit& u, int wr, int wc, int fr, int fq) const {
;     ...
;                         const f32x2 a = gelu_pk((f32x2){v0[0], v0[1]}), bb = gelu_pk((f32x2){v0[2], v0[3]}), c = gelu_pk((f32x2){v1[0], v1[1]}), d = gelu_pk((f32x2){v1[2], v1[3]});
;                         v0 = (f32x4){a.x, a.y, bb.x, bb.y}; v1 = (f32x4){c.x, c.y, d.x, d.y};
	v_and_b32_e32 v137, 0x7fffffff, v195
	v_and_b32_e32 v136, 0x7fffffff, v194
	v_pk_fma_f32 v[136:137], v[136:137], s[62:63], 1.0 op_sel_hi:[1,0,0]
	s_mov_b32 s4, 0xbf3a00e3
	v_rcp_f32_e32 v136, v136
	v_rcp_f32_e32 v137, v137
	v_mov_b64_e32 v[138:139], s[4:5]
	v_cmp_gt_f32_e32 vcc, 0, v194
	v_pk_mul_f32 v[172:173], v[176:177], v[176:177]
	v_pk_fma_f32 v[140:141], v[136:137], s[64:65], v[138:139] op_sel_hi:[1,0,0]
	v_pk_mul_f32 v[172:173], v[172:173], s[74:75] op_sel_hi:[1,0]
	v_pk_fma_f32 v[140:141], v[136:137], v[140:141], s[68:69] op_sel_hi:[1,1,0]
	v_exp_f32_e32 v172, v172
	v_pk_fma_f32 v[140:141], v[136:137], v[140:141], s[70:71] op_sel_hi:[1,1,0]
	v_exp_f32_e32 v173, v173
	v_pk_fma_f32 v[140:141], v[136:137], v[140:141], s[72:73] op_sel_hi:[1,1,0]
	v_pk_mul_f32 v[180:181], v[134:135], v[134:135]
	v_pk_mul_f32 v[136:137], v[136:137], v[140:141]
	v_pk_mul_f32 v[140:141], v[194:195], v[194:195]
	v_pk_mul_f32 v[180:181], v[180:181], s[74:75] op_sel_hi:[1,0]
	v_pk_mul_f32 v[140:141], v[140:141], s[74:75] op_sel_hi:[1,0]
	v_exp_f32_e32 v180, v180
	v_exp_f32_e32 v140, v140
	v_exp_f32_e32 v141, v141
	v_exp_f32_e32 v181, v181
	v_pk_mul_f32 v[136:137], v[140:141], v[136:137]
	s_nop 0
	v_pk_mul_f32 v[140:141], v[194:195], v[136:137]
	v_pk_fma_f32 v[136:137], v[194:195], v[136:137], v[194:195] neg_lo:[1,0,0] neg_hi:[1,0,0]
	s_nop 0
	v_cndmask_b32_e32 v140, v136, v140, vcc
	v_cmp_gt_f32_e32 vcc, 0, v195
	v_and_b32_e32 v136, 0x7fffffff, v176
	s_nop 0
	v_cndmask_b32_e32 v141, v137, v141, vcc
	v_and_b32_e32 v137, 0x7fffffff, v177
	v_pk_fma_f32 v[136:137], v[136:137], s[62:63], 1.0 op_sel_hi:[1,0,0]
	v_cmp_gt_f32_e32 vcc, 0, v176
	v_rcp_f32_e32 v136, v136
	v_rcp_f32_e32 v137, v137
	s_nop 0
	v_pk_fma_f32 v[178:179], v[136:137], s[64:65], v[138:139] op_sel_hi:[1,0,0]
	s_nop 0
	v_pk_fma_f32 v[178:179], v[136:137], v[178:179], s[68:69] op_sel_hi:[1,1,0]
	s_nop 0
	v_pk_fma_f32 v[178:179], v[136:137], v[178:179], s[70:71] op_sel_hi:[1,1,0]
	s_nop 0
	v_pk_fma_f32 v[178:179], v[136:137], v[178:179], s[72:73] op_sel_hi:[1,1,0]
	s_nop 0
	v_pk_mul_f32 v[136:137], v[136:137], v[178:179]
	s_nop 0
	v_pk_mul_f32 v[136:137], v[172:173], v[136:137]
	s_nop 0
	v_pk_mul_f32 v[172:173], v[176:177], v[136:137]
	v_pk_fma_f32 v[136:137], v[176:177], v[136:137], v[176:177] neg_lo:[1,0,0] neg_hi:[1,0,0]
	s_nop 0
	v_cndmask_b32_e32 v172, v136, v172, vcc
	v_cmp_gt_f32_e32 vcc, 0, v177
	v_and_b32_e32 v136, 0x7fffffff, v134
	s_nop 0
	v_cndmask_b32_e32 v173, v137, v173, vcc
	v_and_b32_e32 v137, 0x7fffffff, v135
	v_pk_fma_f32 v[136:137], v[136:137], s[62:63], 1.0 op_sel_hi:[1,0,0]
	v_cmp_gt_f32_e32 vcc, 0, v134
	v_rcp_f32_e32 v136, v136
	v_rcp_f32_e32 v137, v137
	s_nop 0
	v_pk_fma_f32 v[178:179], v[136:137], s[64:65], v[138:139] op_sel_hi:[1,0,0]
	s_nop 0
	v_pk_fma_f32 v[178:179], v[136:137], v[178:179], s[68:69] op_sel_hi:[1,1,0]
	s_nop 0
	v_pk_fma_f32 v[178:179], v[136:137], v[178:179], s[70:71] op_sel_hi:[1,1,0]
	s_nop 0
	v_pk_fma_f32 v[178:179], v[136:137], v[178:179], s[72:73] op_sel_hi:[1,1,0]
	s_nop 0
	v_pk_mul_f32 v[136:137], v[136:137], v[178:179]
	v_pk_mul_f32 v[178:179], v[174:175], v[174:175]
	v_pk_mul_f32 v[136:137], v[180:181], v[136:137]
	s_nop 0
	v_pk_mul_f32 v[180:181], v[134:135], v[136:137]
	v_pk_fma_f32 v[136:137], v[134:135], v[136:137], v[134:135] neg_lo:[1,0,0] neg_hi:[1,0,0]
	s_nop 0
	v_cndmask_b32_e32 v196, v136, v180, vcc
	v_cmp_gt_f32_e32 vcc, 0, v135
	v_and_b32_e32 v136, 0x7fffffff, v174
	s_nop 0
	v_cndmask_b32_e32 v197, v137, v181, vcc
	v_and_b32_e32 v137, 0x7fffffff, v175
	v_pk_fma_f32 v[136:137], v[136:137], s[62:63], 1.0 op_sel_hi:[1,0,0]
	v_cmp_gt_f32_e32 vcc, 0, v174
	v_rcp_f32_e32 v136, v136
	v_rcp_f32_e32 v137, v137
	s_nop 0
	v_pk_fma_f32 v[138:139], v[136:137], s[64:65], v[138:139] op_sel_hi:[1,0,0]
	s_nop 0
	v_pk_fma_f32 v[138:139], v[136:137], v[138:139], s[68:69] op_sel_hi:[1,1,0]
	s_nop 0
	v_pk_fma_f32 v[138:139], v[136:137], v[138:139], s[70:71] op_sel_hi:[1,1,0]
	s_nop 0
	v_pk_fma_f32 v[138:139], v[136:137], v[138:139], s[72:73] op_sel_hi:[1,1,0]
	s_nop 0
	v_pk_mul_f32 v[136:137], v[136:137], v[138:139]
	v_pk_mul_f32 v[138:139], v[178:179], s[74:75] op_sel_hi:[1,0]
	s_nop 0
	v_exp_f32_e32 v138, v138
	v_exp_f32_e32 v139, v139
	s_nop 0
	v_pk_mul_f32 v[136:137], v[138:139], v[136:137]
	s_nop 0
	v_pk_mul_f32 v[138:139], v[174:175], v[136:137]
	v_pk_fma_f32 v[136:137], v[174:175], v[136:137], v[174:175] neg_lo:[1,0,0] neg_hi:[1,0,0]
	s_nop 0
	v_cndmask_b32_e32 v198, v136, v138, vcc
	v_cmp_gt_f32_e32 vcc, 0, v175
	s_nop 1
	v_cndmask_b32_e32 v199, v137, v139, vcc

; __device__ __forceinline__ float ssq_val(ssq_t v) { return (float)v * SSQ_IFX; }
;     __device__ __forceinline__ void operator()(const f32x4 (&acc)[2][2][4][2], const Unit& u, int wr, int wc, int fr, int fq) const {
;     ...
;         for (int i = 0; i < 8; ++i) rsv[i] = QS_B / sqrtf(ssq_val(sv[i]) * (1.0f / 384.0f) + EPS);
; #pragma unroll
;         for (int ai = 0; ai < 2; ++ai)
; #pragma unroll
;             for (int m = 0; m < 4; ++m) {
;                 const int row = row0 + ai * HALF + m * 16;
;                 const float rs = rsv[ai * 4 + m];
; #pragma unroll
;                 for (int bj = 0; bj < 2; ++bj) {
;                     const int colw = u.pn * BM + bj * HALF + wc * 32, col0 = colw + 8 * fq;
;                     const bool rope = (colw % 96) == 64 && colw < 576;
;                     f32x4 v0 = acc[ai][bj][m][0] * rs, v1 = acc[ai][bj][m][1] * rs;
;                     if (rope) {
;                         const float* tp = ropB + ((size_t)row * 16 + ((col0 - colw) >> 1)) * 2;
;                         const f32x4 c0 = *(const f32x4*)tp, c1 = *(const f32x4*)(tp + 4);
;                         f32x4 w0, w1;
;                         w0[0] = v0[0] * c0[0] - v0[1] * c0[1]; w0[1] = v0[1] * c0[0] + v0[0] * c0[1];
;                         w0[2] = v0[2] * c0[2] - v0[3] * c0[3]; w0[3] = v0[3] * c0[2] + v0[2] * c0[3];
;                         w1[0] = v1[0] * c1[0] - v1[1] * c1[1]; w1[1] = v1[1] * c1[0] + v1[0] * c1[1];
;                         w1[2] = v1[2] * c1[2] - v1[3] * c1[3]; w1[3] = v1[3] * c1[2] + v1[2] * c1[3];
;                         v0 = w0; v1 = w1;
;                     }
.LBB0_713:
	s_lshl_b32 s2, s31, 8
	s_add_i32 s2, s2, s4
	v_mbcnt_lo_u32_b32 v0, -1, 0
	v_mbcnt_hi_u32_b32 v0, -1, v0
	s_nop 0
	v_and_or_b32 v140, v0, 15, s2
	v_ashrrev_i32_e32 v141, 31, v140
	v_lshl_add_u64 v[142:143], v[140:141], 3, s[18:19]
	global_load_dwordx2 v[156:157], v[142:143], off
	global_load_dwordx2 v[154:155], v[142:143], off offset:128
	global_load_dwordx2 v[152:153], v[142:143], off offset:256
	global_load_dwordx2 v[150:151], v[142:143], off offset:384
	global_load_dwordx2 v[148:149], v[142:143], off offset:1024
	global_load_dwordx2 v[146:147], v[142:143], off offset:1152
	global_load_dwordx2 v[144:145], v[142:143], off offset:1280
	s_nop 0
	global_load_dwordx2 v[142:143], v[142:143], off offset:1408
	v_lshrrev_b32_e32 v0, 1, v0
	v_and_b32_e32 v0, 24, v0
	v_lshlrev_b64 v[166:167], 7, v[140:141]
	s_waitcnt vmcnt(0) lgkmcnt(0)
	v_ffbh_u32_e32 v158, v157
	v_min_u32_e32 v158, 32, v158
	v_lshlrev_b64 v[156:157], v158, v[156:157]
	v_min_u32_e32 v156, 1, v156
	v_or_b32_e32 v156, v157, v156
	v_cvt_f32_u32_e32 v156, v156
	v_sub_u32_e32 v157, 32, v158
	v_ldexp_f32 v156, v156, v157
	v_mul_f32_e32 v156, 0x33800000, v156
	v_fmamk_f32 v156, v156, 0x3b2aaaab, v226
	s_lshl_b32 s2, s30, 8
	s_or_b32 s30, s2, s5
	s_mul_hi_i32 s2, s30, 0x2aaaaaab
	s_lshr_b32 s3, s2, 31
	s_lshr_b32 s2, s2, 4
	s_add_i32 s2, s2, s3
	s_mulk_i32 s2, 0x60
	s_sub_i32 s2, s30, s2
	s_cmp_eq_u32 s2, 64
	s_cselect_b64 s[2:3], -1, 0
	s_cmpk_lt_i32 s30, 0x240
	s_cselect_b64 s[8:9], -1, 0
	v_rsq_f32_e32 v156, v156
	s_nop 0
	v_mul_f32_e32 v156, s69, v156
	s_and_b64 s[2:3], s[8:9], s[2:3]
	v_pk_mul_f32 v[158:159], v[126:127], v[156:157] op_sel_hi:[1,0]
	v_cndmask_b32_e64 v126, 0, 1, s[2:3]
	v_pk_mul_f32 v[162:163], v[128:129], v[156:157] op_sel_hi:[1,0]
	v_pk_mul_f32 v[160:161], v[132:133], v[156:157] op_sel_hi:[1,0]
	v_pk_mul_f32 v[130:131], v[130:131], v[156:157] op_sel_hi:[1,0]
	v_cmp_ne_u32_e64 s[8:9], 1, v126
	s_andn2_b64 vcc, exec, s[2:3]
	v_lshl_add_u64 v[132:133], s[20:21], 0, v[166:167]
	v_lshlrev_b32_e32 v126, 2, v0
	s_cbranch_vccnz .LBB0_715
	v_mov_b32_e32 v127, v1
	v_lshl_add_u64 v[128:129], v[132:133], 0, v[126:127]
	global_load_dwordx4 v[166:169], v[128:129], off
	global_load_dwordx4 v[170:173], v[128:129], off offset:16
	s_waitcnt vmcnt(0) lgkmcnt(0)
	v_pk_mul_f32 v[174:175], v[158:159], v[166:167] op_sel:[1,1] op_sel_hi:[0,1]
	v_pk_mul_f32 v[128:129], v[158:159], v[166:167]
	v_pk_fma_f32 v[158:159], v[158:159], v[166:167], v[174:175] op_sel_hi:[1,0,1]
	v_pk_mul_f32 v[176:177], v[130:131], v[170:171] op_sel:[1,1] op_sel_hi:[0,1]
	v_mul_f32_e32 v158, v163, v169
	v_pk_fma_f32 v[166:167], v[162:163], v[168:169], v[158:159] op_sel_hi:[1,1,0] neg_lo:[0,0,1] neg_hi:[0,0,1]
	v_mul_f32_e32 v158, v162, v169
	v_pk_fma_f32 v[168:169], v[162:163], v[168:169], v[158:159] op_sel:[1,0,0] op_sel_hi:[0,1,0]
	v_pk_mul_f32 v[162:163], v[130:131], v[170:171]
	v_pk_fma_f32 v[130:131], v[130:131], v[170:171], v[176:177] op_sel_hi:[1,0,1]
	v_sub_f32_e32 v158, v128, v174
	v_mul_f32_e32 v130, v161, v173
	v_pk_fma_f32 v[170:171], v[160:161], v[172:173], v[130:131] op_sel_hi:[1,1,0] neg_lo:[0,0,1] neg_hi:[0,0,1]
	v_mul_f32_e32 v130, v160, v173
	v_pk_fma_f32 v[172:173], v[160:161], v[172:173], v[130:131] op_sel:[1,0,0] op_sel_hi:[0,1,0]
	v_sub_f32_e32 v130, v162, v176
	v_mov_b32_e32 v162, v166
	v_mov_b32_e32 v163, v168
	v_mov_b32_e32 v160, v170
	v_mov_b32_e32 v161, v172

; __device__ __forceinline__ unsigned cvt_pk_bf16(float lo, float hi) { unsigned r; asm volatile("v_cvt_pk_bf16_f32 %0, %1, %2" : "=v"(r) : "v"(lo), "v"(hi)); return r; }
; __device__ __forceinline__ float ssq_val(ssq_t v) { return (float)v * SSQ_IFX; }
;     __device__ __forceinline__ void operator()(const f32x4 (&acc)[2][2][4][2], const Unit& u, int wr, int wc, int fr, int fq) const {
;     ...
;         for (int i = 0; i < 8; ++i) rsv[i] = QS_B / sqrtf(ssq_val(sv[i]) * (1.0f / 384.0f) + EPS);
; #pragma unroll
;         for (int ai = 0; ai < 2; ++ai)
; #pragma unroll
;             for (int m = 0; m < 4; ++m) {
;                 const int row = row0 + ai * HALF + m * 16;
;                 const float rs = rsv[ai * 4 + m];
; #pragma unroll
;                 for (int bj = 0; bj < 2; ++bj) {
;                     const int colw = u.pn * BM + bj * HALF + wc * 32, col0 = colw + 8 * fq;
;                     const bool rope = (colw % 96) == 64 && colw < 576;
;                     f32x4 v0 = acc[ai][bj][m][0] * rs, v1 = acc[ai][bj][m][1] * rs;
;                     if (rope) {
;                         const float* tp = ropB + ((size_t)row * 16 + ((col0 - colw) >> 1)) * 2;
;                         const f32x4 c0 = *(const f32x4*)tp, c1 = *(const f32x4*)(tp + 4);
;                         f32x4 w0, w1;
;                         w0[0] = v0[0] * c0[0] - v0[1] * c0[1]; w0[1] = v0[1] * c0[0] + v0[0] * c0[1];
;                         w0[2] = v0[2] * c0[2] - v0[3] * c0[3]; w0[3] = v0[3] * c0[2] + v0[2] * c0[3];
;                         w1[0] = v1[0] * c1[0] - v1[1] * c1[1]; w1[1] = v1[1] * c1[0] + v1[0] * c1[1];
;                         w1[2] = v1[2] * c1[2] - v1[3] * c1[3]; w1[3] = v1[3] * c1[2] + v1[2] * c1[3];
;                         v0 = w0; v1 = w1;
;                     }
;                     u32x4 w; w.x = cvt_pk_bf16(v0[0], v0[1]); w.y = cvt_pk_bf16(v0[2], v0[3]); w.z = cvt_pk_bf16(v1[0], v1[1]); w.w = cvt_pk_bf16(v1[2], v1[3]);
;                     *(u32x4*)(O + (size_t)row * QMP + col0) = w;
.LBB0_717:
	v_ffbh_u32_e32 v120, v155
	v_min_u32_e32 v127, 32, v120
	v_lshlrev_b64 v[120:121], v127, v[154:155]
	v_min_u32_e32 v120, 1, v120
	v_or_b32_e32 v120, v121, v120
	v_cvt_f32_u32_e32 v120, v120
	v_sub_u32_e32 v121, 32, v127
	s_ashr_i32 s31, s30, 31
	v_cvt_pk_bf16_f32 v154, v122, v123
	v_ldexp_f32 v120, v120, v121
	v_mul_f32_e32 v120, 0x33800000, v120
	v_fmamk_f32 v120, v120, 0x3b2aaaab, v226
	v_cvt_pk_bf16_f32 v155, v158, v159
	v_cvt_pk_bf16_f32 v156, v118, v119
	v_lshl_add_u64 v[118:119], v[0:1], 0, s[30:31]
	v_lshl_add_u64 v[122:123], v[118:119], 1, v[130:131]
	v_cvt_pk_bf16_f32 v157, v124, v125
	global_store_dwordx4 v[122:123], v[154:157], off offset:256
	v_or_b32_e32 v122, 16, v140
	v_ashrrev_i32_e32 v123, 31, v122
	v_lshlrev_b64 v[130:131], 7, v[122:123]
	v_rsq_f32_e32 v120, v120
	s_nop 0
	v_mul_f32_e32 v120, s69, v120
	v_pk_mul_f32 v[124:125], v[116:117], v[120:121] op_sel_hi:[1,0]
	v_pk_mul_f32 v[114:115], v[114:115], v[120:121] op_sel_hi:[1,0]
	v_pk_mul_f32 v[116:117], v[112:113], v[120:121] op_sel_hi:[1,0]
	v_pk_mul_f32 v[110:111], v[110:111], v[120:121] op_sel_hi:[1,0]
	s_and_b64 vcc, exec, s[8:9]
	v_lshl_add_u64 v[112:113], s[20:21], 0, v[130:131]
	s_cbranch_vccnz .LBB0_719
	v_mov_b32_e32 v127, v1
	v_lshl_add_u64 v[154:155], v[112:113], 0, v[126:127]
	global_load_dwordx4 v[130:133], v[154:155], off
	s_nop 0
	global_load_dwordx4 v[154:157], v[154:155], off offset:16
	s_waitcnt vmcnt(0) lgkmcnt(0)
	v_pk_mul_f32 v[160:161], v[114:115], v[130:131] op_sel:[1,1] op_sel_hi:[0,1]
	v_mul_f32_e32 v0, v125, v133
	v_pk_mul_f32 v[158:159], v[114:115], v[130:131]
	v_pk_fma_f32 v[114:115], v[114:115], v[130:131], v[160:161] op_sel_hi:[1,0,1]
	v_pk_fma_f32 v[130:131], v[124:125], v[132:133], v[0:1] op_sel_hi:[1,1,0] neg_lo:[0,0,1] neg_hi:[0,0,1]
	v_mul_f32_e32 v0, v124, v133
	v_pk_fma_f32 v[132:133], v[124:125], v[132:133], v[0:1] op_sel:[1,0,0] op_sel_hi:[0,1,0]
	v_pk_mul_f32 v[162:163], v[110:111], v[154:155] op_sel:[1,1] op_sel_hi:[0,1]
	v_mul_f32_e32 v0, v117, v157
	v_pk_mul_f32 v[124:125], v[110:111], v[154:155]
	v_pk_fma_f32 v[110:111], v[110:111], v[154:155], v[162:163] op_sel_hi:[1,0,1]
	v_pk_fma_f32 v[154:155], v[116:117], v[156:157], v[0:1] op_sel_hi:[1,1,0] neg_lo:[0,0,1] neg_hi:[0,0,1]
	v_mul_f32_e32 v0, v116, v157
	v_pk_fma_f32 v[156:157], v[116:117], v[156:157], v[0:1] op_sel:[1,0,0] op_sel_hi:[0,1,0]
	v_sub_f32_e32 v114, v158, v160
	v_sub_f32_e32 v110, v124, v162
	v_mov_b32_e32 v124, v130
	v_mov_b32_e32 v125, v132
	v_mov_b32_e32 v116, v154
	v_mov_b32_e32 v117, v156

; __device__ __forceinline__ unsigned cvt_pk_bf16(float lo, float hi) { unsigned r; asm volatile("v_cvt_pk_bf16_f32 %0, %1, %2" : "=v"(r) : "v"(lo), "v"(hi)); return r; }
; __device__ __forceinline__ float ssq_val(ssq_t v) { return (float)v * SSQ_IFX; }
;     __device__ __forceinline__ void operator()(const f32x4 (&acc)[2][2][4][2], const Unit& u, int wr, int wc, int fr, int fq) const {
;     ...
;         for (int i = 0; i < 8; ++i) rsv[i] = QS_B / sqrtf(ssq_val(sv[i]) * (1.0f / 384.0f) + EPS);
; #pragma unroll
;         for (int ai = 0; ai < 2; ++ai)
; #pragma unroll
;             for (int m = 0; m < 4; ++m) {
;                 const int row = row0 + ai * HALF + m * 16;
;                 const float rs = rsv[ai * 4 + m];
; #pragma unroll
;                 for (int bj = 0; bj < 2; ++bj) {
;                     const int colw = u.pn * BM + bj * HALF + wc * 32, col0 = colw + 8 * fq;
;                     const bool rope = (colw % 96) == 64 && colw < 576;
;                     f32x4 v0 = acc[ai][bj][m][0] * rs, v1 = acc[ai][bj][m][1] * rs;
;                     if (rope) {
;                         const float* tp = ropB + ((size_t)row * 16 + ((col0 - colw) >> 1)) * 2;
;                         const f32x4 c0 = *(const f32x4*)tp, c1 = *(const f32x4*)(tp + 4);
;                         f32x4 w0, w1;
;                         w0[0] = v0[0] * c0[0] - v0[1] * c0[1]; w0[1] = v0[1] * c0[0] + v0[0] * c0[1];
;                         w0[2] = v0[2] * c0[2] - v0[3] * c0[3]; w0[3] = v0[3] * c0[2] + v0[2] * c0[3];
;                         w1[0] = v1[0] * c1[0] - v1[1] * c1[1]; w1[1] = v1[1] * c1[0] + v1[0] * c1[1];
;                         w1[2] = v1[2] * c1[2] - v1[3] * c1[3]; w1[3] = v1[3] * c1[2] + v1[2] * c1[3];
;                         v0 = w0; v1 = w1;
;                     }
;                     u32x4 w; w.x = cvt_pk_bf16(v0[0], v0[1]); w.y = cvt_pk_bf16(v0[2], v0[3]); w.z = cvt_pk_bf16(v1[0], v1[1]); w.w = cvt_pk_bf16(v1[2], v1[3]);
;                     *(u32x4*)(O + (size_t)row * QMP + col0) = w;
.LBB0_721:
	v_ffbh_u32_e32 v0, v153
	v_min_u32_e32 v0, 32, v0
	v_lshlrev_b64 v[104:105], v0, v[152:153]
	v_min_u32_e32 v104, 1, v104
	v_or_b32_e32 v104, v105, v104
	v_cvt_f32_u32_e32 v104, v104
	v_sub_u32_e32 v0, 32, v0
	v_ldexp_f32 v0, v104, v0
	v_mul_f32_e32 v0, 0x33800000, v0
	v_fmamk_f32 v0, v0, 0x3b2aaaab, v226
	v_cvt_pk_bf16_f32 v112, v106, v107
	v_cvt_pk_bf16_f32 v113, v114, v115
	v_cvt_pk_bf16_f32 v114, v102, v103
	v_lshl_add_u64 v[102:103], v[118:119], 1, v[110:111]
	v_cvt_pk_bf16_f32 v115, v108, v109
	global_store_dwordx4 v[102:103], v[112:115], off offset:256
	v_or_b32_e32 v102, 32, v140
	v_ashrrev_i32_e32 v103, 31, v102
	v_rsq_f32_e32 v104, v0
	s_nop 0
	v_mul_f32_e32 v104, s69, v104
	v_lshlrev_b64 v[108:109], 7, v[102:103]
	v_pk_mul_f32 v[106:107], v[100:101], v[104:105] op_sel_hi:[1,0]
	v_pk_mul_f32 v[98:99], v[98:99], v[104:105] op_sel_hi:[1,0]
	v_pk_mul_f32 v[100:101], v[96:97], v[104:105] op_sel_hi:[1,0]
	v_pk_mul_f32 v[94:95], v[94:95], v[104:105] op_sel_hi:[1,0]
	s_and_b64 vcc, exec, s[8:9]
	v_lshl_add_u64 v[96:97], s[20:21], 0, v[108:109]
	s_cbranch_vccnz .LBB0_723
	v_mov_b32_e32 v127, v1
	v_lshl_add_u64 v[112:113], v[96:97], 0, v[126:127]
	global_load_dwordx4 v[108:111], v[112:113], off
	s_nop 0
	global_load_dwordx4 v[112:115], v[112:113], off offset:16
	s_waitcnt vmcnt(0) lgkmcnt(0)
	v_pk_mul_f32 v[120:121], v[98:99], v[108:109] op_sel:[1,1] op_sel_hi:[0,1]
	v_mul_f32_e32 v0, v107, v111
	v_pk_mul_f32 v[116:117], v[98:99], v[108:109]
	v_pk_fma_f32 v[98:99], v[98:99], v[108:109], v[120:121] op_sel_hi:[1,0,1]
	v_pk_fma_f32 v[108:109], v[106:107], v[110:111], v[0:1] op_sel_hi:[1,1,0] neg_lo:[0,0,1] neg_hi:[0,0,1]
	v_mul_f32_e32 v0, v106, v111
	v_pk_fma_f32 v[110:111], v[106:107], v[110:111], v[0:1] op_sel:[1,0,0] op_sel_hi:[0,1,0]
	v_pk_mul_f32 v[122:123], v[94:95], v[112:113] op_sel:[1,1] op_sel_hi:[0,1]
	v_mul_f32_e32 v0, v101, v115
	v_pk_mul_f32 v[106:107], v[94:95], v[112:113]
	v_pk_fma_f32 v[94:95], v[94:95], v[112:113], v[122:123] op_sel_hi:[1,0,1]
	v_pk_fma_f32 v[112:113], v[100:101], v[114:115], v[0:1] op_sel_hi:[1,1,0] neg_lo:[0,0,1] neg_hi:[0,0,1]
	v_mul_f32_e32 v0, v100, v115
	v_pk_fma_f32 v[114:115], v[100:101], v[114:115], v[0:1] op_sel:[1,0,0] op_sel_hi:[0,1,0]
	v_sub_f32_e32 v98, v116, v120
	v_sub_f32_e32 v94, v106, v122
	v_mov_b32_e32 v106, v108
	v_mov_b32_e32 v107, v110
	v_mov_b32_e32 v100, v112
	v_mov_b32_e32 v101, v114

; __device__ __forceinline__ unsigned cvt_pk_bf16(float lo, float hi) { unsigned r; asm volatile("v_cvt_pk_bf16_f32 %0, %1, %2" : "=v"(r) : "v"(lo), "v"(hi)); return r; }
; __device__ __forceinline__ float ssq_val(ssq_t v) { return (float)v * SSQ_IFX; }
;     __device__ __forceinline__ void operator()(const f32x4 (&acc)[2][2][4][2], const Unit& u, int wr, int wc, int fr, int fq) const {
;     ...
;         for (int i = 0; i < 8; ++i) rsv[i] = QS_B / sqrtf(ssq_val(sv[i]) * (1.0f / 384.0f) + EPS);
; #pragma unroll
;         for (int ai = 0; ai < 2; ++ai)
; #pragma unroll
;             for (int m = 0; m < 4; ++m) {
;                 const int row = row0 + ai * HALF + m * 16;
;                 const float rs = rsv[ai * 4 + m];
; #pragma unroll
;                 for (int bj = 0; bj < 2; ++bj) {
;                     const int colw = u.pn * BM + bj * HALF + wc * 32, col0 = colw + 8 * fq;
;                     const bool rope = (colw % 96) == 64 && colw < 576;
;                     f32x4 v0 = acc[ai][bj][m][0] * rs, v1 = acc[ai][bj][m][1] * rs;
;                     if (rope) {
;                         const float* tp = ropB + ((size_t)row * 16 + ((col0 - colw) >> 1)) * 2;
;                         const f32x4 c0 = *(const f32x4*)tp, c1 = *(const f32x4*)(tp + 4);
;                         f32x4 w0, w1;
;                         w0[0] = v0[0] * c0[0] - v0[1] * c0[1]; w0[1] = v0[1] * c0[0] + v0[0] * c0[1];
;                         w0[2] = v0[2] * c0[2] - v0[3] * c0[3]; w0[3] = v0[3] * c0[2] + v0[2] * c0[3];
;                         w1[0] = v1[0] * c1[0] - v1[1] * c1[1]; w1[1] = v1[1] * c1[0] + v1[0] * c1[1];
;                         w1[2] = v1[2] * c1[2] - v1[3] * c1[3]; w1[3] = v1[3] * c1[2] + v1[2] * c1[3];
;                         v0 = w0; v1 = w1;
;                     }
;                     u32x4 w; w.x = cvt_pk_bf16(v0[0], v0[1]); w.y = cvt_pk_bf16(v0[2], v0[3]); w.z = cvt_pk_bf16(v1[0], v1[1]); w.w = cvt_pk_bf16(v1[2], v1[3]);
;                     *(u32x4*)(O + (size_t)row * QMP + col0) = w;
.LBB0_725:
	v_ffbh_u32_e32 v0, v151
	v_min_u32_e32 v0, 32, v0
	v_lshlrev_b64 v[88:89], v0, v[150:151]
	v_min_u32_e32 v88, 1, v88
	v_or_b32_e32 v88, v89, v88
	v_cvt_f32_u32_e32 v88, v88
	v_sub_u32_e32 v0, 32, v0
	v_ldexp_f32 v0, v88, v0
	v_mul_f32_e32 v0, 0x33800000, v0
	v_fmamk_f32 v0, v0, 0x3b2aaaab, v226
	v_cvt_pk_bf16_f32 v96, v90, v91
	v_cvt_pk_bf16_f32 v97, v98, v99
	v_cvt_pk_bf16_f32 v98, v86, v87
	v_lshl_add_u64 v[86:87], v[118:119], 1, v[94:95]
	v_cvt_pk_bf16_f32 v99, v92, v93
	global_store_dwordx4 v[86:87], v[96:99], off offset:256
	v_or_b32_e32 v86, 48, v140
	v_ashrrev_i32_e32 v87, 31, v86
	v_rsq_f32_e32 v88, v0
	s_nop 0
	v_mul_f32_e32 v88, s69, v88
	v_lshlrev_b64 v[92:93], 7, v[86:87]
	v_pk_mul_f32 v[90:91], v[84:85], v[88:89] op_sel_hi:[1,0]
	v_pk_mul_f32 v[82:83], v[82:83], v[88:89] op_sel_hi:[1,0]
	v_pk_mul_f32 v[84:85], v[80:81], v[88:89] op_sel_hi:[1,0]
	v_pk_mul_f32 v[78:79], v[78:79], v[88:89] op_sel_hi:[1,0]
	s_and_b64 vcc, exec, s[8:9]
	v_lshl_add_u64 v[80:81], s[20:21], 0, v[92:93]
	s_cbranch_vccnz .LBB0_727
	v_mov_b32_e32 v127, v1
	v_lshl_add_u64 v[96:97], v[80:81], 0, v[126:127]
	global_load_dwordx4 v[92:95], v[96:97], off
	s_nop 0
	global_load_dwordx4 v[96:99], v[96:97], off offset:16
	s_waitcnt vmcnt(0) lgkmcnt(0)
	v_pk_mul_f32 v[102:103], v[82:83], v[92:93] op_sel:[1,1] op_sel_hi:[0,1]
	v_mul_f32_e32 v0, v91, v95
	v_pk_mul_f32 v[100:101], v[82:83], v[92:93]
	v_pk_fma_f32 v[82:83], v[82:83], v[92:93], v[102:103] op_sel_hi:[1,0,1]
	v_pk_fma_f32 v[92:93], v[90:91], v[94:95], v[0:1] op_sel_hi:[1,1,0] neg_lo:[0,0,1] neg_hi:[0,0,1]
	v_mul_f32_e32 v0, v90, v95
	v_pk_fma_f32 v[94:95], v[90:91], v[94:95], v[0:1] op_sel:[1,0,0] op_sel_hi:[0,1,0]
	v_pk_mul_f32 v[104:105], v[78:79], v[96:97] op_sel:[1,1] op_sel_hi:[0,1]
	v_mul_f32_e32 v0, v85, v99
	v_pk_mul_f32 v[90:91], v[78:79], v[96:97]
	v_pk_fma_f32 v[78:79], v[78:79], v[96:97], v[104:105] op_sel_hi:[1,0,1]
	v_pk_fma_f32 v[96:97], v[84:85], v[98:99], v[0:1] op_sel_hi:[1,1,0] neg_lo:[0,0,1] neg_hi:[0,0,1]
	v_mul_f32_e32 v0, v84, v99
	v_pk_fma_f32 v[98:99], v[84:85], v[98:99], v[0:1] op_sel:[1,0,0] op_sel_hi:[0,1,0]
	v_sub_f32_e32 v82, v100, v102
	v_sub_f32_e32 v78, v90, v104
	v_mov_b32_e32 v90, v92
	v_mov_b32_e32 v91, v94
	v_mov_b32_e32 v84, v96
	v_mov_b32_e32 v85, v98

; __device__ __forceinline__ unsigned cvt_pk_bf16(float lo, float hi) { unsigned r; asm volatile("v_cvt_pk_bf16_f32 %0, %1, %2" : "=v"(r) : "v"(lo), "v"(hi)); return r; }
; __device__ __forceinline__ float ssq_val(ssq_t v) { return (float)v * SSQ_IFX; }
;     __device__ __forceinline__ void operator()(const f32x4 (&acc)[2][2][4][2], const Unit& u, int wr, int wc, int fr, int fq) const {
;     ...
;         for (int i = 0; i < 8; ++i) rsv[i] = QS_B / sqrtf(ssq_val(sv[i]) * (1.0f / 384.0f) + EPS);
; #pragma unroll
;         for (int ai = 0; ai < 2; ++ai)
; #pragma unroll
;             for (int m = 0; m < 4; ++m) {
;                 const int row = row0 + ai * HALF + m * 16;
;                 const float rs = rsv[ai * 4 + m];
; #pragma unroll
;                 for (int bj = 0; bj < 2; ++bj) {
;                     const int colw = u.pn * BM + bj * HALF + wc * 32, col0 = colw + 8 * fq;
;                     const bool rope = (colw % 96) == 64 && colw < 576;
;                     f32x4 v0 = acc[ai][bj][m][0] * rs, v1 = acc[ai][bj][m][1] * rs;
;                     if (rope) {
;                         const float* tp = ropB + ((size_t)row * 16 + ((col0 - colw) >> 1)) * 2;
;                         const f32x4 c0 = *(const f32x4*)tp, c1 = *(const f32x4*)(tp + 4);
;                         f32x4 w0, w1;
;                         w0[0] = v0[0] * c0[0] - v0[1] * c0[1]; w0[1] = v0[1] * c0[0] + v0[0] * c0[1];
;                         w0[2] = v0[2] * c0[2] - v0[3] * c0[3]; w0[3] = v0[3] * c0[2] + v0[2] * c0[3];
;                         w1[0] = v1[0] * c1[0] - v1[1] * c1[1]; w1[1] = v1[1] * c1[0] + v1[0] * c1[1];
;                         w1[2] = v1[2] * c1[2] - v1[3] * c1[3]; w1[3] = v1[3] * c1[2] + v1[2] * c1[3];
;                         v0 = w0; v1 = w1;
;                     }
;                     u32x4 w; w.x = cvt_pk_bf16(v0[0], v0[1]); w.y = cvt_pk_bf16(v0[2], v0[3]); w.z = cvt_pk_bf16(v1[0], v1[1]); w.w = cvt_pk_bf16(v1[2], v1[3]);
;                     *(u32x4*)(O + (size_t)row * QMP + col0) = w;
.LBB0_729:
	v_ffbh_u32_e32 v0, v149
	v_min_u32_e32 v0, 32, v0
	v_lshlrev_b64 v[76:77], v0, v[148:149]
	v_min_u32_e32 v76, 1, v76
	v_or_b32_e32 v76, v77, v76
	v_cvt_f32_u32_e32 v76, v76
	v_sub_u32_e32 v0, 32, v0
	v_ldexp_f32 v0, v76, v0
	v_mul_f32_e32 v0, 0x33800000, v0
	v_fmamk_f32 v0, v0, 0x3b2aaaab, v226
	v_add_u32_e32 v80, 0x80, v140
	v_ashrrev_i32_e32 v81, 31, v80
	v_rsq_f32_e32 v76, v0
	s_nop 0
	v_mul_f32_e32 v76, s69, v76
	v_cvt_pk_bf16_f32 v84, v74, v75
	v_cvt_pk_bf16_f32 v85, v82, v83
	v_cvt_pk_bf16_f32 v86, v70, v71
	v_cvt_pk_bf16_f32 v87, v72, v73
	v_lshl_add_u64 v[70:71], v[118:119], 1, v[78:79]
	v_lshlrev_b64 v[72:73], 7, v[80:81]
	global_store_dwordx4 v[70:71], v[84:87], off offset:256
	v_pk_mul_f32 v[70:71], v[68:69], v[76:77] op_sel_hi:[1,0]
	v_pk_mul_f32 v[66:67], v[66:67], v[76:77] op_sel_hi:[1,0]
	v_pk_mul_f32 v[68:69], v[64:65], v[76:77] op_sel_hi:[1,0]
	v_pk_mul_f32 v[62:63], v[62:63], v[76:77] op_sel_hi:[1,0]
	s_and_b64 vcc, exec, s[8:9]
	v_lshl_add_u64 v[64:65], s[20:21], 0, v[72:73]
	s_cbranch_vccnz .LBB0_731
	v_mov_b32_e32 v127, v1
	v_lshl_add_u64 v[78:79], v[64:65], 0, v[126:127]
	global_load_dwordx4 v[72:75], v[78:79], off
	global_load_dwordx4 v[82:85], v[78:79], off offset:16
	s_waitcnt vmcnt(0) lgkmcnt(0)
	v_pk_mul_f32 v[86:87], v[66:67], v[72:73] op_sel:[1,1] op_sel_hi:[0,1]
	v_mul_f32_e32 v0, v71, v75
	v_pk_mul_f32 v[78:79], v[66:67], v[72:73]
	v_pk_fma_f32 v[66:67], v[66:67], v[72:73], v[86:87] op_sel_hi:[1,0,1]
	v_pk_fma_f32 v[72:73], v[70:71], v[74:75], v[0:1] op_sel_hi:[1,1,0] neg_lo:[0,0,1] neg_hi:[0,0,1]
	v_mul_f32_e32 v0, v70, v75
	v_pk_fma_f32 v[74:75], v[70:71], v[74:75], v[0:1] op_sel:[1,0,0] op_sel_hi:[0,1,0]
	v_pk_mul_f32 v[88:89], v[62:63], v[82:83] op_sel:[1,1] op_sel_hi:[0,1]
	v_mul_f32_e32 v0, v69, v85
	v_pk_mul_f32 v[70:71], v[62:63], v[82:83]
	v_pk_fma_f32 v[62:63], v[62:63], v[82:83], v[88:89] op_sel_hi:[1,0,1]
	v_pk_fma_f32 v[82:83], v[68:69], v[84:85], v[0:1] op_sel_hi:[1,1,0] neg_lo:[0,0,1] neg_hi:[0,0,1]
	v_mul_f32_e32 v0, v68, v85
	v_pk_fma_f32 v[84:85], v[68:69], v[84:85], v[0:1] op_sel:[1,0,0] op_sel_hi:[0,1,0]
	v_sub_f32_e32 v66, v78, v86
	v_sub_f32_e32 v62, v70, v88
	v_mov_b32_e32 v70, v72
	v_mov_b32_e32 v71, v74
	v_mov_b32_e32 v68, v82
	v_mov_b32_e32 v69, v84

; __device__ __forceinline__ unsigned cvt_pk_bf16(float lo, float hi) { unsigned r; asm volatile("v_cvt_pk_bf16_f32 %0, %1, %2" : "=v"(r) : "v"(lo), "v"(hi)); return r; }
; __device__ __forceinline__ float ssq_val(ssq_t v) { return (float)v * SSQ_IFX; }
;     __device__ __forceinline__ void operator()(const f32x4 (&acc)[2][2][4][2], const Unit& u, int wr, int wc, int fr, int fq) const {
;     ...
;         for (int i = 0; i < 8; ++i) rsv[i] = QS_B / sqrtf(ssq_val(sv[i]) * (1.0f / 384.0f) + EPS);
; #pragma unroll
;         for (int ai = 0; ai < 2; ++ai)
; #pragma unroll
;             for (int m = 0; m < 4; ++m) {
;                 const int row = row0 + ai * HALF + m * 16;
;                 const float rs = rsv[ai * 4 + m];
; #pragma unroll
;                 for (int bj = 0; bj < 2; ++bj) {
;                     const int colw = u.pn * BM + bj * HALF + wc * 32, col0 = colw + 8 * fq;
;                     const bool rope = (colw % 96) == 64 && colw < 576;
;                     f32x4 v0 = acc[ai][bj][m][0] * rs, v1 = acc[ai][bj][m][1] * rs;
;                     if (rope) {
;                         const float* tp = ropB + ((size_t)row * 16 + ((col0 - colw) >> 1)) * 2;
;                         const f32x4 c0 = *(const f32x4*)tp, c1 = *(const f32x4*)(tp + 4);
;                         f32x4 w0, w1;
;                         w0[0] = v0[0] * c0[0] - v0[1] * c0[1]; w0[1] = v0[1] * c0[0] + v0[0] * c0[1];
;                         w0[2] = v0[2] * c0[2] - v0[3] * c0[3]; w0[3] = v0[3] * c0[2] + v0[2] * c0[3];
;                         w1[0] = v1[0] * c1[0] - v1[1] * c1[1]; w1[1] = v1[1] * c1[0] + v1[0] * c1[1];
;                         w1[2] = v1[2] * c1[2] - v1[3] * c1[3]; w1[3] = v1[3] * c1[2] + v1[2] * c1[3];
;                         v0 = w0; v1 = w1;
;                     }
;                     u32x4 w; w.x = cvt_pk_bf16(v0[0], v0[1]); w.y = cvt_pk_bf16(v0[2], v0[3]); w.z = cvt_pk_bf16(v1[0], v1[1]); w.w = cvt_pk_bf16(v1[2], v1[3]);
;                     *(u32x4*)(O + (size_t)row * QMP + col0) = w;
.LBB0_733:
	v_ffbh_u32_e32 v0, v147
	v_min_u32_e32 v0, 32, v0
	v_lshlrev_b64 v[56:57], v0, v[146:147]
	v_min_u32_e32 v56, 1, v56
	v_or_b32_e32 v56, v57, v56
	v_cvt_f32_u32_e32 v56, v56
	v_sub_u32_e32 v0, 32, v0
	v_ldexp_f32 v0, v56, v0
	v_mul_f32_e32 v0, 0x33800000, v0
	v_fmamk_f32 v0, v0, 0x3b2aaaab, v226
	v_cvt_pk_bf16_f32 v64, v58, v59
	v_cvt_pk_bf16_f32 v65, v66, v67
	v_cvt_pk_bf16_f32 v66, v54, v55
	v_lshl_add_u64 v[54:55], v[118:119], 1, v[62:63]
	v_cvt_pk_bf16_f32 v67, v60, v61
	global_store_dwordx4 v[54:55], v[64:67], off offset:256
	v_add_u32_e32 v54, 0x90, v140
	v_ashrrev_i32_e32 v55, 31, v54
	v_rsq_f32_e32 v56, v0
	s_nop 0
	v_mul_f32_e32 v56, s69, v56
	v_lshlrev_b64 v[60:61], 7, v[54:55]
	v_pk_mul_f32 v[58:59], v[52:53], v[56:57] op_sel_hi:[1,0]
	v_pk_mul_f32 v[50:51], v[50:51], v[56:57] op_sel_hi:[1,0]
	v_pk_mul_f32 v[52:53], v[48:49], v[56:57] op_sel_hi:[1,0]
	v_pk_mul_f32 v[46:47], v[46:47], v[56:57] op_sel_hi:[1,0]
	s_and_b64 vcc, exec, s[8:9]
	v_lshl_add_u64 v[48:49], s[20:21], 0, v[60:61]
	s_cbranch_vccnz .LBB0_735
	v_mov_b32_e32 v127, v1
	v_lshl_add_u64 v[64:65], v[48:49], 0, v[126:127]
	global_load_dwordx4 v[60:63], v[64:65], off
	s_nop 0
	global_load_dwordx4 v[64:67], v[64:65], off offset:16
	s_waitcnt vmcnt(0) lgkmcnt(0)
	v_pk_mul_f32 v[70:71], v[50:51], v[60:61] op_sel:[1,1] op_sel_hi:[0,1]
	v_mul_f32_e32 v0, v59, v63
	v_pk_mul_f32 v[68:69], v[50:51], v[60:61]
	v_pk_fma_f32 v[50:51], v[50:51], v[60:61], v[70:71] op_sel_hi:[1,0,1]
	v_pk_fma_f32 v[60:61], v[58:59], v[62:63], v[0:1] op_sel_hi:[1,1,0] neg_lo:[0,0,1] neg_hi:[0,0,1]
	v_mul_f32_e32 v0, v58, v63
	v_pk_fma_f32 v[62:63], v[58:59], v[62:63], v[0:1] op_sel:[1,0,0] op_sel_hi:[0,1,0]
	v_pk_mul_f32 v[72:73], v[46:47], v[64:65] op_sel:[1,1] op_sel_hi:[0,1]
	v_mul_f32_e32 v0, v53, v67
	v_pk_mul_f32 v[58:59], v[46:47], v[64:65]
	v_pk_fma_f32 v[46:47], v[46:47], v[64:65], v[72:73] op_sel_hi:[1,0,1]
	v_pk_fma_f32 v[64:65], v[52:53], v[66:67], v[0:1] op_sel_hi:[1,1,0] neg_lo:[0,0,1] neg_hi:[0,0,1]
	v_mul_f32_e32 v0, v52, v67
	v_pk_fma_f32 v[66:67], v[52:53], v[66:67], v[0:1] op_sel:[1,0,0] op_sel_hi:[0,1,0]
	v_sub_f32_e32 v50, v68, v70
	v_sub_f32_e32 v46, v58, v72
	v_mov_b32_e32 v58, v60
	v_mov_b32_e32 v59, v62
	v_mov_b32_e32 v52, v64
	v_mov_b32_e32 v53, v66

; __device__ __forceinline__ unsigned cvt_pk_bf16(float lo, float hi) { unsigned r; asm volatile("v_cvt_pk_bf16_f32 %0, %1, %2" : "=v"(r) : "v"(lo), "v"(hi)); return r; }
; __device__ __forceinline__ float ssq_val(ssq_t v) { return (float)v * SSQ_IFX; }
;     __device__ __forceinline__ void operator()(const f32x4 (&acc)[2][2][4][2], const Unit& u, int wr, int wc, int fr, int fq) const {
;     ...
;         for (int i = 0; i < 8; ++i) rsv[i] = QS_B / sqrtf(ssq_val(sv[i]) * (1.0f / 384.0f) + EPS);
; #pragma unroll
;         for (int ai = 0; ai < 2; ++ai)
; #pragma unroll
;             for (int m = 0; m < 4; ++m) {
;                 const int row = row0 + ai * HALF + m * 16;
;                 const float rs = rsv[ai * 4 + m];
; #pragma unroll
;                 for (int bj = 0; bj < 2; ++bj) {
;                     const int colw = u.pn * BM + bj * HALF + wc * 32, col0 = colw + 8 * fq;
;                     const bool rope = (colw % 96) == 64 && colw < 576;
;                     f32x4 v0 = acc[ai][bj][m][0] * rs, v1 = acc[ai][bj][m][1] * rs;
;                     if (rope) {
;                         const float* tp = ropB + ((size_t)row * 16 + ((col0 - colw) >> 1)) * 2;
;                         const f32x4 c0 = *(const f32x4*)tp, c1 = *(const f32x4*)(tp + 4);
;                         f32x4 w0, w1;
;                         w0[0] = v0[0] * c0[0] - v0[1] * c0[1]; w0[1] = v0[1] * c0[0] + v0[0] * c0[1];
;                         w0[2] = v0[2] * c0[2] - v0[3] * c0[3]; w0[3] = v0[3] * c0[2] + v0[2] * c0[3];
;                         w1[0] = v1[0] * c1[0] - v1[1] * c1[1]; w1[1] = v1[1] * c1[0] + v1[0] * c1[1];
;                         w1[2] = v1[2] * c1[2] - v1[3] * c1[3]; w1[3] = v1[3] * c1[2] + v1[2] * c1[3];
;                         v0 = w0; v1 = w1;
;                     }
;                     u32x4 w; w.x = cvt_pk_bf16(v0[0], v0[1]); w.y = cvt_pk_bf16(v0[2], v0[3]); w.z = cvt_pk_bf16(v1[0], v1[1]); w.w = cvt_pk_bf16(v1[2], v1[3]);
;                     *(u32x4*)(O + (size_t)row * QMP + col0) = w;
.LBB0_737:
	v_ffbh_u32_e32 v0, v145
	v_min_u32_e32 v0, 32, v0
	v_lshlrev_b64 v[40:41], v0, v[144:145]
	v_min_u32_e32 v40, 1, v40
	v_or_b32_e32 v40, v41, v40
	v_cvt_f32_u32_e32 v40, v40
	v_sub_u32_e32 v0, 32, v0
	v_ldexp_f32 v0, v40, v0
	v_mul_f32_e32 v0, 0x33800000, v0
	v_fmamk_f32 v0, v0, 0x3b2aaaab, v226
	v_cvt_pk_bf16_f32 v48, v42, v43
	v_cvt_pk_bf16_f32 v49, v50, v51
	v_cvt_pk_bf16_f32 v50, v38, v39
	v_lshl_add_u64 v[38:39], v[118:119], 1, v[46:47]
	v_cvt_pk_bf16_f32 v51, v44, v45
	global_store_dwordx4 v[38:39], v[48:51], off offset:256
	v_add_u32_e32 v38, 0xa0, v140
	v_ashrrev_i32_e32 v39, 31, v38
	v_rsq_f32_e32 v40, v0
	s_nop 0
	v_mul_f32_e32 v40, s69, v40
	v_lshlrev_b64 v[44:45], 7, v[38:39]
	v_pk_mul_f32 v[42:43], v[36:37], v[40:41] op_sel_hi:[1,0]
	v_pk_mul_f32 v[34:35], v[34:35], v[40:41] op_sel_hi:[1,0]
	v_pk_mul_f32 v[36:37], v[32:33], v[40:41] op_sel_hi:[1,0]
	v_pk_mul_f32 v[30:31], v[30:31], v[40:41] op_sel_hi:[1,0]
	s_and_b64 vcc, exec, s[8:9]
	v_lshl_add_u64 v[32:33], s[20:21], 0, v[44:45]
	s_cbranch_vccnz .LBB0_739
	v_mov_b32_e32 v127, v1
	v_lshl_add_u64 v[48:49], v[32:33], 0, v[126:127]
	global_load_dwordx4 v[44:47], v[48:49], off
	s_nop 0
	global_load_dwordx4 v[48:51], v[48:49], off offset:16
	s_waitcnt vmcnt(0) lgkmcnt(0)
	v_pk_mul_f32 v[54:55], v[34:35], v[44:45] op_sel:[1,1] op_sel_hi:[0,1]
	v_mul_f32_e32 v0, v43, v47
	v_pk_mul_f32 v[52:53], v[34:35], v[44:45]
	v_pk_fma_f32 v[34:35], v[34:35], v[44:45], v[54:55] op_sel_hi:[1,0,1]
	v_pk_fma_f32 v[44:45], v[42:43], v[46:47], v[0:1] op_sel_hi:[1,1,0] neg_lo:[0,0,1] neg_hi:[0,0,1]
	v_mul_f32_e32 v0, v42, v47
	v_pk_fma_f32 v[46:47], v[42:43], v[46:47], v[0:1] op_sel:[1,0,0] op_sel_hi:[0,1,0]
	v_pk_mul_f32 v[56:57], v[30:31], v[48:49] op_sel:[1,1] op_sel_hi:[0,1]
	v_mul_f32_e32 v0, v37, v51
	v_pk_mul_f32 v[42:43], v[30:31], v[48:49]
	v_pk_fma_f32 v[30:31], v[30:31], v[48:49], v[56:57] op_sel_hi:[1,0,1]
	v_pk_fma_f32 v[48:49], v[36:37], v[50:51], v[0:1] op_sel_hi:[1,1,0] neg_lo:[0,0,1] neg_hi:[0,0,1]
	v_mul_f32_e32 v0, v36, v51
	v_pk_fma_f32 v[50:51], v[36:37], v[50:51], v[0:1] op_sel:[1,0,0] op_sel_hi:[0,1,0]
	v_sub_f32_e32 v34, v52, v54
	v_sub_f32_e32 v30, v42, v56
	v_mov_b32_e32 v42, v44
	v_mov_b32_e32 v43, v46
	v_mov_b32_e32 v36, v48
	v_mov_b32_e32 v37, v50

; __device__ __forceinline__ unsigned cvt_pk_bf16(float lo, float hi) { unsigned r; asm volatile("v_cvt_pk_bf16_f32 %0, %1, %2" : "=v"(r) : "v"(lo), "v"(hi)); return r; }
; __device__ __forceinline__ float ssq_val(ssq_t v) { return (float)v * SSQ_IFX; }
;     __device__ __forceinline__ void operator()(const f32x4 (&acc)[2][2][4][2], const Unit& u, int wr, int wc, int fr, int fq) const {
;     ...
;         for (int i = 0; i < 8; ++i) rsv[i] = QS_B / sqrtf(ssq_val(sv[i]) * (1.0f / 384.0f) + EPS);
; #pragma unroll
;         for (int ai = 0; ai < 2; ++ai)
; #pragma unroll
;             for (int m = 0; m < 4; ++m) {
;                 const int row = row0 + ai * HALF + m * 16;
;                 const float rs = rsv[ai * 4 + m];
; #pragma unroll
;                 for (int bj = 0; bj < 2; ++bj) {
;                     const int colw = u.pn * BM + bj * HALF + wc * 32, col0 = colw + 8 * fq;
;                     const bool rope = (colw % 96) == 64 && colw < 576;
;                     f32x4 v0 = acc[ai][bj][m][0] * rs, v1 = acc[ai][bj][m][1] * rs;
;                     if (rope) {
;                         const float* tp = ropB + ((size_t)row * 16 + ((col0 - colw) >> 1)) * 2;
;                         const f32x4 c0 = *(const f32x4*)tp, c1 = *(const f32x4*)(tp + 4);
;                         f32x4 w0, w1;
;                         w0[0] = v0[0] * c0[0] - v0[1] * c0[1]; w0[1] = v0[1] * c0[0] + v0[0] * c0[1];
;                         w0[2] = v0[2] * c0[2] - v0[3] * c0[3]; w0[3] = v0[3] * c0[2] + v0[2] * c0[3];
;                         w1[0] = v1[0] * c1[0] - v1[1] * c1[1]; w1[1] = v1[1] * c1[0] + v1[0] * c1[1];
;                         w1[2] = v1[2] * c1[2] - v1[3] * c1[3]; w1[3] = v1[3] * c1[2] + v1[2] * c1[3];
;                         v0 = w0; v1 = w1;
;                     }
;                     u32x4 w; w.x = cvt_pk_bf16(v0[0], v0[1]); w.y = cvt_pk_bf16(v0[2], v0[3]); w.z = cvt_pk_bf16(v1[0], v1[1]); w.w = cvt_pk_bf16(v1[2], v1[3]);
;                     *(u32x4*)(O + (size_t)row * QMP + col0) = w;
.LBB0_741:
	v_ffbh_u32_e32 v0, v143
	v_min_u32_e32 v0, 32, v0
	v_lshlrev_b64 v[24:25], v0, v[142:143]
	v_min_u32_e32 v24, 1, v24
	v_or_b32_e32 v24, v25, v24
	v_cvt_f32_u32_e32 v24, v24
	v_sub_u32_e32 v0, 32, v0
	v_ldexp_f32 v0, v24, v0
	v_mul_f32_e32 v0, 0x33800000, v0
	v_fmamk_f32 v0, v0, 0x3b2aaaab, v226
	v_cvt_pk_bf16_f32 v32, v26, v27
	v_cvt_pk_bf16_f32 v33, v34, v35
	v_cvt_pk_bf16_f32 v34, v22, v23
	v_lshl_add_u64 v[22:23], v[118:119], 1, v[30:31]
	v_cvt_pk_bf16_f32 v35, v28, v29
	global_store_dwordx4 v[22:23], v[32:35], off offset:256
	v_add_u32_e32 v22, 0xb0, v140
	v_ashrrev_i32_e32 v23, 31, v22
	v_rsq_f32_e32 v24, v0
	s_nop 0
	v_mul_f32_e32 v24, s69, v24
	v_lshlrev_b64 v[28:29], 7, v[22:23]
	v_pk_mul_f32 v[26:27], v[20:21], v[24:25] op_sel_hi:[1,0]
	v_pk_mul_f32 v[18:19], v[18:19], v[24:25] op_sel_hi:[1,0]
	v_pk_mul_f32 v[20:21], v[12:13], v[24:25] op_sel_hi:[1,0]
	v_pk_mul_f32 v[12:13], v[10:11], v[24:25] op_sel_hi:[1,0]
	s_and_b64 vcc, exec, s[8:9]
	v_lshl_add_u64 v[10:11], s[20:21], 0, v[28:29]
	s_cbranch_vccnz .LBB0_743
	v_mov_b32_e32 v127, v1
	v_lshl_add_u64 v[32:33], v[10:11], 0, v[126:127]
	global_load_dwordx4 v[28:31], v[32:33], off
	s_nop 0
	global_load_dwordx4 v[32:35], v[32:33], off offset:16
	s_waitcnt vmcnt(0) lgkmcnt(0)
	v_pk_mul_f32 v[38:39], v[18:19], v[28:29] op_sel:[1,1] op_sel_hi:[0,1]
	v_mul_f32_e32 v0, v27, v31
	v_pk_mul_f32 v[36:37], v[18:19], v[28:29]
	v_pk_fma_f32 v[18:19], v[18:19], v[28:29], v[38:39] op_sel_hi:[1,0,1]
	v_pk_fma_f32 v[28:29], v[26:27], v[30:31], v[0:1] op_sel_hi:[1,1,0] neg_lo:[0,0,1] neg_hi:[0,0,1]
	v_mul_f32_e32 v0, v26, v31
	v_pk_fma_f32 v[30:31], v[26:27], v[30:31], v[0:1] op_sel:[1,0,0] op_sel_hi:[0,1,0]
	v_pk_mul_f32 v[40:41], v[12:13], v[32:33] op_sel:[1,1] op_sel_hi:[0,1]
	v_mul_f32_e32 v0, v21, v35
	v_pk_mul_f32 v[26:27], v[12:13], v[32:33]
	v_pk_fma_f32 v[12:13], v[12:13], v[32:33], v[40:41] op_sel_hi:[1,0,1]
	v_pk_fma_f32 v[32:33], v[20:21], v[34:35], v[0:1] op_sel_hi:[1,1,0] neg_lo:[0,0,1] neg_hi:[0,0,1]
	v_mul_f32_e32 v0, v20, v35
	v_pk_fma_f32 v[34:35], v[20:21], v[34:35], v[0:1] op_sel:[1,0,0] op_sel_hi:[0,1,0]
	v_sub_f32_e32 v18, v36, v38
	v_sub_f32_e32 v12, v26, v40
	v_mov_b32_e32 v26, v28
	v_mov_b32_e32 v27, v30
	v_mov_b32_e32 v20, v32
	v_mov_b32_e32 v21, v34

; __device__ __forceinline__ unsigned cvt_pk_bf16(float lo, float hi) { unsigned r; asm volatile("v_cvt_pk_bf16_f32 %0, %1, %2" : "=v"(r) : "v"(lo), "v"(hi)); return r; }
; __device__ __forceinline__ float ssq_val(ssq_t v) { return (float)v * SSQ_IFX; }
;     __device__ __forceinline__ void operator()(const f32x4 (&acc)[2][2][4][2], const Unit& u, int wr, int wc, int fr, int fq) const {
;     ...
;         for (int i = 0; i < 8; ++i) sv[i] = ssq[row0 + (i >> 2) * HALF + (i & 3) * 16];
; #pragma unroll
;         for (int i = 0; i < 8; ++i) rsv[i] = 1.0f / sqrtf(ssq_val(sv[i]) * (1.0f / 256.0f) + EPS);
; #pragma unroll
;         for (int ai = 0; ai < 2; ++ai)
; #pragma unroll
;             for (int m = 0; m < 4; ++m) {
;                 const int row = row0 + ai * HALF + m * 16;
;                 const float rs = rsv[ai * 4 + m];
; #pragma unroll
;                 for (int bj = 0; bj < 2; ++bj) {
;                     const int col0 = u.pn * BM + bj * HALF + wc * 32 + 8 * fq;
;                     const f32x4 v0 = acc[ai][bj][m][0] * rs, v1 = acc[ai][bj][m][1] * rs;
;                     u32x4 w; w.x = cvt_pk_bf16(v0[0], v0[1]); w.y = cvt_pk_bf16(v0[2], v0[3]); w.z = cvt_pk_bf16(v1[0], v1[1]); w.w = cvt_pk_bf16(v1[2], v1[3]);
;                     *(u32x4*)(O + (size_t)row * KVP + col0) = w;
.LBB0_761:
	s_lshl_b32 s3, s3, 8
	s_add_i32 s3, s3, s4
	v_mbcnt_lo_u32_b32 v145, -1, 0
	v_mbcnt_hi_u32_b32 v145, -1, v145
	v_mov_b32_e32 v226, 0x358637bd
	v_and_or_b32 v138, v145, 15, s3
	v_ashrrev_i32_e32 v139, 31, v138
	v_lshl_add_u64 v[142:143], v[138:139], 3, s[14:15]
	global_load_dwordx2 v[156:157], v[142:143], off
	global_load_dwordx2 v[158:159], v[142:143], off offset:128
	global_load_dwordx2 v[154:155], v[142:143], off offset:256
	global_load_dwordx2 v[152:153], v[142:143], off offset:384
	v_mov_b32_e32 v223, 0x260
	global_load_dwordx2 v[150:151], v[142:143], off offset:1024
	global_load_dwordx2 v[148:149], v[142:143], off offset:1152
	global_load_dwordx2 v[146:147], v[142:143], off offset:1280
	s_nop 0
	global_load_dwordx2 v[142:143], v[142:143], off offset:1408
	s_lshl_b32 s2, s2, 8
	v_add_u32_e32 v139, 0x80, v138
	v_mov_b32_e32 v222, v224
	v_mov_b64_e32 v[252:253], 0x300
	s_waitcnt vmcnt(0) lgkmcnt(0)
	v_ffbh_u32_e32 v140, v157
	v_min_u32_e32 v140, 32, v140
	v_lshlrev_b64 v[156:157], v140, v[156:157]
	v_min_u32_e32 v144, 1, v156
	v_or_b32_e32 v144, v157, v144
	v_cvt_f32_u32_e32 v144, v144
	v_sub_u32_e32 v140, 32, v140
	v_ldexp_f32 v140, v144, v140
	v_mul_f32_e32 v140, 0x33800000, v140
	v_fmamk_f32 v140, v140, 0x3b800000, v226
	v_rsq_f32_e32 v140, v140
	s_nop 0
	v_ffbh_u32_e32 v144, v159
	v_min_u32_e32 v144, 32, v144
	v_lshlrev_b64 v[156:157], v144, v[158:159]
	v_min_u32_e32 v156, 1, v156
	v_or_b32_e32 v156, v157, v156
	v_cvt_f32_u32_e32 v156, v156
	v_sub_u32_e32 v144, 32, v144
	v_pk_mul_f32 v[132:133], v[132:133], v[140:141] op_sel_hi:[1,0]
	v_pk_mul_f32 v[130:131], v[130:131], v[140:141] op_sel_hi:[1,0]
	v_ldexp_f32 v144, v156, v144
	v_mul_f32_e32 v144, 0x33800000, v144
	v_fmamk_f32 v144, v144, 0x3b800000, v226
	v_pk_mul_f32 v[126:127], v[126:127], v[140:141] op_sel_hi:[1,0]
	v_pk_mul_f32 v[128:129], v[128:129], v[140:141] op_sel_hi:[1,0]
	v_cvt_pk_bf16_f32 v130, v130, v131
	v_cvt_pk_bf16_f32 v131, v132, v133
	v_cvt_pk_bf16_f32 v132, v126, v127
	v_mov_b64_e32 v[126:127], s[12:13]
	v_cvt_pk_bf16_f32 v133, v128, v129
	v_pk_mul_f32 v[124:125], v[124:125], v[140:141] op_sel_hi:[1,0]
	v_pk_mul_f32 v[122:123], v[122:123], v[140:141] op_sel_hi:[1,0]
	v_rsq_f32_e32 v144, v144
	s_nop 0
	v_ffbh_u32_e32 v156, v155
	v_min_u32_e32 v156, 32, v156
	v_lshlrev_b64 v[154:155], v156, v[154:155]
	v_min_u32_e32 v154, 1, v154
	v_or_b32_e32 v154, v155, v154
	v_cvt_f32_u32_e32 v154, v154
	v_sub_u32_e32 v155, 32, v156
	v_pk_mul_f32 v[114:115], v[114:115], v[144:145] op_sel_hi:[1,0]
	v_pk_mul_f32 v[116:117], v[116:117], v[144:145] op_sel_hi:[1,0]
	v_ldexp_f32 v154, v154, v155
	v_mul_f32_e32 v154, 0x33800000, v154
	v_fmamk_f32 v154, v154, 0x3b800000, v226
	v_pk_mul_f32 v[108:109], v[108:109], v[144:145] op_sel_hi:[1,0]
	v_pk_mul_f32 v[106:107], v[106:107], v[144:145] op_sel_hi:[1,0]
	v_rsq_f32_e32 v154, v154
	s_nop 0
	v_ffbh_u32_e32 v155, v153
	v_min_u32_e32 v155, 32, v155
	v_lshlrev_b64 v[152:153], v155, v[152:153]
	v_min_u32_e32 v152, 1, v152
	v_or_b32_e32 v152, v153, v152
	v_cvt_f32_u32_e32 v152, v152
	v_sub_u32_e32 v153, 32, v155
	v_ldexp_f32 v152, v152, v153
	v_mul_f32_e32 v152, 0x33800000, v152
	v_fmamk_f32 v152, v152, 0x3b800000, v226
	v_rsq_f32_e32 v152, v152
	s_nop 0
	v_ffbh_u32_e32 v153, v151
	v_min_u32_e32 v153, 32, v153
	v_lshlrev_b64 v[150:151], v153, v[150:151]
	v_min_u32_e32 v150, 1, v150
	v_or_b32_e32 v150, v151, v150
	v_cvt_f32_u32_e32 v150, v150
	v_sub_u32_e32 v151, 32, v153
	v_ldexp_f32 v150, v150, v151
	v_mul_f32_e32 v150, 0x33800000, v150
	v_fmamk_f32 v150, v150, 0x3b800000, v226
	v_rsq_f32_e32 v150, v150
	s_nop 0
	v_ffbh_u32_e32 v151, v149
	v_min_u32_e32 v151, 32, v151
	v_lshlrev_b64 v[148:149], v151, v[148:149]
	v_min_u32_e32 v148, 1, v148
	v_or_b32_e32 v148, v149, v148
	v_cvt_f32_u32_e32 v148, v148
	v_sub_u32_e32 v149, 32, v151
	v_ldexp_f32 v148, v148, v149
	v_mul_f32_e32 v148, 0x33800000, v148
	v_fmamk_f32 v148, v148, 0x3b800000, v226
	v_rsq_f32_e32 v148, v148
	s_nop 0
	v_ffbh_u32_e32 v149, v147
	v_min_u32_e32 v149, 32, v149
	v_lshlrev_b64 v[146:147], v149, v[146:147]
	v_min_u32_e32 v146, 1, v146
	v_or_b32_e32 v146, v147, v146
	v_cvt_f32_u32_e32 v146, v146
	v_sub_u32_e32 v147, 32, v149
	v_ldexp_f32 v146, v146, v147
	v_mul_f32_e32 v146, 0x33800000, v146
	v_fmamk_f32 v146, v146, 0x3b800000, v226
	v_rsq_f32_e32 v146, v146
	s_nop 0
	v_ffbh_u32_e32 v147, v143
	v_min_u32_e32 v147, 32, v147
	v_lshlrev_b64 v[142:143], v147, v[142:143]
	v_min_u32_e32 v142, 1, v142
	v_or_b32_e32 v142, v143, v142
	v_cvt_f32_u32_e32 v142, v142
	v_sub_u32_e32 v143, 32, v147
	v_pk_mul_f32 v[98:99], v[98:99], v[154:155] op_sel_hi:[1,0]
	v_pk_mul_f32 v[100:101], v[100:101], v[154:155] op_sel_hi:[1,0]
	v_ldexp_f32 v142, v142, v143
	v_mul_f32_e32 v142, 0x33800000, v142
	v_fmamk_f32 v142, v142, 0x3b800000, v226
	v_pk_mul_f32 v[92:93], v[92:93], v[154:155] op_sel_hi:[1,0]
	v_pk_mul_f32 v[90:91], v[90:91], v[154:155] op_sel_hi:[1,0]
	v_rsq_f32_e32 v142, v142
	s_nop 0
	v_lshrrev_b32_e32 v143, 1, v145
	v_and_or_b32 v143, v143, 24, s2
	v_or_b32_e32 v156, s5, v143
	v_ashrrev_i32_e32 v157, 31, v156
	v_mad_i64_i32 v[158:159], s[2:3], v138, s75, v[126:127]
	v_lshlrev_b64 v[128:129], 1, v[156:157]
	v_lshl_add_u64 v[156:157], v[158:159], 0, v[128:129]
	global_store_dwordx4 v[156:157], v[130:133], off
	v_pk_mul_f32 v[74:75], v[74:75], v[152:153] op_sel_hi:[1,0]
	v_pk_mul_f32 v[76:77], v[76:77], v[152:153] op_sel_hi:[1,0]
	v_pk_mul_f32 v[130:131], v[120:121], v[140:141] op_sel_hi:[1,0]
	v_pk_mul_f32 v[120:121], v[118:119], v[140:141] op_sel_hi:[1,0]
	v_cvt_pk_bf16_f32 v118, v122, v123
	v_cvt_pk_bf16_f32 v119, v124, v125
	v_pk_mul_f32 v[60:61], v[60:61], v[152:153] op_sel_hi:[1,0]
; __device__ __forceinline__ unsigned cvt_pk_bf16(float lo, float hi) { unsigned r; asm volatile("v_cvt_pk_bf16_f32 %0, %1, %2" : "=v"(r) : "v"(lo), "v"(hi)); return r; }
;     __device__ __forceinline__ void operator()(const f32x4 (&acc)[2][2][4][2], const Unit& u, int wr, int wc, int fr, int fq) const {
;     ...
;         for (int ai = 0; ai < 2; ++ai)
; #pragma unroll
;             for (int m = 0; m < 4; ++m) {
;                 const int row = row0 + ai * HALF + m * 16;
;                 const float rs = rsv[ai * 4 + m];
; #pragma unroll
;                 for (int bj = 0; bj < 2; ++bj) {
;                     const int col0 = u.pn * BM + bj * HALF + wc * 32 + 8 * fq;
;                     const f32x4 v0 = acc[ai][bj][m][0] * rs, v1 = acc[ai][bj][m][1] * rs;
;                     u32x4 w; w.x = cvt_pk_bf16(v0[0], v0[1]); w.y = cvt_pk_bf16(v0[2], v0[3]); w.z = cvt_pk_bf16(v1[0], v1[1]); w.w = cvt_pk_bf16(v1[2], v1[3]);
;                     *(u32x4*)(O + (size_t)row * KVP + col0) = w;
	v_cvt_pk_bf16_f32 v120, v120, v121
	v_cvt_pk_bf16_f32 v121, v130, v131
	global_store_dwordx4 v[156:157], v[118:121], off offset:256
	v_pk_mul_f32 v[58:59], v[58:59], v[152:153] op_sel_hi:[1,0]
	v_pk_mul_f32 v[62:63], v[62:63], v[150:151] op_sel_hi:[1,0]
	v_or_b32_e32 v120, 16, v138
	v_pk_mul_f32 v[118:119], v[112:113], v[144:145] op_sel_hi:[1,0]
	v_pk_mul_f32 v[112:113], v[110:111], v[144:145] op_sel_hi:[1,0]
	v_cvt_pk_bf16_f32 v110, v114, v115
	v_mad_i64_i32 v[114:115], s[2:3], v120, s75, v[126:127]
	v_cvt_pk_bf16_f32 v111, v116, v117
	v_lshl_add_u64 v[114:115], v[114:115], 0, v[128:129]
	v_cvt_pk_bf16_f32 v112, v112, v113
	v_cvt_pk_bf16_f32 v113, v118, v119
	global_store_dwordx4 v[114:115], v[110:113], off
	v_pk_mul_f32 v[50:51], v[50:51], v[148:149] op_sel_hi:[1,0]
	v_pk_mul_f32 v[52:53], v[52:53], v[148:149] op_sel_hi:[1,0]
	v_pk_mul_f32 v[110:111], v[104:105], v[144:145] op_sel_hi:[1,0]
	v_pk_mul_f32 v[104:105], v[102:103], v[144:145] op_sel_hi:[1,0]
	v_cvt_pk_bf16_f32 v102, v106, v107
	v_cvt_pk_bf16_f32 v103, v108, v109
	v_pk_mul_f32 v[44:45], v[44:45], v[148:149] op_sel_hi:[1,0]
	v_cvt_pk_bf16_f32 v104, v104, v105
	v_cvt_pk_bf16_f32 v105, v110, v111
	global_store_dwordx4 v[114:115], v[102:105], off offset:256
	v_pk_mul_f32 v[42:43], v[42:43], v[148:149] op_sel_hi:[1,0]
	v_pk_mul_f32 v[34:35], v[34:35], v[146:147] op_sel_hi:[1,0]
	v_or_b32_e32 v104, 32, v138
	v_pk_mul_f32 v[102:103], v[96:97], v[154:155] op_sel_hi:[1,0]
	v_pk_mul_f32 v[96:97], v[94:95], v[154:155] op_sel_hi:[1,0]
	v_cvt_pk_bf16_f32 v94, v98, v99
	v_mad_i64_i32 v[98:99], s[2:3], v104, s75, v[126:127]
	v_cvt_pk_bf16_f32 v95, v100, v101
	v_lshl_add_u64 v[98:99], v[98:99], 0, v[128:129]
	v_cvt_pk_bf16_f32 v96, v96, v97
	v_cvt_pk_bf16_f32 v97, v102, v103
	global_store_dwordx4 v[98:99], v[94:97], off
	v_pk_mul_f32 v[36:37], v[36:37], v[146:147] op_sel_hi:[1,0]
	v_pk_mul_f32 v[28:29], v[28:29], v[146:147] op_sel_hi:[1,0]
	v_pk_mul_f32 v[94:95], v[88:89], v[154:155] op_sel_hi:[1,0]
	v_pk_mul_f32 v[88:89], v[86:87], v[154:155] op_sel_hi:[1,0]
	v_cvt_pk_bf16_f32 v86, v90, v91
	v_cvt_pk_bf16_f32 v87, v92, v93
	v_pk_mul_f32 v[26:27], v[26:27], v[146:147] op_sel_hi:[1,0]
	v_cvt_pk_bf16_f32 v88, v88, v89
	v_cvt_pk_bf16_f32 v89, v94, v95
	global_store_dwordx4 v[98:99], v[86:89], off offset:256
	v_pk_mul_f32 v[18:19], v[18:19], v[142:143] op_sel_hi:[1,0]
	v_pk_mul_f32 v[20:21], v[20:21], v[142:143] op_sel_hi:[1,0]
	v_or_b32_e32 v88, 48, v138
	v_pk_mul_f32 v[86:87], v[68:69], v[152:153] op_sel_hi:[1,0]
	v_pk_mul_f32 v[68:69], v[66:67], v[152:153] op_sel_hi:[1,0]
	v_cvt_pk_bf16_f32 v66, v74, v75
	v_mad_i64_i32 v[74:75], s[2:3], v88, s75, v[126:127]
	v_cvt_pk_bf16_f32 v67, v76, v77
	v_lshl_add_u64 v[74:75], v[74:75], 0, v[128:129]
	v_cvt_pk_bf16_f32 v68, v68, v69
	v_cvt_pk_bf16_f32 v69, v86, v87
	global_store_dwordx4 v[74:75], v[66:69], off
	s_and_b64 vcc, exec, s[6:7]
	v_pk_mul_f32 v[8:9], v[8:9], v[142:143] op_sel_hi:[1,0]
	v_pk_mul_f32 v[66:67], v[56:57], v[152:153] op_sel_hi:[1,0]
	v_pk_mul_f32 v[56:57], v[54:55], v[152:153] op_sel_hi:[1,0]
	v_cvt_pk_bf16_f32 v54, v58, v59
	v_cvt_pk_bf16_f32 v55, v60, v61
	v_pk_mul_f32 v[58:59], v[80:81], v[150:151] op_sel_hi:[1,0]
	v_cvt_pk_bf16_f32 v56, v56, v57
	v_cvt_pk_bf16_f32 v57, v66, v67
	global_store_dwordx4 v[74:75], v[54:57], off offset:256
	v_pk_mul_f32 v[60:61], v[78:79], v[150:151] op_sel_hi:[1,0]
	v_pk_mul_f32 v[6:7], v[6:7], v[142:143] op_sel_hi:[1,0]
	v_pk_mul_f32 v[56:57], v[84:85], v[150:151] op_sel_hi:[1,0]
	v_pk_mul_f32 v[54:55], v[82:83], v[150:151] op_sel_hi:[1,0]
	s_nop 0
	v_cvt_pk_bf16_f32 v54, v54, v55
	v_cvt_pk_bf16_f32 v55, v56, v57
	v_cvt_pk_bf16_f32 v56, v60, v61
	v_cvt_pk_bf16_f32 v57, v58, v59
	v_mad_i64_i32 v[58:59], s[2:3], v139, s75, v[126:127]
	v_lshl_add_u64 v[58:59], v[58:59], 0, v[128:129]
	global_store_dwordx4 v[58:59], v[54:57], off
	v_pk_mul_f32 v[60:61], v[64:65], v[150:151] op_sel_hi:[1,0]
	s_nop 0
	v_pk_mul_f32 v[56:57], v[72:73], v[150:151] op_sel_hi:[1,0]
	v_pk_mul_f32 v[54:55], v[70:71], v[150:151] op_sel_hi:[1,0]
	s_nop 0
	v_cvt_pk_bf16_f32 v54, v54, v55
	v_cvt_pk_bf16_f32 v55, v56, v57
	v_cvt_pk_bf16_f32 v56, v62, v63
	v_cvt_pk_bf16_f32 v57, v60, v61
	global_store_dwordx4 v[58:59], v[54:57], off offset:256
	s_nop 1
	v_add_u32_e32 v56, 0x90, v138
	v_pk_mul_f32 v[54:55], v[48:49], v[148:149] op_sel_hi:[1,0]
	v_pk_mul_f32 v[48:49], v[46:47], v[148:149] op_sel_hi:[1,0]
	v_cvt_pk_bf16_f32 v46, v50, v51
	v_mad_i64_i32 v[50:51], s[2:3], v56, s75, v[126:127]
	v_cvt_pk_bf16_f32 v47, v52, v53
	v_lshl_add_u64 v[50:51], v[50:51], 0, v[128:129]
	v_cvt_pk_bf16_f32 v48, v48, v49
	v_cvt_pk_bf16_f32 v49, v54, v55
	global_store_dwordx4 v[50:51], v[46:49], off
	s_nop 1
	v_pk_mul_f32 v[46:47], v[40:41], v[148:149] op_sel_hi:[1,0]
	v_pk_mul_f32 v[40:41], v[38:39], v[148:149] op_sel_hi:[1,0]
	v_cvt_pk_bf16_f32 v38, v42, v43
	v_cvt_pk_bf16_f32 v39, v44, v45
	s_nop 0
	v_cvt_pk_bf16_f32 v40, v40, v41
	v_cvt_pk_bf16_f32 v41, v46, v47
	global_store_dwordx4 v[50:51], v[38:41], off offset:256
	s_nop 1
	v_add_u32_e32 v40, 0xa0, v138
	v_pk_mul_f32 v[38:39], v[32:33], v[146:147] op_sel_hi:[1,0]
	v_pk_mul_f32 v[32:33], v[30:31], v[146:147] op_sel_hi:[1,0]
	v_cvt_pk_bf16_f32 v30, v34, v35
	v_mad_i64_i32 v[34:35], s[2:3], v40, s75, v[126:127]
	v_cvt_pk_bf16_f32 v31, v36, v37
	v_lshl_add_u64 v[34:35], v[34:35], 0, v[128:129]
	v_cvt_pk_bf16_f32 v32, v32, v33
	v_cvt_pk_bf16_f32 v33, v38, v39
	global_store_dwordx4 v[34:35], v[30:33], off
	s_nop 1
	v_pk_mul_f32 v[30:31], v[24:25], v[146:147] op_sel_hi:[1,0]
	v_pk_mul_f32 v[24:25], v[22:23], v[146:147] op_sel_hi:[1,0]
	v_cvt_pk_bf16_f32 v22, v26, v27
	v_cvt_pk_bf16_f32 v23, v28, v29
	s_nop 0
	v_cvt_pk_bf16_f32 v24, v24, v25
	v_cvt_pk_bf16_f32 v25, v30, v31
	global_store_dwordx4 v[34:35], v[22:25], off offset:256
	s_nop 1
	v_add_u32_e32 v24, 0xb0, v138
	v_pk_mul_f32 v[22:23], v[12:13], v[142:143] op_sel_hi:[1,0]
	v_pk_mul_f32 v[12:13], v[10:11], v[142:143] op_sel_hi:[1,0]
	v_cvt_pk_bf16_f32 v10, v18, v19
	v_mad_i64_i32 v[18:19], s[2:3], v24, s75, v[126:127]
	v_cvt_pk_bf16_f32 v11, v20, v21
	v_lshl_add_u64 v[18:19], v[18:19], 0, v[128:129]
	v_cvt_pk_bf16_f32 v12, v12, v13
	v_cvt_pk_bf16_f32 v13, v22, v23
	global_store_dwordx4 v[18:19], v[10:13], off
	s_mov_b64 s[2:3], -1
	s_nop 0
	v_pk_mul_f32 v[10:11], v[4:5], v[142:143] op_sel_hi:[1,0]
	v_pk_mul_f32 v[4:5], v[2:3], v[142:143] op_sel_hi:[1,0]
	v_cvt_pk_bf16_f32 v2, v6, v7
	v_cvt_pk_bf16_f32 v3, v8, v9
	s_nop 0
	v_cvt_pk_bf16_f32 v4, v4, v5
	v_cvt_pk_bf16_f32 v5, v10, v11
	global_store_dwordx4 v[18:19], v[2:5], off offset:256
	s_cbranch_vccnz .LBB0_754
	s_andn2_b64 vcc, exec, s[10:11]
	s_cbranch_vccnz .LBB0_753
	s_barrier
	s_branch .LBB0_753

; __device__ __forceinline__ float bflo(unsigned w) { return __uint_as_float(w << 16); }
; __device__ __forceinline__ float bfhi(unsigned w) { return __uint_as_float(w & 0xffff0000u); }
; __device__ __forceinline__ float shfl_x(float v, int m, int lane) { return __builtin_bit_cast(float, __builtin_amdgcn_ds_bpermute((lane ^ m) << 2, __builtin_bit_cast(int, v))); }
; __device__ __forceinline__ void sgu_unit(LAS unsigned char* lds, const bf16_t* proj, bf16_t* Y, const bf16_t* wsb  , const float* lnw, const float* lnb, const float* bs  , int row0, unsigned long long* gss, const int wave_s) {
;     ...
;         const int s = tid >> 2, q = tid & 3;
;         const u32x4* src = (const u32x4*)(proj + (size_t)(row0 + s) * PJP + PC_CV + 64 * q);
;         float v[64]; float sum = 0.f;
; #pragma unroll
;         for (int i = 0; i < 8; ++i) { const u32x4 w = src[i];
;             v[8 * i + 0] = bflo(w.x); v[8 * i + 1] = bfhi(w.x); v[8 * i + 2] = bflo(w.y); v[8 * i + 3] = bfhi(w.y);
;             v[8 * i + 4] = bflo(w.z); v[8 * i + 5] = bfhi(w.z); v[8 * i + 6] = bflo(w.w); v[8 * i + 7] = bfhi(w.w); }
; #pragma unroll
;         for (int i = 0; i < 64; ++i) sum += v[i];
;         sum += shfl_x(sum, 1, lane); sum += shfl_x(sum, 2, lane);
.LBB0_835:
	s_ashr_i32 s2, s4, 31
	s_lshr_b32 s2, s2, 23
	s_add_i32 s2, s4, s2
	s_and_b32 s2, s2, 0x1fffe00
	s_sub_i32 s2, s4, s2
	s_load_dwordx2 s[6:7], s[0:1], 0xb8
	s_waitcnt lgkmcnt(0)
	s_load_dwordx2 s[8:9], s[0:1], 0xb8
	s_waitcnt lgkmcnt(0)
	s_load_dwordx2 s[10:11], s[0:1], 0xb8
	s_waitcnt lgkmcnt(0)
	s_load_dwordx2 s[12:13], s[0:1], 0xb8
	s_waitcnt lgkmcnt(0)
	v_mbcnt_lo_u32_b32 v10, -1, 0
	v_mbcnt_hi_u32_b32 v10, -1, v10
	s_lshl_b32 s2, s2, 7
	v_or_b32_e32 v21, s63, v10
	v_ashrrev_i32_e32 v6, 2, v21
	v_add_u32_e32 v0, s2, v6
	v_mov_b64_e32 v[2:3], s[6:7]
	v_mad_i64_i32 v[4:5], s[6:7], v0, s85, v[2:3]
	v_lshlrev_b32_e32 v0, 6, v10
	v_and_b32_e32 v75, 0xc0, v0
	v_lshlrev_b32_e32 v0, 1, v75
	v_lshl_add_u64 v[4:5], v[4:5], 0, v[0:1]
	s_mov_b64 s[6:7], 0x10000000
	v_lshl_add_u64 v[4:5], v[4:5], 0, s[6:7]
	global_load_dwordx4 v[12:15], v[4:5], off offset:3584
	global_load_dwordx4 v[78:81], v[4:5], off offset:3680
	v_and_b32_e32 v9, 63, v10
	v_readfirstlane_b32 s3, v21
	v_lshlrev_b32_e32 v21, 2, v9
	v_and_b32_e32 v8, 31, v10
	v_bfe_u32 v10, v10, 5, 1
	s_ashr_i32 s22, s2, 31
	v_readlane_b32 s24, v255, 8
	v_readlane_b32 s25, v255, 9
	s_waitcnt vmcnt(0) lgkmcnt(0)
	v_lshlrev_b32_e32 v7, 16, v12
	v_and_b32_e32 v77, 0xffff0000, v12
	v_lshlrev_b32_e32 v76, 16, v13
	v_and_b32_e32 v74, 0xffff0000, v13
	v_lshlrev_b32_e32 v73, 16, v14
	v_and_b32_e32 v72, 0xffff0000, v14
	v_lshlrev_b32_e32 v71, 16, v15
	v_and_b32_e32 v69, 0xffff0000, v15
	global_load_dwordx4 v[12:15], v[4:5], off offset:3600
	v_lshlrev_b32_e32 v23, 16, v78
	v_and_b32_e32 v18, 0xffff0000, v78
	v_lshlrev_b32_e32 v11, 16, v81
	v_and_b32_e32 v0, 0xffff0000, v81
	s_waitcnt vmcnt(0) lgkmcnt(0)
	v_lshlrev_b32_e32 v70, 16, v12
	v_and_b32_e32 v68, 0xffff0000, v12
	v_lshlrev_b32_e32 v67, 16, v13
	v_and_b32_e32 v65, 0xffff0000, v13
	v_lshlrev_b32_e32 v64, 16, v14
	v_and_b32_e32 v63, 0xffff0000, v14
	v_lshlrev_b32_e32 v62, 16, v15
	v_and_b32_e32 v60, 0xffff0000, v15
	global_load_dwordx4 v[12:15], v[4:5], off offset:3616
	s_waitcnt vmcnt(0) lgkmcnt(0)
	v_lshlrev_b32_e32 v61, 16, v12
	v_and_b32_e32 v59, 0xffff0000, v12
	v_lshlrev_b32_e32 v58, 16, v13
	v_and_b32_e32 v57, 0xffff0000, v13
	v_lshlrev_b32_e32 v56, 16, v14
	v_and_b32_e32 v55, 0xffff0000, v14
	v_lshlrev_b32_e32 v54, 16, v15
	v_and_b32_e32 v52, 0xffff0000, v15
	global_load_dwordx4 v[12:15], v[4:5], off offset:3632
	s_waitcnt vmcnt(0) lgkmcnt(0)
	v_lshlrev_b32_e32 v53, 16, v12
	v_and_b32_e32 v51, 0xffff0000, v12
	v_lshlrev_b32_e32 v50, 16, v13
	v_and_b32_e32 v49, 0xffff0000, v13
	v_lshlrev_b32_e32 v47, 16, v14
	v_and_b32_e32 v46, 0xffff0000, v14
	v_lshlrev_b32_e32 v45, 16, v15
	v_and_b32_e32 v43, 0xffff0000, v15
	global_load_dwordx4 v[12:15], v[4:5], off offset:3648
	s_waitcnt vmcnt(0) lgkmcnt(0)
	v_lshlrev_b32_e32 v44, 16, v12
	v_and_b32_e32 v42, 0xffff0000, v12
	v_lshlrev_b32_e32 v41, 16, v13
	v_and_b32_e32 v40, 0xffff0000, v13
	v_lshlrev_b32_e32 v39, 16, v14
	v_and_b32_e32 v38, 0xffff0000, v14
	v_lshlrev_b32_e32 v37, 16, v15
	v_and_b32_e32 v35, 0xffff0000, v15
	global_load_dwordx4 v[12:15], v[4:5], off offset:3664
	s_waitcnt vmcnt(0) lgkmcnt(0)
	v_lshlrev_b32_e32 v36, 16, v12
	v_and_b32_e32 v34, 0xffff0000, v12
	v_lshlrev_b32_e32 v32, 16, v13
	v_and_b32_e32 v30, 0xffff0000, v13
	v_lshlrev_b32_e32 v28, 16, v14
	v_and_b32_e32 v26, 0xffff0000, v14
	v_lshlrev_b32_e32 v24, 16, v15
	v_and_b32_e32 v20, 0xffff0000, v15
	v_lshlrev_b32_e32 v15, 16, v79
	v_and_b32_e32 v14, 0xffff0000, v79
	v_lshlrev_b32_e32 v13, 16, v80
	v_and_b32_e32 v12, 0xffff0000, v80
	global_load_dwordx4 v[78:81], v[4:5], off offset:3696
	v_add_f32_e32 v4, 0, v7
	v_add_f32_e32 v4, v4, v77
	v_add_f32_e32 v4, v4, v76
	v_add_f32_e32 v4, v4, v74
	v_add_f32_e32 v4, v4, v73
	v_add_f32_e32 v4, v4, v72
	v_add_f32_e32 v4, v4, v71
	v_add_f32_e32 v4, v4, v69
	v_add_f32_e32 v4, v4, v70
	v_add_f32_e32 v4, v4, v68
	v_add_f32_e32 v4, v4, v67
	v_add_f32_e32 v4, v4, v65
	v_add_f32_e32 v4, v4, v64
	v_add_f32_e32 v4, v4, v63
	v_add_f32_e32 v4, v4, v62
	v_add_f32_e32 v4, v4, v60
	v_add_f32_e32 v4, v4, v61
	v_add_f32_e32 v4, v4, v59
	v_add_f32_e32 v4, v4, v58
	v_add_f32_e32 v4, v4, v57
	v_add_f32_e32 v4, v4, v56
	v_add_f32_e32 v4, v4, v55
	v_add_f32_e32 v4, v4, v54
	v_add_f32_e32 v4, v4, v52
	v_add_f32_e32 v4, v4, v53
	v_add_f32_e32 v4, v4, v51
	v_add_f32_e32 v4, v4, v50
	v_add_f32_e32 v4, v4, v49
	v_add_f32_e32 v4, v4, v47
	v_add_f32_e32 v4, v4, v46
	v_add_f32_e32 v4, v4, v45
	v_add_f32_e32 v4, v4, v43
	v_add_f32_e32 v4, v4, v44
	v_add_f32_e32 v4, v4, v42
	v_add_f32_e32 v4, v4, v41
	v_add_f32_e32 v4, v4, v40
	v_add_f32_e32 v4, v4, v39
	v_add_f32_e32 v4, v4, v38
	v_add_f32_e32 v4, v4, v37
	v_add_f32_e32 v4, v4, v35
	v_add_f32_e32 v4, v4, v36
	v_add_f32_e32 v4, v4, v34
	v_add_f32_e32 v4, v4, v32
	v_add_f32_e32 v4, v4, v30
	v_add_f32_e32 v4, v4, v28
	v_add_f32_e32 v4, v4, v26
	v_add_f32_e32 v4, v4, v24
	v_add_f32_e32 v4, v4, v20
	v_add_f32_e32 v4, v4, v23
	v_add_f32_e32 v4, v4, v18
	v_add_f32_e32 v4, v4, v15
	v_add_f32_e32 v4, v4, v14
	v_add_f32_e32 v4, v4, v13
	v_add_f32_e32 v4, v4, v12
	v_add_f32_e32 v4, v4, v11
	v_add_f32_e32 v4, v4, v0
	v_xor_b32_e32 v5, 4, v21
	s_waitcnt vmcnt(0) lgkmcnt(0)
	v_lshlrev_b32_e32 v33, 16, v78
	v_and_b32_e32 v31, 0xffff0000, v78
	v_add_f32_e32 v4, v4, v33
	v_lshlrev_b32_e32 v29, 16, v79
	v_add_f32_e32 v4, v4, v31
	v_and_b32_e32 v27, 0xffff0000, v79
	v_add_f32_e32 v4, v4, v29
	v_lshlrev_b32_e32 v25, 16, v80
	v_add_f32_e32 v4, v4, v27
	v_and_b32_e32 v22, 0xffff0000, v80
	v_add_f32_e32 v4, v4, v25
	v_lshlrev_b32_e32 v19, 16, v81
	v_add_f32_e32 v4, v4, v22
	v_and_b32_e32 v17, 0xffff0000, v81
	v_add_f32_e32 v4, v4, v19
	v_add_f32_e32 v4, v4, v17
	ds_bpermute_b32 v48, v5, v4
	s_waitcnt lgkmcnt(0)
; __device__ __forceinline__ unsigned cvtpk(float lo, float hi) { unsigned r; asm volatile("v_cvt_pk_bf16_f32 %0, %1, %2" : "=v"(r) : "v"(lo), "v"(hi)); return r; }
; __device__ __forceinline__ float shfl_x(float v, int m, int lane) { return __builtin_bit_cast(float, __builtin_amdgcn_ds_bpermute((lane ^ m) << 2, __builtin_bit_cast(int, v))); }
; __device__ __forceinline__ void sgu_unit(LAS unsigned char* lds, const bf16_t* proj, bf16_t* Y, const bf16_t* wsb  , const float* lnw, const float* lnb, const float* bs  , int row0, unsigned long long* gss, const int wave_s) {
;     ...
;         sum += shfl_x(sum, 1, lane); sum += shfl_x(sum, 2, lane);
;         const float mu = sum * (1.0f / 256.0f); float sq = 0.f;
; #pragma unroll
;         for (int i = 0; i < 64; ++i) { v[i] -= mu; sq += v[i] * v[i]; }
;         sq += shfl_x(sq, 1, lane); sq += shfl_x(sq, 2, lane);
;         const float rstd = 1.0f / sqrtf(sq * (1.0f / 256.0f) + EPS);
; #pragma unroll
;         for (int i = 0; i < 64; i += 2) {
;             const int c = 64 * q + i;
;             const float a = v[i] * rstd * lnw[c] + lnb[c], b = v[i + 1] * rstd * lnw[c + 1] + lnb[c + 1];
;             const unsigned w = cvtpk(a, b);
;             vt[c * SSTR + s] = (unsigned short)(w & 0xffffu); vt[(c + 1) * SSTR + s] = (unsigned short)(w >> 16);
;         }
	v_add_f32_e32 v4, v4, v48
	v_xor_b32_e32 v48, 8, v21
	ds_bpermute_b32 v66, v48, v4
	s_waitcnt lgkmcnt(0)
	v_add_f32_e32 v4, v4, v66
	v_fmac_f32_e32 v77, 0xbb800000, v4
	v_fmac_f32_e32 v7, 0xbb800000, v4
	v_mul_f32_e32 v66, v77, v77
	v_fmac_f32_e32 v66, v7, v7
	v_fmac_f32_e32 v76, 0xbb800000, v4
	v_fmac_f32_e32 v66, v76, v76
	v_fmac_f32_e32 v74, 0xbb800000, v4
	v_fmac_f32_e32 v66, v74, v74
	v_fmac_f32_e32 v73, 0xbb800000, v4
	v_fmac_f32_e32 v66, v73, v73
	v_fmac_f32_e32 v72, 0xbb800000, v4
	v_fmac_f32_e32 v66, v72, v72
	v_fmac_f32_e32 v71, 0xbb800000, v4
	v_fmac_f32_e32 v66, v71, v71
	v_fmac_f32_e32 v69, 0xbb800000, v4
	v_fmac_f32_e32 v66, v69, v69
	v_fmac_f32_e32 v70, 0xbb800000, v4
	v_fmac_f32_e32 v66, v70, v70
	v_fmac_f32_e32 v68, 0xbb800000, v4
	v_fmac_f32_e32 v66, v68, v68
	v_fmac_f32_e32 v67, 0xbb800000, v4
	v_fmac_f32_e32 v66, v67, v67
	v_fmac_f32_e32 v65, 0xbb800000, v4
	v_fmac_f32_e32 v66, v65, v65
	v_fmac_f32_e32 v64, 0xbb800000, v4
	v_fmac_f32_e32 v66, v64, v64
	v_fmac_f32_e32 v63, 0xbb800000, v4
	v_fmac_f32_e32 v66, v63, v63
	v_fmac_f32_e32 v62, 0xbb800000, v4
	v_fmac_f32_e32 v66, v62, v62
	v_fmac_f32_e32 v60, 0xbb800000, v4
	v_fmac_f32_e32 v66, v60, v60
	v_fmac_f32_e32 v61, 0xbb800000, v4
	v_fmac_f32_e32 v66, v61, v61
	v_fmac_f32_e32 v59, 0xbb800000, v4
	v_fmac_f32_e32 v66, v59, v59
	v_fmac_f32_e32 v58, 0xbb800000, v4
	v_fmac_f32_e32 v66, v58, v58
	v_fmac_f32_e32 v57, 0xbb800000, v4
	v_fmac_f32_e32 v66, v57, v57
	v_fmac_f32_e32 v56, 0xbb800000, v4
	v_fmac_f32_e32 v66, v56, v56
	v_fmac_f32_e32 v55, 0xbb800000, v4
	v_fmac_f32_e32 v66, v55, v55
	v_fmac_f32_e32 v54, 0xbb800000, v4
	v_fmac_f32_e32 v66, v54, v54
	v_fmac_f32_e32 v52, 0xbb800000, v4
	v_fmac_f32_e32 v66, v52, v52
	v_fmac_f32_e32 v53, 0xbb800000, v4
	v_fmac_f32_e32 v66, v53, v53
	v_fmac_f32_e32 v51, 0xbb800000, v4
	v_fmac_f32_e32 v66, v51, v51
	v_fmac_f32_e32 v50, 0xbb800000, v4
	v_fmac_f32_e32 v66, v50, v50
	v_fmac_f32_e32 v49, 0xbb800000, v4
	v_fmac_f32_e32 v66, v49, v49
	v_fmac_f32_e32 v47, 0xbb800000, v4
	v_fmac_f32_e32 v66, v47, v47
	v_fmac_f32_e32 v46, 0xbb800000, v4
	v_fmac_f32_e32 v66, v46, v46
	v_fmac_f32_e32 v45, 0xbb800000, v4
	v_fmac_f32_e32 v66, v45, v45
	v_fmac_f32_e32 v43, 0xbb800000, v4
	v_fmac_f32_e32 v66, v43, v43
	v_fmac_f32_e32 v44, 0xbb800000, v4
	v_fmac_f32_e32 v66, v44, v44
	v_fmac_f32_e32 v42, 0xbb800000, v4
	v_fmac_f32_e32 v66, v42, v42
	v_fmac_f32_e32 v41, 0xbb800000, v4
	v_fmac_f32_e32 v66, v41, v41
	v_fmac_f32_e32 v40, 0xbb800000, v4
	v_fmac_f32_e32 v66, v40, v40
	v_fmac_f32_e32 v39, 0xbb800000, v4
	v_fmac_f32_e32 v66, v39, v39
	v_fmac_f32_e32 v38, 0xbb800000, v4
	v_fmac_f32_e32 v66, v38, v38
	v_fmac_f32_e32 v37, 0xbb800000, v4
	v_fmac_f32_e32 v66, v37, v37
	v_fmac_f32_e32 v35, 0xbb800000, v4
	v_fmac_f32_e32 v66, v35, v35
	v_fmac_f32_e32 v36, 0xbb800000, v4
	v_fmac_f32_e32 v66, v36, v36
	v_fmac_f32_e32 v34, 0xbb800000, v4
	v_fmac_f32_e32 v66, v34, v34
	v_fmac_f32_e32 v32, 0xbb800000, v4
	v_fmac_f32_e32 v66, v32, v32
	v_fmac_f32_e32 v30, 0xbb800000, v4
	v_fmac_f32_e32 v66, v30, v30
	v_fmac_f32_e32 v28, 0xbb800000, v4
	v_fmac_f32_e32 v66, v28, v28
	v_fmac_f32_e32 v26, 0xbb800000, v4
	v_fmac_f32_e32 v66, v26, v26
	v_fmac_f32_e32 v24, 0xbb800000, v4
	v_fmac_f32_e32 v66, v24, v24
	v_fmac_f32_e32 v20, 0xbb800000, v4
	v_fmac_f32_e32 v66, v20, v20
	v_fmac_f32_e32 v23, 0xbb800000, v4
	v_fmac_f32_e32 v66, v23, v23
	v_fmac_f32_e32 v18, 0xbb800000, v4
	v_fmac_f32_e32 v66, v18, v18
	v_fmac_f32_e32 v15, 0xbb800000, v4
	v_fmac_f32_e32 v66, v15, v15
	v_fmac_f32_e32 v14, 0xbb800000, v4
	v_fmac_f32_e32 v66, v14, v14
	v_fmac_f32_e32 v13, 0xbb800000, v4
	v_fmac_f32_e32 v66, v13, v13
	v_fmac_f32_e32 v12, 0xbb800000, v4
	v_fmac_f32_e32 v66, v12, v12
	v_fmac_f32_e32 v11, 0xbb800000, v4
	v_fmac_f32_e32 v66, v11, v11
	v_fmac_f32_e32 v0, 0xbb800000, v4
	v_fmac_f32_e32 v66, v0, v0
	v_fmac_f32_e32 v33, 0xbb800000, v4
	v_fmac_f32_e32 v66, v33, v33
	v_fmac_f32_e32 v31, 0xbb800000, v4
	v_fmac_f32_e32 v66, v31, v31
	v_fmac_f32_e32 v29, 0xbb800000, v4
	v_fmac_f32_e32 v66, v29, v29
	v_fmac_f32_e32 v27, 0xbb800000, v4
	v_fmac_f32_e32 v66, v27, v27
	v_fmac_f32_e32 v25, 0xbb800000, v4
	v_fmac_f32_e32 v66, v25, v25
	v_fmac_f32_e32 v22, 0xbb800000, v4
	v_fmac_f32_e32 v66, v22, v22
	v_fmac_f32_e32 v19, 0xbb800000, v4
	v_fmac_f32_e32 v66, v19, v19
	v_fmac_f32_e32 v17, 0xbb800000, v4
	v_fmac_f32_e32 v66, v17, v17
	ds_bpermute_b32 v4, v5, v66
	s_waitcnt lgkmcnt(0)
	v_add_f32_e32 v4, v66, v4
	ds_bpermute_b32 v5, v48, v4
	s_waitcnt lgkmcnt(0)
	v_add_f32_e32 v4, v4, v5
	v_fmamk_f32 v4, v4, 0x3b800000, v226
	s_ashr_i32 s6, s3, 7
	s_lshr_b32 s7, s3, 1
	s_lshl_b32 s5, s6, 6
	v_rsq_f32_e32 v48, v4
	s_nop 0
	v_lshlrev_b32_e32 v66, 2, v75
	v_lshlrev_b32_e32 v78, 1, v6
	v_mul_f32_e32 v79, v7, v48
	global_load_dwordx2 v[4:5], v66, s[14:15]
	global_load_dwordx2 v[6:7], v66, s[16:17]
	v_mul_f32_e32 v0, v0, v48
	s_and_b32 s7, s7, 32
	s_or_b32 s5, s5, s7
	s_movk_i32 s7, 0x88
	s_and_b32 s3, s3, 0xffffff80
	s_waitcnt vmcnt(0)
	v_fma_f32 v4, v4, v79, v6
	v_mul_f32_e32 v6, v77, v48
	v_fmac_f32_e32 v7, v5, v6
	v_cvt_pk_bf16_f32 v5, v4, v7
	v_mul_u32_u24_e32 v4, 0x110, v75
	v_add3_u32 v4, 0, v78, v4
	ds_write_b16 v4, v5
	ds_write_b16_d16_hi v4, v5 offset:272
	v_mul_f32_e32 v5, v76, v48
	global_load_dwordx2 v[6:7], v66, s[14:15] offset:8
	global_load_dwordx2 v[76:77], v66, s[16:17] offset:8
	s_waitcnt vmcnt(0)
	v_fma_f32 v5, v6, v5, v76
	v_mul_f32_e32 v6, v74, v48
	v_fmac_f32_e32 v77, v7, v6
	v_cvt_pk_bf16_f32 v5, v5, v77
	ds_write_b16 v4, v5 offset:544
	ds_write_b16_d16_hi v4, v5 offset:816
	global_load_dwordx2 v[6:7], v66, s[14:15] offset:16
	global_load_dwordx2 v[74:75], v66, s[16:17] offset:16
	v_mul_f32_e32 v5, v73, v48
	s_waitcnt vmcnt(0)
; __device__ __forceinline__ unsigned cvtpk(float lo, float hi) { unsigned r; asm volatile("v_cvt_pk_bf16_f32 %0, %1, %2" : "=v"(r) : "v"(lo), "v"(hi)); return r; }
; __device__ __forceinline__ void sgu_unit(LAS unsigned char* lds, const bf16_t* proj, bf16_t* Y, const bf16_t* wsb  , const float* lnw, const float* lnb, const float* bs  , int row0, unsigned long long* gss, const int wave_s) {
;     ...
; #pragma unroll
;         for (int i = 0; i < 64; i += 2) {
;             const int c = 64 * q + i;
;             const float a = v[i] * rstd * lnw[c] + lnb[c], b = v[i + 1] * rstd * lnw[c + 1] + lnb[c + 1];
;             const unsigned w = cvtpk(a, b);
;             vt[c * SSTR + s] = (unsigned short)(w & 0xffffu); vt[(c + 1) * SSTR + s] = (unsigned short)(w >> 16);
;         }
	v_fma_f32 v5, v6, v5, v74
	v_mul_f32_e32 v6, v72, v48
	v_fmac_f32_e32 v75, v7, v6
	v_cvt_pk_bf16_f32 v5, v5, v75
	ds_write_b16 v4, v5 offset:1088
	ds_write_b16_d16_hi v4, v5 offset:1360
	global_load_dwordx2 v[6:7], v66, s[14:15] offset:24
	global_load_dwordx2 v[72:73], v66, s[16:17] offset:24
	v_mul_f32_e32 v5, v71, v48
	s_waitcnt vmcnt(0)
	v_fma_f32 v5, v6, v5, v72
	v_mul_f32_e32 v6, v69, v48
	v_fmac_f32_e32 v73, v7, v6
	v_cvt_pk_bf16_f32 v5, v5, v73
	ds_write_b16 v4, v5 offset:1632
	ds_write_b16_d16_hi v4, v5 offset:1904
	v_mul_f32_e32 v5, v70, v48
	global_load_dwordx2 v[6:7], v66, s[14:15] offset:32
	global_load_dwordx2 v[70:71], v66, s[16:17] offset:32
	s_waitcnt vmcnt(0)
	v_fma_f32 v5, v6, v5, v70
	v_mul_f32_e32 v6, v68, v48
	v_fmac_f32_e32 v71, v7, v6
	v_cvt_pk_bf16_f32 v5, v5, v71
	ds_write_b16 v4, v5 offset:2176
	ds_write_b16_d16_hi v4, v5 offset:2448
	global_load_dwordx2 v[6:7], v66, s[14:15] offset:40
	global_load_dwordx2 v[68:69], v66, s[16:17] offset:40
	v_mul_f32_e32 v5, v67, v48
	s_waitcnt vmcnt(0)
	v_fma_f32 v5, v6, v5, v68
	v_mul_f32_e32 v6, v65, v48
	v_fmac_f32_e32 v69, v7, v6
	v_cvt_pk_bf16_f32 v5, v5, v69
	ds_write_b16 v4, v5 offset:2720
	ds_write_b16_d16_hi v4, v5 offset:2992
	v_mul_f32_e32 v5, v64, v48
	global_load_dwordx2 v[6:7], v66, s[14:15] offset:48
	global_load_dwordx2 v[64:65], v66, s[16:17] offset:48
	s_waitcnt vmcnt(0)
	v_fma_f32 v5, v6, v5, v64
	v_mul_f32_e32 v6, v63, v48
	v_fmac_f32_e32 v65, v7, v6
	v_cvt_pk_bf16_f32 v5, v5, v65
	ds_write_b16 v4, v5 offset:3264
	ds_write_b16_d16_hi v4, v5 offset:3536
	v_mul_f32_e32 v5, v62, v48
	global_load_dwordx2 v[6:7], v66, s[14:15] offset:56
	global_load_dwordx2 v[62:63], v66, s[16:17] offset:56
	s_waitcnt vmcnt(0)
	v_fma_f32 v5, v6, v5, v62
	v_mul_f32_e32 v6, v60, v48
	v_fmac_f32_e32 v63, v7, v6
	v_cvt_pk_bf16_f32 v5, v5, v63
	ds_write_b16 v4, v5 offset:3808
	ds_write_b16_d16_hi v4, v5 offset:4080
	v_mul_f32_e32 v5, v61, v48
	global_load_dwordx2 v[6:7], v66, s[14:15] offset:64
	global_load_dwordx2 v[60:61], v66, s[16:17] offset:64
	s_waitcnt vmcnt(0)
	v_fma_f32 v5, v6, v5, v60
	v_mul_f32_e32 v6, v59, v48
	v_fmac_f32_e32 v61, v7, v6
	v_cvt_pk_bf16_f32 v5, v5, v61
	ds_write_b16 v4, v5 offset:4352
	ds_write_b16_d16_hi v4, v5 offset:4624
	v_mul_f32_e32 v5, v58, v48
	global_load_dwordx2 v[6:7], v66, s[14:15] offset:72
	global_load_dwordx2 v[58:59], v66, s[16:17] offset:72
	s_waitcnt vmcnt(0)
	v_fma_f32 v5, v6, v5, v58
	v_mul_f32_e32 v6, v57, v48
	v_fmac_f32_e32 v59, v7, v6
	v_cvt_pk_bf16_f32 v5, v5, v59
	ds_write_b16 v4, v5 offset:4896
	ds_write_b16_d16_hi v4, v5 offset:5168
	v_mul_f32_e32 v5, v56, v48
	global_load_dwordx2 v[6:7], v66, s[14:15] offset:80
	global_load_dwordx2 v[56:57], v66, s[16:17] offset:80
	s_waitcnt vmcnt(0)
	v_fma_f32 v5, v6, v5, v56
	v_mul_f32_e32 v6, v55, v48
	v_fmac_f32_e32 v57, v7, v6
	v_cvt_pk_bf16_f32 v5, v5, v57
	ds_write_b16 v4, v5 offset:5440
	ds_write_b16_d16_hi v4, v5 offset:5712
	v_mul_f32_e32 v5, v54, v48
	global_load_dwordx2 v[6:7], v66, s[14:15] offset:88
	global_load_dwordx2 v[54:55], v66, s[16:17] offset:88
	s_waitcnt vmcnt(0)
	v_fma_f32 v5, v6, v5, v54
	v_mul_f32_e32 v6, v52, v48
	v_fmac_f32_e32 v55, v7, v6
	v_cvt_pk_bf16_f32 v5, v5, v55
	ds_write_b16 v4, v5 offset:5984
	ds_write_b16_d16_hi v4, v5 offset:6256
	v_mul_f32_e32 v5, v53, v48
	global_load_dwordx2 v[6:7], v66, s[14:15] offset:96
	global_load_dwordx2 v[52:53], v66, s[16:17] offset:96
	s_waitcnt vmcnt(0)
	v_fma_f32 v5, v6, v5, v52
	v_mul_f32_e32 v6, v51, v48
	v_fmac_f32_e32 v53, v7, v6
	v_cvt_pk_bf16_f32 v5, v5, v53
	ds_write_b16 v4, v5 offset:6528
	ds_write_b16_d16_hi v4, v5 offset:6800
	v_mul_f32_e32 v5, v50, v48
	global_load_dwordx2 v[6:7], v66, s[14:15] offset:104
	global_load_dwordx2 v[50:51], v66, s[16:17] offset:104
	s_waitcnt vmcnt(0)
	v_fma_f32 v5, v6, v5, v50
	v_mul_f32_e32 v6, v49, v48
	v_fmac_f32_e32 v51, v7, v6
	v_cvt_pk_bf16_f32 v5, v5, v51
	ds_write_b16 v4, v5 offset:7072
	ds_write_b16_d16_hi v4, v5 offset:7344
	global_load_dwordx2 v[6:7], v66, s[14:15] offset:112
	global_load_dwordx2 v[50:51], v66, s[16:17] offset:112
	v_mul_f32_e32 v5, v47, v48
	s_waitcnt vmcnt(0)
	v_fma_f32 v5, v6, v5, v50
	v_mul_f32_e32 v6, v46, v48
	v_fmac_f32_e32 v51, v7, v6
	v_cvt_pk_bf16_f32 v5, v5, v51
	ds_write_b16 v4, v5 offset:7616
	ds_write_b16_d16_hi v4, v5 offset:7888
	global_load_dwordx2 v[6:7], v66, s[14:15] offset:120
	global_load_dwordx2 v[46:47], v66, s[16:17] offset:120
	v_mul_f32_e32 v5, v45, v48
	s_waitcnt vmcnt(0)
	v_fma_f32 v5, v6, v5, v46
	v_mul_f32_e32 v6, v43, v48
	v_fmac_f32_e32 v47, v7, v6
	v_cvt_pk_bf16_f32 v5, v5, v47
	ds_write_b16 v4, v5 offset:8160
	ds_write_b16_d16_hi v4, v5 offset:8432
	v_mul_f32_e32 v5, v44, v48
	global_load_dwordx2 v[6:7], v66, s[14:15] offset:128
	global_load_dwordx2 v[44:45], v66, s[16:17] offset:128
	s_waitcnt vmcnt(0)
	v_fma_f32 v5, v6, v5, v44
	v_mul_f32_e32 v6, v42, v48
	v_fmac_f32_e32 v45, v7, v6
	v_cvt_pk_bf16_f32 v5, v5, v45
	ds_write_b16 v4, v5 offset:8704
	ds_write_b16_d16_hi v4, v5 offset:8976
	global_load_dwordx2 v[6:7], v66, s[14:15] offset:136
	global_load_dwordx2 v[42:43], v66, s[16:17] offset:136
	v_mul_f32_e32 v5, v41, v48
	s_waitcnt vmcnt(0)
	v_fma_f32 v5, v6, v5, v42
	v_mul_f32_e32 v6, v40, v48
	v_fmac_f32_e32 v43, v7, v6
	v_cvt_pk_bf16_f32 v5, v5, v43
	ds_write_b16 v4, v5 offset:9248
	ds_write_b16_d16_hi v4, v5 offset:9520
	global_load_dwordx2 v[6:7], v66, s[14:15] offset:144
	global_load_dwordx2 v[40:41], v66, s[16:17] offset:144
	v_mul_f32_e32 v5, v39, v48
	s_waitcnt vmcnt(0)
; #define LAS __attribute__((address_space(3)))
; __device__ __forceinline__ unsigned cvtpk(float lo, float hi) { unsigned r; asm volatile("v_cvt_pk_bf16_f32 %0, %1, %2" : "=v"(r) : "v"(lo), "v"(hi)); return r; }
; __device__ __forceinline__ void sgu_unit(LAS unsigned char* lds, const bf16_t* proj, bf16_t* Y, const bf16_t* wsb  , const float* lnw, const float* lnb, const float* bs  , int row0, unsigned long long* gss, const int wave_s) {
;     ...
; #pragma unroll
;         for (int i = 0; i < 64; i += 2) {
;             const int c = 64 * q + i;
;             const float a = v[i] * rstd * lnw[c] + lnb[c], b = v[i + 1] * rstd * lnw[c + 1] + lnb[c + 1];
;             const unsigned w = cvtpk(a, b);
;             vt[c * SSTR + s] = (unsigned short)(w & 0xffffu); vt[(c + 1) * SSTR + s] = (unsigned short)(w >> 16);
;         }
;     }
;     __syncthreads();
;     const int g = wid >> 1, dh = wid & 1;
;     const LAS unsigned char* ab = lds + ((64 * g + 32 * dh + r32) * SSTR + 8 * hi) * 2;
;     const bf16_t* wg = wsb + (size_t)g * 128 * 128;
; #pragma unroll 1
;     for (int tt = 0; tt < 4; ++tt) {
;         f32x16 acc;
; #pragma unroll
;         for (int r = 0; r < 16; ++r) acc[r] = 0.f;
;         const bf16_t* wrow = wg + (size_t)(32 * tt + r32) * 128 + 8 * hi;
	v_fma_f32 v5, v6, v5, v40
	v_mul_f32_e32 v6, v38, v48
	v_fmac_f32_e32 v41, v7, v6
	v_cvt_pk_bf16_f32 v5, v5, v41
	ds_write_b16 v4, v5 offset:9792
	ds_write_b16_d16_hi v4, v5 offset:10064
	global_load_dwordx2 v[6:7], v66, s[14:15] offset:152
	global_load_dwordx2 v[38:39], v66, s[16:17] offset:152
	v_mul_f32_e32 v5, v37, v48
	s_waitcnt vmcnt(0)
	v_fma_f32 v5, v5, v6, v38
	v_mul_f32_e32 v6, v35, v48
	v_fmac_f32_e32 v39, v6, v7
	v_cvt_pk_bf16_f32 v5, v5, v39
	ds_write_b16 v4, v5 offset:10336
	ds_write_b16_d16_hi v4, v5 offset:10608
	v_mul_f32_e32 v5, v36, v48
	global_load_dwordx2 v[6:7], v66, s[14:15] offset:160
	global_load_dwordx2 v[36:37], v66, s[16:17] offset:160
	s_waitcnt vmcnt(0)
	v_fma_f32 v5, v5, v6, v36
	v_mul_f32_e32 v6, v34, v48
	v_fmac_f32_e32 v37, v6, v7
	v_cvt_pk_bf16_f32 v5, v5, v37
	ds_write_b16 v4, v5 offset:10880
	ds_write_b16_d16_hi v4, v5 offset:11152
	global_load_dwordx2 v[6:7], v66, s[14:15] offset:168
	global_load_dwordx2 v[34:35], v66, s[16:17] offset:168
	v_mul_f32_e32 v5, v32, v48
	s_waitcnt vmcnt(0)
	v_fma_f32 v5, v5, v6, v34
	v_mul_f32_e32 v6, v30, v48
	v_fmac_f32_e32 v35, v6, v7
	v_cvt_pk_bf16_f32 v5, v5, v35
	ds_write_b16 v4, v5 offset:11424
	ds_write_b16_d16_hi v4, v5 offset:11696
	global_load_dwordx2 v[6:7], v66, s[14:15] offset:176
	global_load_dwordx2 v[34:35], v66, s[16:17] offset:176
	v_mul_f32_e32 v5, v28, v48
	s_waitcnt vmcnt(0)
	v_fma_f32 v5, v5, v6, v34
	v_mul_f32_e32 v6, v26, v48
	v_fmac_f32_e32 v35, v6, v7
	v_cvt_pk_bf16_f32 v5, v5, v35
	ds_write_b16 v4, v5 offset:11968
	ds_write_b16_d16_hi v4, v5 offset:12240
	global_load_dwordx2 v[6:7], v66, s[14:15] offset:184
	global_load_dwordx2 v[34:35], v66, s[16:17] offset:184
	v_mul_f32_e32 v5, v24, v48
	s_waitcnt vmcnt(0)
	v_fma_f32 v5, v5, v6, v34
	v_mul_f32_e32 v6, v20, v48
	v_fmac_f32_e32 v35, v6, v7
	v_cvt_pk_bf16_f32 v5, v5, v35
	ds_write_b16 v4, v5 offset:12512
	ds_write_b16_d16_hi v4, v5 offset:12784
	global_load_dwordx2 v[6:7], v66, s[14:15] offset:192
	global_load_dwordx2 v[34:35], v66, s[16:17] offset:192
	v_mul_f32_e32 v5, v23, v48
	s_waitcnt vmcnt(0)
	v_fma_f32 v5, v5, v6, v34
	v_mul_f32_e32 v6, v18, v48
	v_fmac_f32_e32 v35, v6, v7
	v_cvt_pk_bf16_f32 v5, v5, v35
	ds_write_b16 v4, v5 offset:13056
	ds_write_b16_d16_hi v4, v5 offset:13328
	global_load_dwordx2 v[6:7], v66, s[14:15] offset:200
	global_load_dwordx2 v[34:35], v66, s[16:17] offset:200
	v_mul_f32_e32 v5, v15, v48
	s_waitcnt vmcnt(0)
	v_fma_f32 v5, v5, v6, v34
	v_mul_f32_e32 v6, v14, v48
	v_fmac_f32_e32 v35, v6, v7
	v_cvt_pk_bf16_f32 v5, v5, v35
	ds_write_b16 v4, v5 offset:13600
	ds_write_b16_d16_hi v4, v5 offset:13872
	global_load_dwordx2 v[6:7], v66, s[14:15] offset:208
	global_load_dwordx2 v[14:15], v66, s[16:17] offset:208
	v_mul_f32_e32 v5, v13, v48
	s_waitcnt vmcnt(0)
	v_fma_f32 v5, v5, v6, v14
	v_mul_f32_e32 v6, v12, v48
	v_fmac_f32_e32 v15, v6, v7
	v_cvt_pk_bf16_f32 v5, v5, v15
	ds_write_b16 v4, v5 offset:14144
	ds_write_b16_d16_hi v4, v5 offset:14416
	global_load_dwordx2 v[6:7], v66, s[14:15] offset:216
	global_load_dwordx2 v[12:13], v66, s[16:17] offset:216
	v_mul_f32_e32 v5, v11, v48
	v_or_b32_e32 v14, s3, v8
	s_waitcnt vmcnt(0)
	v_fma_f32 v5, v5, v6, v12
	v_fmac_f32_e32 v13, v0, v7
	v_cvt_pk_bf16_f32 v0, v5, v13
	ds_write_b16 v4, v0 offset:14688
	ds_write_b16_d16_hi v4, v0 offset:14960
	global_load_dwordx2 v[6:7], v66, s[14:15] offset:224
	global_load_dwordx2 v[12:13], v66, s[16:17] offset:224
	v_mul_f32_e32 v0, v33, v48
	v_mul_f32_e32 v5, v31, v48
	s_waitcnt vmcnt(0)
	v_fma_f32 v0, v0, v6, v12
	v_fmac_f32_e32 v13, v5, v7
	v_cvt_pk_bf16_f32 v0, v0, v13
	ds_write_b16 v4, v0 offset:15232
	ds_write_b16_d16_hi v4, v0 offset:15504
	global_load_dwordx2 v[6:7], v66, s[14:15] offset:232
	global_load_dwordx2 v[12:13], v66, s[16:17] offset:232
	v_mul_f32_e32 v0, v29, v48
	v_mul_f32_e32 v5, v27, v48
	s_waitcnt vmcnt(0)
	v_fma_f32 v0, v0, v6, v12
	v_fmac_f32_e32 v13, v5, v7
	v_cvt_pk_bf16_f32 v0, v0, v13
	ds_write_b16 v4, v0 offset:15776
	ds_write_b16_d16_hi v4, v0 offset:16048
	global_load_dwordx2 v[6:7], v66, s[14:15] offset:240
	global_load_dwordx2 v[12:13], v66, s[16:17] offset:240
	v_mul_f32_e32 v0, v25, v48
	v_mul_f32_e32 v5, v22, v48
	s_waitcnt vmcnt(0)
	v_fma_f32 v0, v0, v6, v12
	v_fmac_f32_e32 v13, v5, v7
	v_cvt_pk_bf16_f32 v0, v0, v13
	ds_write_b16 v4, v0 offset:16320
	ds_write_b16_d16_hi v4, v0 offset:16592
	global_load_dwordx2 v[6:7], v66, s[14:15] offset:248
	global_load_dwordx2 v[12:13], v66, s[16:17] offset:248
	v_mul_f32_e32 v0, v19, v48
	v_mul_f32_e32 v5, v17, v48
	s_waitcnt vmcnt(0)
	v_fma_f32 v0, v0, v6, v12
	v_fmac_f32_e32 v13, v5, v7
	v_cvt_pk_bf16_f32 v0, v0, v13
	ds_write_b16 v4, v0 offset:16864
	ds_write_b16_d16_hi v4, v0 offset:17136
	v_or_b32_e32 v0, s5, v8
	v_mul_lo_u32 v0, v0, s7
	s_ashr_i32 s7, s6, 31
	s_lshl_b64 s[20:21], s[6:7], 15
	v_lshlrev_b32_e32 v4, 3, v10
	s_add_u32 s12, s12, s24
	v_add_lshl_u32 v11, v0, v4, 1
	s_addc_u32 s13, s13, s25
	v_or_b32_e32 v4, s2, v8
	v_readlane_b32 s2, v255, 10
	v_readlane_b32 s3, v255, 11
	s_add_u32 s2, s10, s2
	v_lshlrev_b32_e32 v6, 8, v8
	v_lshlrev_b32_e32 v7, 4, v10
	s_addc_u32 s3, s11, s3
	v_or3_b32 v6, s20, v6, v7
	v_mov_b32_e32 v7, s21
	v_lshl_add_u64 v[52:53], s[2:3], 0, v[6:7]
	v_lshl_or_b32 v6, v10, 2, s5
	v_mov_b32_e32 v5, s22
	v_ashrrev_i32_e32 v7, 31, v6
	v_lshlrev_b64 v[54:55], 1, v[6:7]
	v_lshlrev_b64 v[6:7], 11, v[4:5]
	v_mad_u64_u32 v[58:59], s[2:3], v4, s85, v[2:3]
	v_mov_b32_e32 v2, 0x1080
	v_xor_b32_e32 v0, 0x80, v21
	v_cmp_gt_u32_e64 s[6:7], 32, v9
	v_lshl_add_u64 v[50:51], v[4:5], 3, s[12:13]
	v_lshl_add_u64 v[56:57], s[8:9], 0, v[6:7]
	v_mad_i32_i24 v59, s22, v2, v59
	s_mov_b32 s5, 0
	s_mov_b64 s[20:21], 0
	v_add_u32_e32 v17, 0, v11
	s_waitcnt lgkmcnt(0)
	s_barrier
	s_branch .LBB0_837

;     __device__ __forceinline__ void operator()(const f32x4 (&acc)[2][2][4][2], const Unit& u, int wr, int wc, int fr, int fq) const {
;     ...
;         if constexpr (GN) { ssq_t sc_[8];
; #pragma unroll
;             for (int i = 0; i < 8; ++i) sc_[i] = gsc[u.pm * BM + wr * 64 + fr + (i >> 2) * HALF + (i & 3) * 16];
; #pragma unroll
;             for (int i = 0; i < 8; ++i) rc[i] = 1.0f / sqrtf(ssq_val(sc_[i]) * (1.0f / 256.0f) + EPS); }
;         const int col0 = u.pn * BM + wc * 32 + 8 * fq; const int b = (u.pm * BM) >> 12;
;         const float* gp = gate + (size_t)b * NMOD + col0; const float* sp = sc + (size_t)b * NMOD + col0;
;         f32x4 g[2][2], cf[2][2];
; #pragma unroll
;         for (int bj = 0; bj < 2; ++bj) {
;             g[bj][0] = *(const f32x4*)(gp + bj * HALF); g[bj][1] = *(const f32x4*)(gp + bj * HALF + 4);
;             const f32x4 n0 = *(const f32x4*)(nw + col0 + bj * HALF), n1 = *(const f32x4*)(nw + col0 + bj * HALF + 4);
;             const f32x4 c0 = *(const f32x4*)(sp + bj * HALF), c1 = *(const f32x4*)(sp + bj * HALF + 4);
;             cf[bj][0] = n0 * (c0 + 1.0f); cf[bj][1] = n1 * (c1 + 1.0f);
;         }
; #pragma unroll
;         for (int ai = 0; ai < 2; ++ai)
; #pragma unroll
;         for (int mp = 0; mp < 4; mp += 2) {
;             u32x4 bv[2][2];
; #pragma unroll
;             for (int mm = 0; mm < 2; ++mm)
; #pragma unroll
;                 for (int bj = 0; bj < 2; ++bj)
;                     bv[mm][bj] = *(gl_u32x4*)(PG8_GCPTR(base) + (unsigned)((u.pm * BM + ai * HALF + wr * 64 + (mp + mm) * 16 + fr) * DM + col0 + bj * HALF) * 2u);
; #pragma unroll
;             for (int mm = 0; mm < 2; ++mm) {
;                 const int m = mp + mm;
;                 const int row = u.pm * BM + ai * HALF + wr * 64 + m * 16 + fr; float q = 0.f;
; #pragma unroll
;                 for (int bj = 0; bj < 2; ++bj) {
;                     const unsigned offb = (unsigned)(row * DM + col0 + bj * HALF) * 2u;
;                     const u32x4 bw = bv[mm][bj];
;                     const f32x4 b0 = (f32x4){__uint_as_float(bw.x << 16), __uint_as_float(bw.x & 0xffff0000u), __uint_as_float(bw.y << 16), __uint_as_float(bw.y & 0xffff0000u)};
;                     const f32x4 b1 = (f32x4){__uint_as_float(bw.z << 16), __uint_as_float(bw.z & 0xffff0000u), __uint_as_float(bw.w << 16), __uint_as_float(bw.w & 0xffff0000u)};
.LBB0_1087:
	s_lshl_b32 s2, s10, 8
	v_mbcnt_lo_u32_b32 v0, -1, 0
	v_mbcnt_hi_u32_b32 v0, -1, v0
	s_add_i32 s2, s2, s90
	v_and_b32_e32 v182, 15, v0
	v_or_b32_e32 v216, s2, v182
	v_ashrrev_i32_e32 v217, 31, v216
	v_lshl_add_u64 v[2:3], v[216:217], 3, s[16:17]
	global_load_dwordx2 v[70:71], v[2:3], off
	global_load_dwordx2 v[218:219], v[2:3], off offset:128
	global_load_dwordx2 v[214:215], v[2:3], off offset:256
	global_load_dwordx2 v[212:213], v[2:3], off offset:384
	global_load_dwordx2 v[210:211], v[2:3], off offset:1024
	global_load_dwordx2 v[208:209], v[2:3], off offset:1152
	global_load_dwordx2 v[206:207], v[2:3], off offset:1280
	s_nop 0
	global_load_dwordx2 v[2:3], v[2:3], off offset:1408
	v_bfe_u32 v183, v0, 4, 2
	v_lshlrev_b32_e32 v232, 11, v216
	s_waitcnt vmcnt(0) lgkmcnt(0)
	v_ffbh_u32_e32 v0, v71
	v_min_u32_e32 v0, 32, v0
	v_lshlrev_b64 v[70:71], v0, v[70:71]
	v_min_u32_e32 v70, 1, v70
	v_or_b32_e32 v70, v71, v70
	v_cvt_f32_u32_e32 v70, v70
	v_sub_u32_e32 v0, 32, v0
	v_ldexp_f32 v0, v70, v0
	v_mul_f32_e32 v0, 0x33800000, v0
	v_fmamk_f32 v0, v0, 0x3b800000, v226
	v_cmp_eq_u32_e64 s[8:9], 0, v183
	s_nop 0
	s_lshl_b32 s2, s50, 8
	v_rsq_f32_e32 v0, v0
	s_nop 0
	v_lshl_or_b32 v70, v183, 3, s2
	s_ashr_i32 s2, s10, 4
	v_or_b32_e32 v180, s91, v70
	s_mul_i32 s5, s2, 0x6000
	s_mul_hi_i32 s4, s2, 0x6000
	s_add_u32 s2, s52, s5
	v_ashrrev_i32_e32 v181, 31, v180
	s_addc_u32 s3, s83, s4
	v_lshlrev_b64 v[70:71], 2, v[180:181]
	v_lshl_add_u64 v[158:159], s[2:3], 0, v[70:71]
	s_add_u32 s2, s88, s5
	s_addc_u32 s3, s89, s4
	v_lshl_add_u64 v[174:175], s[2:3], 0, v[70:71]
	v_lshl_add_u64 v[160:161], s[20:21], 0, v[70:71]
	global_load_dwordx4 v[82:85], v[158:159], off
	global_load_dwordx4 v[78:81], v[158:159], off offset:16
	global_load_dwordx4 v[70:73], v[160:161], off offset:16
	global_load_dwordx4 v[74:77], v[160:161], off
	global_load_dwordx4 v[150:153], v[174:175], off
	global_load_dwordx4 v[154:157], v[174:175], off offset:16
	v_lshlrev_b32_e32 v230, 1, v180
	v_add_u32_e32 v231, v230, v232
	v_and_b32_e32 v240, 0xffff8000, v231
	v_bfe_u32 v241, v231, 11, 4
	v_lshl_or_b32 v240, v241, 6, v240
	v_bfe_u32 v241, v231, 9, 2
	v_lshl_or_b32 v240, v241, 13, v240
	v_bfe_u32 v241, v231, 6, 2
	v_lshl_or_b32 v240, v241, 11, v240
	v_and_b32_e32 v241, 48, v231
	v_or_b32_e32 v240, v240, v241
	s_movk_i32 s2, 0x80
	v_pk_mul_f32 v[146:147], v[146:147], v[0:1] op_sel_hi:[1,0]
	v_pk_mul_f32 v[148:149], v[148:149], v[0:1] op_sel_hi:[1,0]
	v_pk_mul_f32 v[142:143], v[142:143], v[0:1] op_sel_hi:[1,0]
	v_pk_mul_f32 v[144:145], v[144:145], v[0:1] op_sel_hi:[1,0]
	v_pk_mul_f32 v[138:139], v[138:139], v[0:1] op_sel_hi:[1,0]
	v_pk_mul_f32 v[140:141], v[140:141], v[0:1] op_sel_hi:[1,0]
	v_pk_mul_f32 v[134:135], v[134:135], v[0:1] op_sel_hi:[1,0]
	v_pk_mul_f32 v[136:137], v[136:137], v[0:1] op_sel_hi:[1,0]
	s_waitcnt vmcnt(0) lgkmcnt(0)
	v_pk_add_f32 v[152:153], v[152:153], 1.0 op_sel_hi:[1,0]
	v_pk_add_f32 v[150:151], v[150:151], 1.0 op_sel_hi:[1,0]
	v_pk_mul_f32 v[200:201], v[76:77], v[152:153]
	v_pk_mul_f32 v[204:205], v[74:75], v[150:151]
	v_pk_add_f32 v[74:75], v[156:157], 1.0 op_sel_hi:[1,0]
	v_pk_add_f32 v[76:77], v[154:155], 1.0 op_sel_hi:[1,0]
	v_pk_mul_f32 v[198:199], v[72:73], v[74:75]
	v_pk_mul_f32 v[202:203], v[70:71], v[76:77]
	global_load_dwordx4 v[74:77], v[158:159], off offset:512
	global_load_dwordx4 v[70:73], v[158:159], off offset:528
	global_load_dwordx4 v[150:153], v[160:161], off offset:528
	global_load_dwordx4 v[154:157], v[160:161], off offset:512
	s_nop 0
	global_load_dwordx4 v[158:161], v[174:175], off offset:512
	global_load_dwordx4 v[176:179], v[174:175], off offset:528
	s_waitcnt vmcnt(0) lgkmcnt(0)
	v_pk_add_f32 v[160:161], v[160:161], 1.0 op_sel_hi:[1,0]
	v_pk_add_f32 v[158:159], v[158:159], 1.0 op_sel_hi:[1,0]
	v_pk_mul_f32 v[196:197], v[156:157], v[160:161]
	v_pk_mul_f32 v[174:175], v[154:155], v[158:159]
	v_pk_add_f32 v[154:155], v[178:179], 1.0 op_sel_hi:[1,0]
	global_load_dwordx4 v[178:181], v240, s[22:23]
	global_load_dwordx4 v[158:161], v240, s[22:23] offset:1024
	v_pk_add_f32 v[156:157], v[176:177], 1.0 op_sel_hi:[1,0]
	v_pk_mul_f32 v[176:177], v[152:153], v[154:155]
	v_pk_mul_f32 v[194:195], v[150:151], v[156:157]
	v_lshlrev_b32_e32 v150, 6, v183
	v_lshlrev_b32_e32 v151, 2, v182
	v_bitop3_b32 v229, v150, 64, v151 bitop3:0x36
	v_bitop3_b32 v228, v150, s2, v151 bitop3:0x36
	v_add_u32_e32 v150, 0x8000, v240
	global_load_dwordx4 v[154:157], v150, s[22:23]
	s_nop 0
	global_load_dwordx4 v[150:153], v150, s[22:23] offset:1024
	s_waitcnt vmcnt(3)
	v_lshlrev_b32_e32 v182, 16, v178
	v_and_b32_e32 v183, 0xffff0000, v178
	v_lshlrev_b32_e32 v178, 16, v179
	v_and_b32_e32 v179, 0xffff0000, v179
	v_lshlrev_b32_e32 v184, 16, v180
	v_and_b32_e32 v185, 0xffff0000, v180
	v_lshlrev_b32_e32 v180, 16, v181
	v_and_b32_e32 v181, 0xffff0000, v181
	v_pk_fma_f32 v[148:149], v[84:85], v[148:149], v[178:179]
	v_pk_fma_f32 v[146:147], v[82:83], v[146:147], v[182:183]
	v_pk_fma_f32 v[178:179], v[80:81], v[144:145], v[180:181]
	v_pk_fma_f32 v[180:181], v[78:79], v[142:143], v[184:185]
	v_cvt_pk_bf16_f32 v142, v146, v147
	v_cvt_pk_bf16_f32 v143, v148, v149
	v_pk_mul_f32 v[182:183], v[198:199], v[178:179]
	v_cvt_pk_bf16_f32 v144, v180, v181
	v_cvt_pk_bf16_f32 v145, v178, v179
	global_store_dwordx4 v240, v[142:145], s[24:25]
	v_pk_mul_f32 v[184:185], v[202:203], v[180:181]
	s_nop 0
	v_pk_mul_f32 v[142:143], v[204:205], v[146:147]
	v_pk_mul_f32 v[144:145], v[200:201], v[148:149]
	v_cvt_pk_bf16_f32 v142, v142, v143
	s_nop 0
	v_cvt_pk_bf16_f32 v143, v144, v145
	v_cvt_pk_bf16_f32 v144, v184, v185
	v_cvt_pk_bf16_f32 v145, v182, v183
	global_store_dwordx4 v231, v[142:145], s[26:27]
	s_nop 1
	v_mul_f32_e32 v142, v147, v147
	v_mul_f32_e32 v143, v149, v149
	v_fmac_f32_e32 v142, v146, v146
	v_fmac_f32_e32 v143, v148, v148
	v_add_f32_e32 v142, v142, v143
	v_mul_f32_e32 v143, v181, v181
	v_fmac_f32_e32 v143, v180, v180
	v_add_f32_e32 v142, v143, v142
	v_mul_f32_e32 v143, v179, v179
	v_fmac_f32_e32 v143, v178, v178
	v_add_f32_e32 v178, v143, v142
	s_waitcnt vmcnt(4)
; __device__ __forceinline__ unsigned cvt_pk_bf16(float lo, float hi) { unsigned r; asm volatile("v_cvt_pk_bf16_f32 %0, %1, %2" : "=v"(r) : "v"(lo), "v"(hi)); return r; }
; #define PG8_GPTR(p) ((__attribute__((address_space(1))) char*)(p))
;     __device__ __forceinline__ void operator()(const f32x4 (&acc)[2][2][4][2], const Unit& u, int wr, int wc, int fr, int fq) const {
;     ...
;                     bv[mm][bj] = *(gl_u32x4*)(PG8_GCPTR(base) + (unsigned)((u.pm * BM + ai * HALF + wr * 64 + (mp + mm) * 16 + fr) * DM + col0 + bj * HALF) * 2u);
; #pragma unroll
;             for (int mm = 0; mm < 2; ++mm) {
;                 const int m = mp + mm;
;                 const int row = u.pm * BM + ai * HALF + wr * 64 + m * 16 + fr; float q = 0.f;
; #pragma unroll
;                 for (int bj = 0; bj < 2; ++bj) {
;                     const unsigned offb = (unsigned)(row * DM + col0 + bj * HALF) * 2u;
;                     const u32x4 bw = bv[mm][bj];
;                     const f32x4 b0 = (f32x4){__uint_as_float(bw.x << 16), __uint_as_float(bw.x & 0xffff0000u), __uint_as_float(bw.y << 16), __uint_as_float(bw.y & 0xffff0000u)};
;                     const f32x4 b1 = (f32x4){__uint_as_float(bw.z << 16), __uint_as_float(bw.z & 0xffff0000u), __uint_as_float(bw.w << 16), __uint_as_float(bw.w & 0xffff0000u)};
;                     f32x4 a0 = acc[ai][bj][m][0], a1 = acc[ai][bj][m][1]; if constexpr (GN) { a0 *= rc[ai * 4 + m]; a1 *= rc[ai * 4 + m]; }
;                     const f32x4 o0 = b0 + g[bj][0] * a0, o1 = b1 + g[bj][1] * a1;
;                     u32x4 wo; wo.x = cvt_pk_bf16(o0[0], o0[1]); wo.y = cvt_pk_bf16(o0[2], o0[3]); wo.z = cvt_pk_bf16(o1[0], o1[1]); wo.w = cvt_pk_bf16(o1[2], o1[3]);
;                     *(gs_u32x4*)(PG8_GPTR(out) + offb) = wo;
;                     if (xg) {
;                         const f32x4 h0 = o0 * cf[bj][0], h1 = o1 * cf[bj][1];
;                         u32x4 w; w.x = cvt_pk_bf16(h0[0], h0[1]); w.y = cvt_pk_bf16(h0[2], h0[3]); w.z = cvt_pk_bf16(h1[0], h1[1]); w.w = cvt_pk_bf16(h1[2], h1[3]);
;                         *(gs_u32x4*)(PG8_GPTR(xg) + offb) = w;
;                         q += (o0[0] * o0[0] + o0[1] * o0[1]) + (o0[2] * o0[2] + o0[3] * o0[3]) + (o1[0] * o1[0] + o1[1] * o1[1]) + (o1[2] * o1[2] + o1[3] * o1[3]);
;                     }
;                 }
;                 if (xg) ssq_put(ssq, row, q, fr, fq);
	v_lshlrev_b32_e32 v142, 16, v158
	v_and_b32_e32 v143, 0xffff0000, v158
	v_lshlrev_b32_e32 v144, 16, v159
	v_and_b32_e32 v145, 0xffff0000, v159
	v_lshlrev_b32_e32 v146, 16, v160
	v_and_b32_e32 v147, 0xffff0000, v160
	v_lshlrev_b32_e32 v148, 16, v161
	v_and_b32_e32 v149, 0xffff0000, v161
	v_pk_fma_f32 v[140:141], v[140:141], v[76:77], v[144:145]
	v_pk_fma_f32 v[138:139], v[138:139], v[74:75], v[142:143]
	v_pk_fma_f32 v[142:143], v[136:137], v[72:73], v[148:149]
	v_pk_fma_f32 v[144:145], v[134:135], v[70:71], v[146:147]
	v_cvt_pk_bf16_f32 v134, v138, v139
	v_cvt_pk_bf16_f32 v135, v140, v141
	v_pk_mul_f32 v[146:147], v[176:177], v[142:143]
	v_cvt_pk_bf16_f32 v136, v144, v145
	v_cvt_pk_bf16_f32 v137, v142, v143
	global_store_dwordx4 v240, v[134:137], s[24:25] offset:1024
	v_pk_mul_f32 v[148:149], v[194:195], v[144:145]
	v_mul_f32_e32 v0, v143, v143
	v_pk_mul_f32 v[136:137], v[196:197], v[140:141]
	v_pk_mul_f32 v[134:135], v[174:175], v[138:139]
	v_fmac_f32_e32 v0, v142, v142
	v_cvt_pk_bf16_f32 v134, v134, v135
	v_cvt_pk_bf16_f32 v135, v136, v137
	v_cvt_pk_bf16_f32 v136, v148, v149
	v_cvt_pk_bf16_f32 v137, v146, v147
	global_store_dwordx4 v231, v[134:137], s[26:27] offset:256
	s_nop 1
	v_mul_f32_e32 v135, v139, v139
	v_mul_f32_e32 v136, v141, v141
	v_mul_f32_e32 v134, v145, v145
	v_fmac_f32_e32 v135, v138, v138
	v_fmac_f32_e32 v136, v140, v140
	v_fmac_f32_e32 v134, v144, v144
	v_add_f32_e32 v135, v135, v136
	v_add_f32_e32 v134, v134, v135
	v_add_f32_e32 v0, v0, v134
	v_add_f32_e32 v0, v178, v0
	ds_bpermute_b32 v134, v229, v0
	s_waitcnt lgkmcnt(0)
	v_add_f32_e32 v0, v0, v134
	ds_bpermute_b32 v136, v228, v0
	v_lshl_add_u64 v[134:135], v[216:217], 3, s[28:29]
	s_and_saveexec_b64 s[2:3], s[8:9]
	s_cbranch_execz .LBB0_1089
	s_waitcnt lgkmcnt(0)
	v_add_f32_e32 v0, v0, v136
	v_mul_f32_e32 v0, 0x4b800000, v0
	v_trunc_f32_e32 v0, v0
	v_mul_f32_e32 v136, 0x2f800000, v0
	v_floor_f32_e32 v137, v136
	v_fmac_f32_e32 v0, 0xcf800000, v137
	v_cvt_u32_f32_e32 v136, v0
	v_cvt_u32_f32_e32 v137, v137
	global_atomic_add_x2 v[134:135], v[136:137], off
.LBB0_1089:
	s_or_b64 exec, exec, s[2:3]
	v_ffbh_u32_e32 v0, v219
	v_min_u32_e32 v0, 32, v0
	s_waitcnt lgkmcnt(0)
	v_lshlrev_b64 v[136:137], v0, v[218:219]
	v_min_u32_e32 v136, 1, v136
	v_or_b32_e32 v136, v137, v136
	v_cvt_f32_u32_e32 v136, v136
	v_sub_u32_e32 v0, 32, v0
	s_waitcnt vmcnt(0)
	v_and_b32_e32 v141, 0xffff0000, v155
	v_lshlrev_b32_e32 v142, 16, v156
	v_ldexp_f32 v0, v136, v0
	v_mul_f32_e32 v0, 0x33800000, v0
	v_fmamk_f32 v0, v0, 0x3b800000, v226
	v_and_b32_e32 v143, 0xffff0000, v156
	v_lshlrev_b32_e32 v144, 16, v157
	v_and_b32_e32 v145, 0xffff0000, v157
	s_mov_b32 s2, 0x8000
	v_rsq_f32_e32 v0, v0
	s_nop 0
	v_lshlrev_b32_e32 v136, 11, v216
	v_lshlrev_b32_e32 v138, 16, v154
	v_and_b32_e32 v139, 0xffff0000, v154
	v_lshlrev_b32_e32 v140, 16, v155
	v_pk_mul_f32 v[130:131], v[130:131], v[0:1] op_sel_hi:[1,0]
	v_pk_mul_f32 v[132:133], v[132:133], v[0:1] op_sel_hi:[1,0]
	v_pk_mul_f32 v[126:127], v[126:127], v[0:1] op_sel_hi:[1,0]
	v_add3_u32 v137, v230, v136, s2
	v_add_u32_e32 v241, s2, v240
	v_pk_mul_f32 v[128:129], v[128:129], v[0:1] op_sel_hi:[1,0]
	v_pk_fma_f32 v[132:133], v[84:85], v[132:133], v[140:141]
	v_pk_fma_f32 v[130:131], v[82:83], v[130:131], v[138:139]
	v_pk_fma_f32 v[140:141], v[78:79], v[126:127], v[142:143]
	v_cvt_pk_bf16_f32 v126, v130, v131
	v_cvt_pk_bf16_f32 v127, v132, v133
	v_pk_fma_f32 v[138:139], v[80:81], v[128:129], v[144:145]
	v_cvt_pk_bf16_f32 v128, v140, v141
	v_pk_mul_f32 v[144:145], v[202:203], v[140:141]
	v_cvt_pk_bf16_f32 v129, v138, v139
	global_store_dwordx4 v241, v[126:129], s[24:25]
	v_pk_mul_f32 v[142:143], v[198:199], v[138:139]
	v_pk_mul_f32 v[122:123], v[122:123], v[0:1] op_sel_hi:[1,0]
	v_pk_mul_f32 v[126:127], v[204:205], v[130:131]
	v_pk_mul_f32 v[128:129], v[200:201], v[132:133]
	v_cvt_pk_bf16_f32 v126, v126, v127
	v_pk_mul_f32 v[124:125], v[124:125], v[0:1] op_sel_hi:[1,0]
	v_cvt_pk_bf16_f32 v127, v128, v129
	v_cvt_pk_bf16_f32 v128, v144, v145
	v_cvt_pk_bf16_f32 v129, v142, v143
	global_store_dwordx4 v137, v[126:129], s[26:27]
	v_pk_mul_f32 v[118:119], v[118:119], v[0:1] op_sel_hi:[1,0]
	v_pk_mul_f32 v[120:121], v[120:121], v[0:1] op_sel_hi:[1,0]
	v_mul_f32_e32 v126, v131, v131
	v_mul_f32_e32 v127, v133, v133
	v_fmac_f32_e32 v126, v130, v130
	v_fmac_f32_e32 v127, v132, v132
	v_add_f32_e32 v126, v126, v127
	v_mul_f32_e32 v127, v141, v141
	v_fmac_f32_e32 v127, v140, v140
	v_add_f32_e32 v126, v127, v126
	v_mul_f32_e32 v127, v139, v139
	v_fmac_f32_e32 v127, v138, v138
	v_add_f32_e32 v138, v127, v126
	v_lshlrev_b32_e32 v126, 16, v150
	v_and_b32_e32 v127, 0xffff0000, v150
	v_lshlrev_b32_e32 v128, 16, v151
	v_and_b32_e32 v129, 0xffff0000, v151
	v_lshlrev_b32_e32 v130, 16, v152
	v_and_b32_e32 v131, 0xffff0000, v152
	v_lshlrev_b32_e32 v132, 16, v153
	v_and_b32_e32 v133, 0xffff0000, v153
	v_pk_fma_f32 v[124:125], v[124:125], v[76:77], v[128:129]
	v_pk_fma_f32 v[122:123], v[122:123], v[74:75], v[126:127]
	v_pk_fma_f32 v[126:127], v[120:121], v[72:73], v[132:133]
	v_pk_fma_f32 v[128:129], v[118:119], v[70:71], v[130:131]
	v_cvt_pk_bf16_f32 v118, v122, v123
	v_cvt_pk_bf16_f32 v119, v124, v125
	v_mul_f32_e32 v0, v127, v127
	v_cvt_pk_bf16_f32 v120, v128, v129
	v_cvt_pk_bf16_f32 v121, v126, v127
	global_store_dwordx4 v241, v[118:121], s[24:25] offset:1024
	v_fmac_f32_e32 v0, v126, v126
	v_pk_mul_f32 v[130:131], v[196:197], v[124:125]
	v_mul_f32_e32 v119, v123, v123
	v_mul_f32_e32 v120, v125, v125
	v_mul_f32_e32 v118, v129, v129
	v_fmac_f32_e32 v119, v122, v122
	v_fmac_f32_e32 v120, v124, v124
	v_fmac_f32_e32 v118, v128, v128
	v_add_f32_e32 v119, v119, v120
	v_add_f32_e32 v118, v118, v119
	v_add_f32_e32 v0, v0, v118
	v_add_f32_e32 v0, v138, v0
	ds_bpermute_b32 v121, v229, v0
	v_pk_mul_f32 v[118:119], v[174:175], v[122:123]
	v_pk_mul_f32 v[122:123], v[194:195], v[128:129]
	v_cvt_pk_bf16_f32 v120, v118, v119
	v_pk_mul_f32 v[124:125], v[176:177], v[126:127]
	s_waitcnt lgkmcnt(0)
	v_add_f32_e32 v0, v0, v121
	ds_bpermute_b32 v118, v228, v0
	v_cvt_pk_bf16_f32 v121, v130, v131
	v_cvt_pk_bf16_f32 v122, v122, v123
	v_cvt_pk_bf16_f32 v123, v124, v125
	global_store_dwordx4 v137, v[120:123], s[26:27] offset:256
	s_and_saveexec_b64 s[2:3], s[8:9]
	s_cbranch_execz .LBB0_1091
	s_waitcnt lgkmcnt(0)
	v_add_f32_e32 v0, v0, v118
	v_mul_f32_e32 v0, 0x4b800000, v0
	v_trunc_f32_e32 v0, v0
	v_mul_f32_e32 v118, 0x2f800000, v0
	v_floor_f32_e32 v119, v118
	v_fmac_f32_e32 v0, 0xcf800000, v119
	v_cvt_u32_f32_e32 v118, v0
	v_cvt_u32_f32_e32 v119, v119
	global_atomic_add_x2 v[134:135], v[118:119], off offset:128
; __device__ __forceinline__ unsigned cvt_pk_bf16(float lo, float hi) { unsigned r; asm volatile("v_cvt_pk_bf16_f32 %0, %1, %2" : "=v"(r) : "v"(lo), "v"(hi)); return r; }
; #define PG8_GPTR(p) ((__attribute__((address_space(1))) char*)(p))
;     __device__ __forceinline__ void operator()(const f32x4 (&acc)[2][2][4][2], const Unit& u, int wr, int wc, int fr, int fq) const {
;     ...
;                     bv[mm][bj] = *(gl_u32x4*)(PG8_GCPTR(base) + (unsigned)((u.pm * BM + ai * HALF + wr * 64 + (mp + mm) * 16 + fr) * DM + col0 + bj * HALF) * 2u);
; #pragma unroll
;             for (int mm = 0; mm < 2; ++mm) {
;                 const int m = mp + mm;
;                 const int row = u.pm * BM + ai * HALF + wr * 64 + m * 16 + fr; float q = 0.f;
; #pragma unroll
;                 for (int bj = 0; bj < 2; ++bj) {
;                     const unsigned offb = (unsigned)(row * DM + col0 + bj * HALF) * 2u;
;                     const u32x4 bw = bv[mm][bj];
;                     const f32x4 b0 = (f32x4){__uint_as_float(bw.x << 16), __uint_as_float(bw.x & 0xffff0000u), __uint_as_float(bw.y << 16), __uint_as_float(bw.y & 0xffff0000u)};
;                     const f32x4 b1 = (f32x4){__uint_as_float(bw.z << 16), __uint_as_float(bw.z & 0xffff0000u), __uint_as_float(bw.w << 16), __uint_as_float(bw.w & 0xffff0000u)};
;                     f32x4 a0 = acc[ai][bj][m][0], a1 = acc[ai][bj][m][1]; if constexpr (GN) { a0 *= rc[ai * 4 + m]; a1 *= rc[ai * 4 + m]; }
;                     const f32x4 o0 = b0 + g[bj][0] * a0, o1 = b1 + g[bj][1] * a1;
;                     u32x4 wo; wo.x = cvt_pk_bf16(o0[0], o0[1]); wo.y = cvt_pk_bf16(o0[2], o0[3]); wo.z = cvt_pk_bf16(o1[0], o1[1]); wo.w = cvt_pk_bf16(o1[2], o1[3]);
;                     *(gs_u32x4*)(PG8_GPTR(out) + offb) = wo;
;                     if (xg) {
;                         const f32x4 h0 = o0 * cf[bj][0], h1 = o1 * cf[bj][1];
;                         u32x4 w; w.x = cvt_pk_bf16(h0[0], h0[1]); w.y = cvt_pk_bf16(h0[2], h0[3]); w.z = cvt_pk_bf16(h1[0], h1[1]); w.w = cvt_pk_bf16(h1[2], h1[3]);
;                         *(gs_u32x4*)(PG8_GPTR(xg) + offb) = w;
;                         q += (o0[0] * o0[0] + o0[1] * o0[1]) + (o0[2] * o0[2] + o0[3] * o0[3]) + (o1[0] * o1[0] + o1[1] * o1[1]) + (o1[2] * o1[2] + o1[3] * o1[3]);
;                     }
;                 }
;                 if (xg) ssq_put(ssq, row, q, fr, fq);
.LBB0_1091:
	s_or_b64 exec, exec, s[2:3]
	v_ffbh_u32_e32 v0, v215
	v_min_u32_e32 v0, 32, v0
	s_waitcnt lgkmcnt(0)
	v_lshlrev_b64 v[118:119], v0, v[214:215]
	v_min_u32_e32 v118, 1, v118
	v_or_b32_e32 v118, v119, v118
	v_cvt_f32_u32_e32 v118, v118
	v_sub_u32_e32 v0, 32, v0
	v_ldexp_f32 v0, v118, v0
	v_mul_f32_e32 v0, 0x33800000, v0
	v_fmamk_f32 v0, v0, 0x3b800000, v226
	s_mov_b32 s2, 0x10000
	v_add3_u32 v137, v230, v136, s2
	v_add_u32_e32 v241, s2, v240
	v_rsq_f32_e32 v0, v0
	s_nop 0
	v_add_u32_e32 v118, 0x10000, v240
	global_load_dwordx4 v[130:133], v118, s[22:23]
	global_load_dwordx4 v[126:129], v118, s[22:23] offset:1024
	v_add_u32_e32 v118, 0x18000, v240
	global_load_dwordx4 v[122:125], v118, s[22:23]
	s_nop 0
	global_load_dwordx4 v[118:121], v118, s[22:23] offset:1024
	v_pk_mul_f32 v[114:115], v[114:115], v[0:1] op_sel_hi:[1,0]
	v_pk_mul_f32 v[116:117], v[116:117], v[0:1] op_sel_hi:[1,0]
	v_pk_mul_f32 v[110:111], v[110:111], v[0:1] op_sel_hi:[1,0]
	v_pk_mul_f32 v[112:113], v[112:113], v[0:1] op_sel_hi:[1,0]
	v_pk_mul_f32 v[106:107], v[106:107], v[0:1] op_sel_hi:[1,0]
	v_pk_mul_f32 v[108:109], v[108:109], v[0:1] op_sel_hi:[1,0]
	v_pk_mul_f32 v[102:103], v[102:103], v[0:1] op_sel_hi:[1,0]
	v_pk_mul_f32 v[104:105], v[104:105], v[0:1] op_sel_hi:[1,0]
	s_waitcnt vmcnt(0)
	v_lshlrev_b32_e32 v138, 16, v130
	v_and_b32_e32 v139, 0xffff0000, v130
	v_lshlrev_b32_e32 v130, 16, v131
	v_and_b32_e32 v131, 0xffff0000, v131
	v_lshlrev_b32_e32 v140, 16, v132
	v_and_b32_e32 v141, 0xffff0000, v132
	v_lshlrev_b32_e32 v132, 16, v133
	v_and_b32_e32 v133, 0xffff0000, v133
	v_pk_fma_f32 v[116:117], v[84:85], v[116:117], v[130:131]
	v_pk_fma_f32 v[114:115], v[82:83], v[114:115], v[138:139]
	v_pk_fma_f32 v[130:131], v[80:81], v[112:113], v[132:133]
	v_pk_fma_f32 v[132:133], v[78:79], v[110:111], v[140:141]
	v_cvt_pk_bf16_f32 v110, v114, v115
	v_cvt_pk_bf16_f32 v111, v116, v117
	v_pk_mul_f32 v[138:139], v[198:199], v[130:131]
	v_cvt_pk_bf16_f32 v112, v132, v133
	v_cvt_pk_bf16_f32 v113, v130, v131
	global_store_dwordx4 v241, v[110:113], s[24:25]
	v_pk_mul_f32 v[140:141], v[202:203], v[132:133]
	s_nop 0
	v_pk_mul_f32 v[110:111], v[204:205], v[114:115]
	v_pk_mul_f32 v[112:113], v[200:201], v[116:117]
	v_cvt_pk_bf16_f32 v110, v110, v111
	s_nop 0
	v_cvt_pk_bf16_f32 v111, v112, v113
	v_cvt_pk_bf16_f32 v112, v140, v141
	v_cvt_pk_bf16_f32 v113, v138, v139
	global_store_dwordx4 v137, v[110:113], s[26:27]
	s_nop 1
	v_mul_f32_e32 v110, v115, v115
	v_mul_f32_e32 v111, v117, v117
	v_fmac_f32_e32 v110, v114, v114
	v_fmac_f32_e32 v111, v116, v116
	v_add_f32_e32 v110, v110, v111
	v_mul_f32_e32 v111, v133, v133
	v_fmac_f32_e32 v111, v132, v132
	v_add_f32_e32 v110, v111, v110
	v_mul_f32_e32 v111, v131, v131
	v_fmac_f32_e32 v111, v130, v130
	v_add_f32_e32 v130, v111, v110
	v_lshlrev_b32_e32 v110, 16, v126
	v_and_b32_e32 v111, 0xffff0000, v126
	v_lshlrev_b32_e32 v112, 16, v127
	v_and_b32_e32 v113, 0xffff0000, v127
	v_lshlrev_b32_e32 v114, 16, v128
	v_and_b32_e32 v115, 0xffff0000, v128
	v_lshlrev_b32_e32 v116, 16, v129
	v_and_b32_e32 v117, 0xffff0000, v129
	v_pk_fma_f32 v[108:109], v[108:109], v[76:77], v[112:113]
	v_pk_fma_f32 v[106:107], v[106:107], v[74:75], v[110:111]
	v_pk_fma_f32 v[110:111], v[104:105], v[72:73], v[116:117]
	v_pk_fma_f32 v[112:113], v[102:103], v[70:71], v[114:115]
	v_cvt_pk_bf16_f32 v102, v106, v107
	v_cvt_pk_bf16_f32 v103, v108, v109
	v_pk_mul_f32 v[114:115], v[176:177], v[110:111]
	v_cvt_pk_bf16_f32 v104, v112, v113
	v_cvt_pk_bf16_f32 v105, v110, v111
	global_store_dwordx4 v241, v[102:105], s[24:25] offset:1024
	v_pk_mul_f32 v[116:117], v[194:195], v[112:113]
	v_mul_f32_e32 v0, v111, v111
	v_pk_mul_f32 v[104:105], v[196:197], v[108:109]
	v_pk_mul_f32 v[102:103], v[174:175], v[106:107]
	v_fmac_f32_e32 v0, v110, v110
	v_cvt_pk_bf16_f32 v102, v102, v103
	v_cvt_pk_bf16_f32 v103, v104, v105
	v_cvt_pk_bf16_f32 v104, v116, v117
	v_cvt_pk_bf16_f32 v105, v114, v115
	global_store_dwordx4 v137, v[102:105], s[26:27] offset:256
	s_nop 1
	v_mul_f32_e32 v103, v107, v107
	v_mul_f32_e32 v104, v109, v109
	v_mul_f32_e32 v102, v113, v113
	v_fmac_f32_e32 v103, v106, v106
	v_fmac_f32_e32 v104, v108, v108
	v_fmac_f32_e32 v102, v112, v112
	v_add_f32_e32 v103, v103, v104
	v_add_f32_e32 v102, v102, v103
	v_add_f32_e32 v0, v0, v102
	v_add_f32_e32 v0, v130, v0
	ds_bpermute_b32 v102, v229, v0
	s_waitcnt lgkmcnt(0)
	v_add_f32_e32 v0, v0, v102
	ds_bpermute_b32 v102, v228, v0
	s_and_saveexec_b64 s[2:3], s[8:9]
	s_cbranch_execz .LBB0_1093
	s_waitcnt lgkmcnt(0)
	v_add_f32_e32 v0, v0, v102
	v_mul_f32_e32 v0, 0x4b800000, v0
	v_trunc_f32_e32 v0, v0
	v_mul_f32_e32 v102, 0x2f800000, v0
	v_floor_f32_e32 v103, v102
	v_fmac_f32_e32 v0, 0xcf800000, v103
	v_cvt_u32_f32_e32 v102, v0
	v_cvt_u32_f32_e32 v103, v103
	global_atomic_add_x2 v[134:135], v[102:103], off offset:256
; __device__ __forceinline__ unsigned cvt_pk_bf16(float lo, float hi) { unsigned r; asm volatile("v_cvt_pk_bf16_f32 %0, %1, %2" : "=v"(r) : "v"(lo), "v"(hi)); return r; }
; #define PG8_GPTR(p) ((__attribute__((address_space(1))) char*)(p))
;     __device__ __forceinline__ void operator()(const f32x4 (&acc)[2][2][4][2], const Unit& u, int wr, int wc, int fr, int fq) const {
;     ...
;                     bv[mm][bj] = *(gl_u32x4*)(PG8_GCPTR(base) + (unsigned)((u.pm * BM + ai * HALF + wr * 64 + (mp + mm) * 16 + fr) * DM + col0 + bj * HALF) * 2u);
; #pragma unroll
;             for (int mm = 0; mm < 2; ++mm) {
;                 const int m = mp + mm;
;                 const int row = u.pm * BM + ai * HALF + wr * 64 + m * 16 + fr; float q = 0.f;
; #pragma unroll
;                 for (int bj = 0; bj < 2; ++bj) {
;                     const unsigned offb = (unsigned)(row * DM + col0 + bj * HALF) * 2u;
;                     const u32x4 bw = bv[mm][bj];
;                     const f32x4 b0 = (f32x4){__uint_as_float(bw.x << 16), __uint_as_float(bw.x & 0xffff0000u), __uint_as_float(bw.y << 16), __uint_as_float(bw.y & 0xffff0000u)};
;                     const f32x4 b1 = (f32x4){__uint_as_float(bw.z << 16), __uint_as_float(bw.z & 0xffff0000u), __uint_as_float(bw.w << 16), __uint_as_float(bw.w & 0xffff0000u)};
;                     f32x4 a0 = acc[ai][bj][m][0], a1 = acc[ai][bj][m][1]; if constexpr (GN) { a0 *= rc[ai * 4 + m]; a1 *= rc[ai * 4 + m]; }
;                     const f32x4 o0 = b0 + g[bj][0] * a0, o1 = b1 + g[bj][1] * a1;
;                     u32x4 wo; wo.x = cvt_pk_bf16(o0[0], o0[1]); wo.y = cvt_pk_bf16(o0[2], o0[3]); wo.z = cvt_pk_bf16(o1[0], o1[1]); wo.w = cvt_pk_bf16(o1[2], o1[3]);
;                     *(gs_u32x4*)(PG8_GPTR(out) + offb) = wo;
;                     if (xg) {
;                         const f32x4 h0 = o0 * cf[bj][0], h1 = o1 * cf[bj][1];
;                         u32x4 w; w.x = cvt_pk_bf16(h0[0], h0[1]); w.y = cvt_pk_bf16(h0[2], h0[3]); w.z = cvt_pk_bf16(h1[0], h1[1]); w.w = cvt_pk_bf16(h1[2], h1[3]);
;                         *(gs_u32x4*)(PG8_GPTR(xg) + offb) = w;
;                         q += (o0[0] * o0[0] + o0[1] * o0[1]) + (o0[2] * o0[2] + o0[3] * o0[3]) + (o1[0] * o1[0] + o1[1] * o1[1]) + (o1[2] * o1[2] + o1[3] * o1[3]);
;                     }
;                 }
;                 if (xg) ssq_put(ssq, row, q, fr, fq);
.LBB0_1093:
	s_or_b64 exec, exec, s[2:3]
	v_ffbh_u32_e32 v0, v213
	v_min_u32_e32 v0, 32, v0
	s_waitcnt lgkmcnt(0)
	v_lshlrev_b64 v[102:103], v0, v[212:213]
	v_min_u32_e32 v102, 1, v102
	v_or_b32_e32 v102, v103, v102
	v_cvt_f32_u32_e32 v102, v102
	v_sub_u32_e32 v0, 32, v0
	v_and_b32_e32 v107, 0xffff0000, v124
	v_lshlrev_b32_e32 v108, 16, v125
	v_ldexp_f32 v0, v102, v0
	v_mul_f32_e32 v0, 0x33800000, v0
	v_fmamk_f32 v0, v0, 0x3b800000, v226
	v_and_b32_e32 v109, 0xffff0000, v125
	s_nop 0
	s_mov_b32 s2, 0x18000
	v_add3_u32 v110, v230, v136, s2
	v_add_u32_e32 v241, s2, v240
	v_rsq_f32_e32 v0, v0
	s_nop 0
	v_lshlrev_b32_e32 v102, 16, v122
	v_and_b32_e32 v103, 0xffff0000, v122
	v_lshlrev_b32_e32 v104, 16, v123
	v_and_b32_e32 v105, 0xffff0000, v123
	v_lshlrev_b32_e32 v106, 16, v124
	v_pk_mul_f32 v[98:99], v[98:99], v[0:1] op_sel_hi:[1,0]
	v_pk_mul_f32 v[100:101], v[100:101], v[0:1] op_sel_hi:[1,0]
	v_pk_mul_f32 v[94:95], v[94:95], v[0:1] op_sel_hi:[1,0]
	v_pk_mul_f32 v[96:97], v[96:97], v[0:1] op_sel_hi:[1,0]
	v_pk_fma_f32 v[100:101], v[84:85], v[100:101], v[104:105]
	v_pk_fma_f32 v[98:99], v[82:83], v[98:99], v[102:103]
	v_pk_fma_f32 v[104:105], v[78:79], v[94:95], v[106:107]
	v_cvt_pk_bf16_f32 v94, v98, v99
	v_cvt_pk_bf16_f32 v95, v100, v101
	v_pk_fma_f32 v[102:103], v[80:81], v[96:97], v[108:109]
	v_cvt_pk_bf16_f32 v96, v104, v105
	v_pk_mul_f32 v[108:109], v[202:203], v[104:105]
	v_cvt_pk_bf16_f32 v97, v102, v103
	global_store_dwordx4 v241, v[94:97], s[24:25]
	v_pk_mul_f32 v[106:107], v[198:199], v[102:103]
	v_pk_mul_f32 v[90:91], v[90:91], v[0:1] op_sel_hi:[1,0]
	v_pk_mul_f32 v[94:95], v[204:205], v[98:99]
	v_pk_mul_f32 v[96:97], v[200:201], v[100:101]
	v_cvt_pk_bf16_f32 v94, v94, v95
	v_pk_mul_f32 v[92:93], v[92:93], v[0:1] op_sel_hi:[1,0]
	v_cvt_pk_bf16_f32 v95, v96, v97
	v_cvt_pk_bf16_f32 v96, v108, v109
	v_cvt_pk_bf16_f32 v97, v106, v107
	global_store_dwordx4 v110, v[94:97], s[26:27]
	v_pk_mul_f32 v[86:87], v[86:87], v[0:1] op_sel_hi:[1,0]
	v_pk_mul_f32 v[88:89], v[88:89], v[0:1] op_sel_hi:[1,0]
	v_mul_f32_e32 v94, v99, v99
	v_mul_f32_e32 v95, v101, v101
	v_fmac_f32_e32 v94, v98, v98
	v_fmac_f32_e32 v95, v100, v100
	v_add_f32_e32 v94, v94, v95
	v_mul_f32_e32 v95, v105, v105
	v_fmac_f32_e32 v95, v104, v104
	v_add_f32_e32 v94, v95, v94
	v_mul_f32_e32 v95, v103, v103
	v_fmac_f32_e32 v95, v102, v102
	v_add_f32_e32 v102, v95, v94
	v_lshlrev_b32_e32 v94, 16, v118
	v_and_b32_e32 v95, 0xffff0000, v118
	v_lshlrev_b32_e32 v96, 16, v119
	v_and_b32_e32 v97, 0xffff0000, v119
	v_lshlrev_b32_e32 v98, 16, v120
	v_and_b32_e32 v99, 0xffff0000, v120
	v_lshlrev_b32_e32 v100, 16, v121
	v_and_b32_e32 v101, 0xffff0000, v121
	v_pk_fma_f32 v[92:93], v[92:93], v[76:77], v[96:97]
	v_pk_fma_f32 v[90:91], v[90:91], v[74:75], v[94:95]
	v_pk_fma_f32 v[94:95], v[88:89], v[72:73], v[100:101]
	v_pk_fma_f32 v[96:97], v[86:87], v[70:71], v[98:99]
	v_cvt_pk_bf16_f32 v86, v90, v91
	v_cvt_pk_bf16_f32 v87, v92, v93
	v_mul_f32_e32 v0, v95, v95
	v_cvt_pk_bf16_f32 v88, v96, v97
	v_cvt_pk_bf16_f32 v89, v94, v95
	global_store_dwordx4 v241, v[86:89], s[24:25] offset:1024
	v_fmac_f32_e32 v0, v94, v94
	v_pk_mul_f32 v[98:99], v[196:197], v[92:93]
	v_mul_f32_e32 v87, v91, v91
	v_mul_f32_e32 v88, v93, v93
	v_mul_f32_e32 v86, v97, v97
	v_fmac_f32_e32 v87, v90, v90
	v_fmac_f32_e32 v88, v92, v92
	v_fmac_f32_e32 v86, v96, v96
	v_add_f32_e32 v87, v87, v88
	v_add_f32_e32 v86, v86, v87
	v_add_f32_e32 v0, v0, v86
	v_add_f32_e32 v0, v102, v0
	ds_bpermute_b32 v89, v229, v0
	v_pk_mul_f32 v[86:87], v[174:175], v[90:91]
	v_pk_mul_f32 v[90:91], v[194:195], v[96:97]
	v_cvt_pk_bf16_f32 v88, v86, v87
	v_pk_mul_f32 v[92:93], v[176:177], v[94:95]
	s_waitcnt lgkmcnt(0)
	v_add_f32_e32 v0, v0, v89
	ds_bpermute_b32 v86, v228, v0
	v_cvt_pk_bf16_f32 v89, v98, v99
	v_cvt_pk_bf16_f32 v90, v90, v91
	v_cvt_pk_bf16_f32 v91, v92, v93
	global_store_dwordx4 v110, v[88:91], s[26:27] offset:256
	s_and_saveexec_b64 s[2:3], s[8:9]
	s_cbranch_execz .LBB0_1095
	s_waitcnt lgkmcnt(0)
	v_add_f32_e32 v0, v0, v86
	v_mul_f32_e32 v0, 0x4b800000, v0
	v_trunc_f32_e32 v0, v0
	v_mul_f32_e32 v86, 0x2f800000, v0
	v_floor_f32_e32 v87, v86
	v_fmac_f32_e32 v0, 0xcf800000, v87
	v_cvt_u32_f32_e32 v86, v0
	v_cvt_u32_f32_e32 v87, v87
	global_atomic_add_x2 v[134:135], v[86:87], off offset:384
; __device__ __forceinline__ unsigned cvt_pk_bf16(float lo, float hi) { unsigned r; asm volatile("v_cvt_pk_bf16_f32 %0, %1, %2" : "=v"(r) : "v"(lo), "v"(hi)); return r; }
; #define PG8_GPTR(p) ((__attribute__((address_space(1))) char*)(p))
;     __device__ __forceinline__ void operator()(const f32x4 (&acc)[2][2][4][2], const Unit& u, int wr, int wc, int fr, int fq) const {
;     ...
;                     bv[mm][bj] = *(gl_u32x4*)(PG8_GCPTR(base) + (unsigned)((u.pm * BM + ai * HALF + wr * 64 + (mp + mm) * 16 + fr) * DM + col0 + bj * HALF) * 2u);
; #pragma unroll
;             for (int mm = 0; mm < 2; ++mm) {
;                 const int m = mp + mm;
;                 const int row = u.pm * BM + ai * HALF + wr * 64 + m * 16 + fr; float q = 0.f;
; #pragma unroll
;                 for (int bj = 0; bj < 2; ++bj) {
;                     const unsigned offb = (unsigned)(row * DM + col0 + bj * HALF) * 2u;
;                     const u32x4 bw = bv[mm][bj];
;                     const f32x4 b0 = (f32x4){__uint_as_float(bw.x << 16), __uint_as_float(bw.x & 0xffff0000u), __uint_as_float(bw.y << 16), __uint_as_float(bw.y & 0xffff0000u)};
;                     const f32x4 b1 = (f32x4){__uint_as_float(bw.z << 16), __uint_as_float(bw.z & 0xffff0000u), __uint_as_float(bw.w << 16), __uint_as_float(bw.w & 0xffff0000u)};
;                     f32x4 a0 = acc[ai][bj][m][0], a1 = acc[ai][bj][m][1]; if constexpr (GN) { a0 *= rc[ai * 4 + m]; a1 *= rc[ai * 4 + m]; }
;                     const f32x4 o0 = b0 + g[bj][0] * a0, o1 = b1 + g[bj][1] * a1;
;                     u32x4 wo; wo.x = cvt_pk_bf16(o0[0], o0[1]); wo.y = cvt_pk_bf16(o0[2], o0[3]); wo.z = cvt_pk_bf16(o1[0], o1[1]); wo.w = cvt_pk_bf16(o1[2], o1[3]);
;                     *(gs_u32x4*)(PG8_GPTR(out) + offb) = wo;
;                     if (xg) {
;                         const f32x4 h0 = o0 * cf[bj][0], h1 = o1 * cf[bj][1];
;                         u32x4 w; w.x = cvt_pk_bf16(h0[0], h0[1]); w.y = cvt_pk_bf16(h0[2], h0[3]); w.z = cvt_pk_bf16(h1[0], h1[1]); w.w = cvt_pk_bf16(h1[2], h1[3]);
;                         *(gs_u32x4*)(PG8_GPTR(xg) + offb) = w;
;                         q += (o0[0] * o0[0] + o0[1] * o0[1]) + (o0[2] * o0[2] + o0[3] * o0[3]) + (o1[0] * o1[0] + o1[1] * o1[1]) + (o1[2] * o1[2] + o1[3] * o1[3]);
;                     }
;                 }
;                 if (xg) ssq_put(ssq, row, q, fr, fq);
.LBB0_1095:
	s_or_b64 exec, exec, s[2:3]
	v_ffbh_u32_e32 v0, v211
	v_min_u32_e32 v0, 32, v0
	s_waitcnt lgkmcnt(0)
	v_lshlrev_b64 v[86:87], v0, v[210:211]
	v_min_u32_e32 v86, 1, v86
	v_or_b32_e32 v86, v87, v86
	v_cvt_f32_u32_e32 v86, v86
	v_sub_u32_e32 v0, 32, v0
	v_ldexp_f32 v0, v86, v0
	v_mul_f32_e32 v0, 0x33800000, v0
	v_fmamk_f32 v0, v0, 0x3b800000, v226
	s_mov_b32 s2, 0x40000
	v_add3_u32 v106, v232, v230, s2
	v_add_u32_e32 v241, s2, v240
	v_rsq_f32_e32 v0, v0
	s_nop 0
	v_add_u32_e32 v86, 0x40000, v240
	global_load_dwordx4 v[98:101], v86, s[22:23]
	global_load_dwordx4 v[94:97], v86, s[22:23] offset:1024
	v_add_u32_e32 v86, 0x48000, v240
	global_load_dwordx4 v[90:93], v86, s[22:23]
	s_nop 0
	global_load_dwordx4 v[86:89], v86, s[22:23] offset:1024
	v_pk_mul_f32 v[66:67], v[66:67], v[0:1] op_sel_hi:[1,0]
	v_pk_mul_f32 v[68:69], v[68:69], v[0:1] op_sel_hi:[1,0]
	v_pk_mul_f32 v[62:63], v[62:63], v[0:1] op_sel_hi:[1,0]
	v_pk_mul_f32 v[64:65], v[64:65], v[0:1] op_sel_hi:[1,0]
	v_pk_mul_f32 v[58:59], v[58:59], v[0:1] op_sel_hi:[1,0]
	v_pk_mul_f32 v[60:61], v[60:61], v[0:1] op_sel_hi:[1,0]
	v_pk_mul_f32 v[54:55], v[54:55], v[0:1] op_sel_hi:[1,0]
	v_pk_mul_f32 v[56:57], v[56:57], v[0:1] op_sel_hi:[1,0]
	s_waitcnt vmcnt(0)
	v_lshlrev_b32_e32 v102, 16, v98
	v_and_b32_e32 v103, 0xffff0000, v98
	v_lshlrev_b32_e32 v98, 16, v99
	v_and_b32_e32 v99, 0xffff0000, v99
	v_lshlrev_b32_e32 v104, 16, v100
	v_and_b32_e32 v105, 0xffff0000, v100
	v_lshlrev_b32_e32 v100, 16, v101
	v_and_b32_e32 v101, 0xffff0000, v101
	v_pk_fma_f32 v[68:69], v[84:85], v[68:69], v[98:99]
	v_pk_fma_f32 v[66:67], v[82:83], v[66:67], v[102:103]
	v_pk_fma_f32 v[98:99], v[80:81], v[64:65], v[100:101]
	v_pk_fma_f32 v[100:101], v[78:79], v[62:63], v[104:105]
	v_cvt_pk_bf16_f32 v62, v66, v67
	v_cvt_pk_bf16_f32 v63, v68, v69
	v_pk_mul_f32 v[102:103], v[198:199], v[98:99]
	v_cvt_pk_bf16_f32 v64, v100, v101
	v_cvt_pk_bf16_f32 v65, v98, v99
	global_store_dwordx4 v241, v[62:65], s[24:25]
	v_pk_mul_f32 v[104:105], v[202:203], v[100:101]
	s_nop 0
	v_pk_mul_f32 v[62:63], v[204:205], v[66:67]
	v_pk_mul_f32 v[64:65], v[200:201], v[68:69]
	v_cvt_pk_bf16_f32 v62, v62, v63
	s_nop 0
	v_cvt_pk_bf16_f32 v63, v64, v65
	v_cvt_pk_bf16_f32 v64, v104, v105
	v_cvt_pk_bf16_f32 v65, v102, v103
	global_store_dwordx4 v106, v[62:65], s[26:27]
	s_nop 1
	v_mul_f32_e32 v62, v67, v67
	v_mul_f32_e32 v63, v69, v69
	v_fmac_f32_e32 v62, v66, v66
	v_fmac_f32_e32 v63, v68, v68
	v_add_f32_e32 v62, v62, v63
	v_mul_f32_e32 v63, v101, v101
	v_fmac_f32_e32 v63, v100, v100
	v_add_f32_e32 v62, v63, v62
	v_mul_f32_e32 v63, v99, v99
	v_fmac_f32_e32 v63, v98, v98
	v_add_f32_e32 v98, v63, v62
	v_lshlrev_b32_e32 v62, 16, v94
	v_and_b32_e32 v63, 0xffff0000, v94
	v_lshlrev_b32_e32 v64, 16, v95
	v_and_b32_e32 v65, 0xffff0000, v95
	v_lshlrev_b32_e32 v66, 16, v96
	v_and_b32_e32 v67, 0xffff0000, v96
	v_lshlrev_b32_e32 v68, 16, v97
	v_and_b32_e32 v69, 0xffff0000, v97
	v_pk_fma_f32 v[60:61], v[60:61], v[76:77], v[64:65]
	v_pk_fma_f32 v[58:59], v[58:59], v[74:75], v[62:63]
	v_pk_fma_f32 v[62:63], v[56:57], v[72:73], v[68:69]
	v_pk_fma_f32 v[64:65], v[54:55], v[70:71], v[66:67]
	v_cvt_pk_bf16_f32 v54, v58, v59
	v_cvt_pk_bf16_f32 v55, v60, v61
	v_pk_mul_f32 v[66:67], v[176:177], v[62:63]
	v_cvt_pk_bf16_f32 v56, v64, v65
	v_cvt_pk_bf16_f32 v57, v62, v63
	global_store_dwordx4 v241, v[54:57], s[24:25] offset:1024
	v_pk_mul_f32 v[68:69], v[194:195], v[64:65]
	v_mul_f32_e32 v0, v63, v63
	v_pk_mul_f32 v[56:57], v[196:197], v[60:61]
	v_pk_mul_f32 v[54:55], v[174:175], v[58:59]
	v_fmac_f32_e32 v0, v62, v62
	v_cvt_pk_bf16_f32 v54, v54, v55
	v_cvt_pk_bf16_f32 v55, v56, v57
	v_cvt_pk_bf16_f32 v56, v68, v69
	v_cvt_pk_bf16_f32 v57, v66, v67
	global_store_dwordx4 v106, v[54:57], s[26:27] offset:256
	s_nop 1
	v_mul_f32_e32 v55, v59, v59
	v_mul_f32_e32 v56, v61, v61
	v_mul_f32_e32 v54, v65, v65
	v_fmac_f32_e32 v55, v58, v58
	v_fmac_f32_e32 v56, v60, v60
	v_fmac_f32_e32 v54, v64, v64
	v_add_f32_e32 v55, v55, v56
	v_add_f32_e32 v54, v54, v55
	v_add_f32_e32 v0, v0, v54
	v_add_f32_e32 v0, v98, v0
	ds_bpermute_b32 v54, v229, v0
	s_waitcnt lgkmcnt(0)
	v_add_f32_e32 v0, v0, v54
	ds_bpermute_b32 v54, v228, v0
	s_and_saveexec_b64 s[2:3], s[8:9]
	s_cbranch_execz .LBB0_1097
	s_waitcnt lgkmcnt(0)
	v_add_f32_e32 v0, v0, v54
	v_mul_f32_e32 v0, 0x4b800000, v0
	v_trunc_f32_e32 v0, v0
	v_mul_f32_e32 v54, 0x2f800000, v0
	v_floor_f32_e32 v55, v54
	v_fmac_f32_e32 v0, 0xcf800000, v55
	v_cvt_u32_f32_e32 v54, v0
	v_cvt_u32_f32_e32 v55, v55
	global_atomic_add_x2 v[134:135], v[54:55], off offset:1024
;     __device__ __forceinline__ void operator()(const f32x4 (&acc)[2][2][4][2], const Unit& u, int wr, int wc, int fr, int fq) const {
;     ...
;         if constexpr (GN) { ssq_t sc_[8];
; #pragma unroll
;             for (int i = 0; i < 8; ++i) sc_[i] = gsc[u.pm * BM + wr * 64 + fr + (i >> 2) * HALF + (i & 3) * 16];
; #pragma unroll
;             for (int i = 0; i < 8; ++i) rc[i] = 1.0f / sqrtf(ssq_val(sc_[i]) * (1.0f / 256.0f) + EPS); }
;         const int col0 = u.pn * BM + wc * 32 + 8 * fq; const int b = (u.pm * BM) >> 12;
;         const float* gp = gate + (size_t)b * NMOD + col0; const float* sp = sc + (size_t)b * NMOD + col0;
;         f32x4 g[2][2], cf[2][2];
; #pragma unroll
;         for (int bj = 0; bj < 2; ++bj) {
;             g[bj][0] = *(const f32x4*)(gp + bj * HALF); g[bj][1] = *(const f32x4*)(gp + bj * HALF + 4);
;             const f32x4 n0 = *(const f32x4*)(nw + col0 + bj * HALF), n1 = *(const f32x4*)(nw + col0 + bj * HALF + 4);
;             const f32x4 c0 = *(const f32x4*)(sp + bj * HALF), c1 = *(const f32x4*)(sp + bj * HALF + 4);
;             cf[bj][0] = n0 * (c0 + 1.0f); cf[bj][1] = n1 * (c1 + 1.0f);
;         }
; #pragma unroll
;         for (int ai = 0; ai < 2; ++ai)
; #pragma unroll
;         for (int mp = 0; mp < 4; mp += 2) {
;             u32x4 bv[2][2];
; #pragma unroll
;             for (int mm = 0; mm < 2; ++mm)
; #pragma unroll
;                 for (int bj = 0; bj < 2; ++bj)
;                     bv[mm][bj] = *(gl_u32x4*)(PG8_GCPTR(base) + (unsigned)((u.pm * BM + ai * HALF + wr * 64 + (mp + mm) * 16 + fr) * DM + col0 + bj * HALF) * 2u);
; #pragma unroll
;             for (int mm = 0; mm < 2; ++mm) {
;                 const int m = mp + mm;
;                 const int row = u.pm * BM + ai * HALF + wr * 64 + m * 16 + fr; float q = 0.f;
; #pragma unroll
;                 for (int bj = 0; bj < 2; ++bj) {
;                     const unsigned offb = (unsigned)(row * DM + col0 + bj * HALF) * 2u;
;                     const u32x4 bw = bv[mm][bj];
;                     const f32x4 b0 = (f32x4){__uint_as_float(bw.x << 16), __uint_as_float(bw.x & 0xffff0000u), __uint_as_float(bw.y << 16), __uint_as_float(bw.y & 0xffff0000u)};
;                     const f32x4 b1 = (f32x4){__uint_as_float(bw.z << 16), __uint_as_float(bw.z & 0xffff0000u), __uint_as_float(bw.w << 16), __uint_as_float(bw.w & 0xffff0000u)};
.LBB0_1097:
	s_or_b64 exec, exec, s[2:3]
	v_ffbh_u32_e32 v0, v209
	v_min_u32_e32 v0, 32, v0
	s_waitcnt lgkmcnt(0)
	v_lshlrev_b64 v[54:55], v0, v[208:209]
	v_min_u32_e32 v54, 1, v54
	v_or_b32_e32 v54, v55, v54
	v_cvt_f32_u32_e32 v54, v54
	v_sub_u32_e32 v0, 32, v0
	v_and_b32_e32 v59, 0xffff0000, v92
	v_lshlrev_b32_e32 v60, 16, v93
	v_ldexp_f32 v0, v54, v0
	v_mul_f32_e32 v0, 0x33800000, v0
	v_fmamk_f32 v0, v0, 0x3b800000, v226
	v_and_b32_e32 v61, 0xffff0000, v93
	s_nop 0
	s_mov_b32 s2, 0x48000
	v_add3_u32 v62, v136, v230, s2
	v_add_u32_e32 v241, s2, v240
	v_rsq_f32_e32 v0, v0
	s_nop 0
	v_lshlrev_b32_e32 v54, 16, v90
	v_and_b32_e32 v55, 0xffff0000, v90
	v_lshlrev_b32_e32 v56, 16, v91
	v_and_b32_e32 v57, 0xffff0000, v91
	v_lshlrev_b32_e32 v58, 16, v92
	v_pk_mul_f32 v[50:51], v[50:51], v[0:1] op_sel_hi:[1,0]
	v_pk_mul_f32 v[52:53], v[52:53], v[0:1] op_sel_hi:[1,0]
	v_pk_mul_f32 v[46:47], v[46:47], v[0:1] op_sel_hi:[1,0]
	v_pk_mul_f32 v[48:49], v[48:49], v[0:1] op_sel_hi:[1,0]
	v_pk_fma_f32 v[52:53], v[84:85], v[52:53], v[56:57]
	v_pk_fma_f32 v[50:51], v[82:83], v[50:51], v[54:55]
	v_pk_fma_f32 v[56:57], v[78:79], v[46:47], v[58:59]
	v_cvt_pk_bf16_f32 v46, v50, v51
	v_cvt_pk_bf16_f32 v47, v52, v53
	v_pk_fma_f32 v[54:55], v[80:81], v[48:49], v[60:61]
	v_cvt_pk_bf16_f32 v48, v56, v57
	v_pk_mul_f32 v[60:61], v[202:203], v[56:57]
	v_cvt_pk_bf16_f32 v49, v54, v55
	global_store_dwordx4 v241, v[46:49], s[24:25]
	v_pk_mul_f32 v[58:59], v[198:199], v[54:55]
	v_pk_mul_f32 v[42:43], v[42:43], v[0:1] op_sel_hi:[1,0]
	v_pk_mul_f32 v[46:47], v[204:205], v[50:51]
	v_pk_mul_f32 v[48:49], v[200:201], v[52:53]
	v_cvt_pk_bf16_f32 v46, v46, v47
	v_pk_mul_f32 v[44:45], v[44:45], v[0:1] op_sel_hi:[1,0]
	v_cvt_pk_bf16_f32 v47, v48, v49
	v_cvt_pk_bf16_f32 v48, v60, v61
	v_cvt_pk_bf16_f32 v49, v58, v59
	global_store_dwordx4 v62, v[46:49], s[26:27]
	v_pk_mul_f32 v[38:39], v[38:39], v[0:1] op_sel_hi:[1,0]
	v_pk_mul_f32 v[40:41], v[40:41], v[0:1] op_sel_hi:[1,0]
	v_mul_f32_e32 v46, v51, v51
	v_mul_f32_e32 v47, v53, v53
	v_fmac_f32_e32 v46, v50, v50
	v_fmac_f32_e32 v47, v52, v52
	v_add_f32_e32 v46, v46, v47
	v_mul_f32_e32 v47, v57, v57
	v_fmac_f32_e32 v47, v56, v56
	v_add_f32_e32 v46, v47, v46
	v_mul_f32_e32 v47, v55, v55
	v_fmac_f32_e32 v47, v54, v54
	v_add_f32_e32 v54, v47, v46
	v_lshlrev_b32_e32 v46, 16, v86
	v_and_b32_e32 v47, 0xffff0000, v86
	v_lshlrev_b32_e32 v48, 16, v87
	v_and_b32_e32 v49, 0xffff0000, v87
	v_lshlrev_b32_e32 v50, 16, v88
	v_and_b32_e32 v51, 0xffff0000, v88
	v_lshlrev_b32_e32 v52, 16, v89
	v_and_b32_e32 v53, 0xffff0000, v89
	v_pk_fma_f32 v[44:45], v[76:77], v[44:45], v[48:49]
	v_pk_fma_f32 v[42:43], v[74:75], v[42:43], v[46:47]
	v_pk_fma_f32 v[46:47], v[40:41], v[72:73], v[52:53]
	v_pk_fma_f32 v[48:49], v[38:39], v[70:71], v[50:51]
	v_cvt_pk_bf16_f32 v38, v42, v43
	v_cvt_pk_bf16_f32 v39, v44, v45
	v_mul_f32_e32 v0, v47, v47
	v_cvt_pk_bf16_f32 v40, v48, v49
	v_cvt_pk_bf16_f32 v41, v46, v47
	global_store_dwordx4 v241, v[38:41], s[24:25] offset:1024
	v_fmac_f32_e32 v0, v46, v46
	v_pk_mul_f32 v[50:51], v[196:197], v[44:45]
	v_mul_f32_e32 v39, v43, v43
	v_mul_f32_e32 v40, v45, v45
	v_mul_f32_e32 v38, v49, v49
	v_fmac_f32_e32 v39, v42, v42
	v_fmac_f32_e32 v40, v44, v44
	v_fmac_f32_e32 v38, v48, v48
	v_add_f32_e32 v39, v39, v40
	v_add_f32_e32 v38, v38, v39
	v_add_f32_e32 v0, v0, v38
	v_add_f32_e32 v0, v54, v0
	ds_bpermute_b32 v41, v229, v0
	v_pk_mul_f32 v[38:39], v[174:175], v[42:43]
	v_pk_mul_f32 v[42:43], v[194:195], v[48:49]
	v_cvt_pk_bf16_f32 v40, v38, v39
	v_pk_mul_f32 v[44:45], v[176:177], v[46:47]
	s_waitcnt lgkmcnt(0)
	v_add_f32_e32 v0, v0, v41
	ds_bpermute_b32 v38, v228, v0
	v_cvt_pk_bf16_f32 v41, v50, v51
	v_cvt_pk_bf16_f32 v42, v42, v43
	v_cvt_pk_bf16_f32 v43, v44, v45
	global_store_dwordx4 v62, v[40:43], s[26:27] offset:256
	s_and_saveexec_b64 s[2:3], s[8:9]
	s_cbranch_execz .LBB0_1099
	s_waitcnt lgkmcnt(0)
	v_add_f32_e32 v0, v0, v38
	v_mul_f32_e32 v0, 0x4b800000, v0
	v_trunc_f32_e32 v0, v0
	v_mul_f32_e32 v38, 0x2f800000, v0
	v_floor_f32_e32 v39, v38
	v_fmac_f32_e32 v0, 0xcf800000, v39
	v_cvt_u32_f32_e32 v38, v0
	v_cvt_u32_f32_e32 v39, v39
	global_atomic_add_x2 v[134:135], v[38:39], off offset:1152
.LBB0_1099:
	s_or_b64 exec, exec, s[2:3]
	v_ffbh_u32_e32 v0, v207
	v_min_u32_e32 v0, 32, v0
	s_waitcnt lgkmcnt(0)
	v_lshlrev_b64 v[38:39], v0, v[206:207]
	v_min_u32_e32 v38, 1, v38
	v_or_b32_e32 v38, v39, v38
	v_cvt_f32_u32_e32 v38, v38
	v_sub_u32_e32 v0, 32, v0
	v_ldexp_f32 v0, v38, v0
	v_mul_f32_e32 v0, 0x33800000, v0
	v_fmamk_f32 v0, v0, 0x3b800000, v226
	s_mov_b32 s2, 0x50000
	v_add3_u32 v58, v136, v230, s2
	v_add_u32_e32 v241, s2, v240
	v_rsq_f32_e32 v0, v0
	s_nop 0
	v_add_u32_e32 v38, 0x50000, v240
	global_load_dwordx4 v[50:53], v38, s[22:23]
	global_load_dwordx4 v[46:49], v38, s[22:23] offset:1024
	v_add_u32_e32 v38, 0x58000, v240
	global_load_dwordx4 v[42:45], v38, s[22:23]
	s_nop 0
	global_load_dwordx4 v[38:41], v38, s[22:23] offset:1024
	v_pk_mul_f32 v[34:35], v[34:35], v[0:1] op_sel_hi:[1,0]
	v_pk_mul_f32 v[36:37], v[36:37], v[0:1] op_sel_hi:[1,0]
	v_pk_mul_f32 v[30:31], v[30:31], v[0:1] op_sel_hi:[1,0]
	v_pk_mul_f32 v[32:33], v[32:33], v[0:1] op_sel_hi:[1,0]
	v_pk_mul_f32 v[26:27], v[26:27], v[0:1] op_sel_hi:[1,0]
	v_pk_mul_f32 v[28:29], v[28:29], v[0:1] op_sel_hi:[1,0]
	v_pk_mul_f32 v[22:23], v[22:23], v[0:1] op_sel_hi:[1,0]
	v_pk_mul_f32 v[24:25], v[24:25], v[0:1] op_sel_hi:[1,0]
	s_waitcnt vmcnt(0)
; __device__ __forceinline__ unsigned cvt_pk_bf16(float lo, float hi) { unsigned r; asm volatile("v_cvt_pk_bf16_f32 %0, %1, %2" : "=v"(r) : "v"(lo), "v"(hi)); return r; }
; #define PG8_GPTR(p) ((__attribute__((address_space(1))) char*)(p))
;     __device__ __forceinline__ void operator()(const f32x4 (&acc)[2][2][4][2], const Unit& u, int wr, int wc, int fr, int fq) const {
;     ...
;                     bv[mm][bj] = *(gl_u32x4*)(PG8_GCPTR(base) + (unsigned)((u.pm * BM + ai * HALF + wr * 64 + (mp + mm) * 16 + fr) * DM + col0 + bj * HALF) * 2u);
; #pragma unroll
;             for (int mm = 0; mm < 2; ++mm) {
;                 const int m = mp + mm;
;                 const int row = u.pm * BM + ai * HALF + wr * 64 + m * 16 + fr; float q = 0.f;
; #pragma unroll
;                 for (int bj = 0; bj < 2; ++bj) {
;                     const unsigned offb = (unsigned)(row * DM + col0 + bj * HALF) * 2u;
;                     const u32x4 bw = bv[mm][bj];
;                     const f32x4 b0 = (f32x4){__uint_as_float(bw.x << 16), __uint_as_float(bw.x & 0xffff0000u), __uint_as_float(bw.y << 16), __uint_as_float(bw.y & 0xffff0000u)};
;                     const f32x4 b1 = (f32x4){__uint_as_float(bw.z << 16), __uint_as_float(bw.z & 0xffff0000u), __uint_as_float(bw.w << 16), __uint_as_float(bw.w & 0xffff0000u)};
;                     f32x4 a0 = acc[ai][bj][m][0], a1 = acc[ai][bj][m][1]; if constexpr (GN) { a0 *= rc[ai * 4 + m]; a1 *= rc[ai * 4 + m]; }
;                     const f32x4 o0 = b0 + g[bj][0] * a0, o1 = b1 + g[bj][1] * a1;
;                     u32x4 wo; wo.x = cvt_pk_bf16(o0[0], o0[1]); wo.y = cvt_pk_bf16(o0[2], o0[3]); wo.z = cvt_pk_bf16(o1[0], o1[1]); wo.w = cvt_pk_bf16(o1[2], o1[3]);
;                     *(gs_u32x4*)(PG8_GPTR(out) + offb) = wo;
;                     if (xg) {
;                         const f32x4 h0 = o0 * cf[bj][0], h1 = o1 * cf[bj][1];
;                         u32x4 w; w.x = cvt_pk_bf16(h0[0], h0[1]); w.y = cvt_pk_bf16(h0[2], h0[3]); w.z = cvt_pk_bf16(h1[0], h1[1]); w.w = cvt_pk_bf16(h1[2], h1[3]);
;                         *(gs_u32x4*)(PG8_GPTR(xg) + offb) = w;
;                         q += (o0[0] * o0[0] + o0[1] * o0[1]) + (o0[2] * o0[2] + o0[3] * o0[3]) + (o1[0] * o1[0] + o1[1] * o1[1]) + (o1[2] * o1[2] + o1[3] * o1[3]);
;                     }
;                 }
;                 if (xg) ssq_put(ssq, row, q, fr, fq);
	v_lshlrev_b32_e32 v54, 16, v50
	v_and_b32_e32 v55, 0xffff0000, v50
	v_lshlrev_b32_e32 v50, 16, v51
	v_and_b32_e32 v51, 0xffff0000, v51
	v_lshlrev_b32_e32 v56, 16, v52
	v_and_b32_e32 v57, 0xffff0000, v52
	v_lshlrev_b32_e32 v52, 16, v53
	v_and_b32_e32 v53, 0xffff0000, v53
	v_pk_fma_f32 v[36:37], v[84:85], v[36:37], v[50:51]
	v_pk_fma_f32 v[34:35], v[82:83], v[34:35], v[54:55]
	v_pk_fma_f32 v[50:51], v[80:81], v[32:33], v[52:53]
	v_pk_fma_f32 v[52:53], v[78:79], v[30:31], v[56:57]
	v_cvt_pk_bf16_f32 v30, v34, v35
	v_cvt_pk_bf16_f32 v31, v36, v37
	v_pk_mul_f32 v[54:55], v[198:199], v[50:51]
	v_cvt_pk_bf16_f32 v32, v52, v53
	v_cvt_pk_bf16_f32 v33, v50, v51
	global_store_dwordx4 v241, v[30:33], s[24:25]
	v_pk_mul_f32 v[56:57], v[202:203], v[52:53]
	s_nop 0
	v_pk_mul_f32 v[30:31], v[204:205], v[34:35]
	v_pk_mul_f32 v[32:33], v[200:201], v[36:37]
	v_cvt_pk_bf16_f32 v30, v30, v31
	s_nop 0
	v_cvt_pk_bf16_f32 v31, v32, v33
	v_cvt_pk_bf16_f32 v32, v56, v57
	v_cvt_pk_bf16_f32 v33, v54, v55
	global_store_dwordx4 v58, v[30:33], s[26:27]
	s_nop 1
	v_mul_f32_e32 v30, v35, v35
	v_mul_f32_e32 v31, v37, v37
	v_fmac_f32_e32 v30, v34, v34
	v_fmac_f32_e32 v31, v36, v36
	v_add_f32_e32 v30, v30, v31
	v_mul_f32_e32 v31, v53, v53
	v_fmac_f32_e32 v31, v52, v52
	v_add_f32_e32 v30, v31, v30
	v_mul_f32_e32 v31, v51, v51
	v_fmac_f32_e32 v31, v50, v50
	v_add_f32_e32 v50, v31, v30
	v_lshlrev_b32_e32 v30, 16, v46
	v_and_b32_e32 v31, 0xffff0000, v46
	v_lshlrev_b32_e32 v32, 16, v47
	v_and_b32_e32 v33, 0xffff0000, v47
	v_lshlrev_b32_e32 v34, 16, v48
	v_and_b32_e32 v35, 0xffff0000, v48
	v_lshlrev_b32_e32 v36, 16, v49
	v_and_b32_e32 v37, 0xffff0000, v49
	v_pk_fma_f32 v[28:29], v[76:77], v[28:29], v[32:33]
	v_pk_fma_f32 v[26:27], v[74:75], v[26:27], v[30:31]
	v_pk_fma_f32 v[30:31], v[72:73], v[24:25], v[36:37]
	v_pk_fma_f32 v[32:33], v[70:71], v[22:23], v[34:35]
	v_cvt_pk_bf16_f32 v22, v26, v27
	v_cvt_pk_bf16_f32 v23, v28, v29
	v_pk_mul_f32 v[34:35], v[176:177], v[30:31]
	v_cvt_pk_bf16_f32 v24, v32, v33
	v_cvt_pk_bf16_f32 v25, v30, v31
	global_store_dwordx4 v241, v[22:25], s[24:25] offset:1024
	v_pk_mul_f32 v[36:37], v[194:195], v[32:33]
	v_mul_f32_e32 v0, v31, v31
	v_pk_mul_f32 v[24:25], v[196:197], v[28:29]
	v_pk_mul_f32 v[22:23], v[174:175], v[26:27]
	v_fmac_f32_e32 v0, v30, v30
	v_cvt_pk_bf16_f32 v22, v22, v23
	v_cvt_pk_bf16_f32 v23, v24, v25
	v_cvt_pk_bf16_f32 v24, v36, v37
	v_cvt_pk_bf16_f32 v25, v34, v35
	global_store_dwordx4 v58, v[22:25], s[26:27] offset:256
	s_nop 1
	v_mul_f32_e32 v23, v27, v27
	v_mul_f32_e32 v24, v29, v29
	v_mul_f32_e32 v22, v33, v33
	v_fmac_f32_e32 v23, v26, v26
	v_fmac_f32_e32 v24, v28, v28
	v_fmac_f32_e32 v22, v32, v32
	v_add_f32_e32 v23, v23, v24
	v_add_f32_e32 v22, v22, v23
	v_add_f32_e32 v0, v0, v22
	v_add_f32_e32 v0, v50, v0
	ds_bpermute_b32 v22, v229, v0
	s_waitcnt lgkmcnt(0)
	v_add_f32_e32 v0, v0, v22
	ds_bpermute_b32 v22, v228, v0
	s_and_saveexec_b64 s[2:3], s[8:9]
	s_cbranch_execz .LBB0_1101
	s_waitcnt lgkmcnt(0)
	v_add_f32_e32 v0, v0, v22
	v_mul_f32_e32 v0, 0x4b800000, v0
	v_trunc_f32_e32 v0, v0
	v_mul_f32_e32 v22, 0x2f800000, v0
	v_floor_f32_e32 v23, v22
	v_fmac_f32_e32 v0, 0xcf800000, v23
	v_cvt_u32_f32_e32 v22, v0
	v_cvt_u32_f32_e32 v23, v23
	global_atomic_add_x2 v[134:135], v[22:23], off offset:1280
;     __device__ __forceinline__ void operator()(const f32x4 (&acc)[2][2][4][2], const Unit& u, int wr, int wc, int fr, int fq) const {
;     ...
;         if constexpr (GN) { ssq_t sc_[8];
; #pragma unroll
;             for (int i = 0; i < 8; ++i) sc_[i] = gsc[u.pm * BM + wr * 64 + fr + (i >> 2) * HALF + (i & 3) * 16];
; #pragma unroll
;             for (int i = 0; i < 8; ++i) rc[i] = 1.0f / sqrtf(ssq_val(sc_[i]) * (1.0f / 256.0f) + EPS); }
;         const int col0 = u.pn * BM + wc * 32 + 8 * fq; const int b = (u.pm * BM) >> 12;
;         const float* gp = gate + (size_t)b * NMOD + col0; const float* sp = sc + (size_t)b * NMOD + col0;
;         f32x4 g[2][2], cf[2][2];
; #pragma unroll
;         for (int bj = 0; bj < 2; ++bj) {
;             g[bj][0] = *(const f32x4*)(gp + bj * HALF); g[bj][1] = *(const f32x4*)(gp + bj * HALF + 4);
;             const f32x4 n0 = *(const f32x4*)(nw + col0 + bj * HALF), n1 = *(const f32x4*)(nw + col0 + bj * HALF + 4);
;             const f32x4 c0 = *(const f32x4*)(sp + bj * HALF), c1 = *(const f32x4*)(sp + bj * HALF + 4);
;             cf[bj][0] = n0 * (c0 + 1.0f); cf[bj][1] = n1 * (c1 + 1.0f);
;         }
; #pragma unroll
;         for (int ai = 0; ai < 2; ++ai)
; #pragma unroll
;         for (int mp = 0; mp < 4; mp += 2) {
;             u32x4 bv[2][2];
; #pragma unroll
;             for (int mm = 0; mm < 2; ++mm)
; #pragma unroll
;                 for (int bj = 0; bj < 2; ++bj)
;                     bv[mm][bj] = *(gl_u32x4*)(PG8_GCPTR(base) + (unsigned)((u.pm * BM + ai * HALF + wr * 64 + (mp + mm) * 16 + fr) * DM + col0 + bj * HALF) * 2u);
; #pragma unroll
;             for (int mm = 0; mm < 2; ++mm) {
;                 const int m = mp + mm;
;                 const int row = u.pm * BM + ai * HALF + wr * 64 + m * 16 + fr; float q = 0.f;
; #pragma unroll
;                 for (int bj = 0; bj < 2; ++bj) {
;                     const unsigned offb = (unsigned)(row * DM + col0 + bj * HALF) * 2u;
;                     const u32x4 bw = bv[mm][bj];
;                     const f32x4 b0 = (f32x4){__uint_as_float(bw.x << 16), __uint_as_float(bw.x & 0xffff0000u), __uint_as_float(bw.y << 16), __uint_as_float(bw.y & 0xffff0000u)};
;                     const f32x4 b1 = (f32x4){__uint_as_float(bw.z << 16), __uint_as_float(bw.z & 0xffff0000u), __uint_as_float(bw.w << 16), __uint_as_float(bw.w & 0xffff0000u)};
.LBB0_1101:
	s_or_b64 exec, exec, s[2:3]
	v_ffbh_u32_e32 v0, v3
	v_min_u32_e32 v0, 32, v0
	v_lshlrev_b64 v[2:3], v0, v[2:3]
	v_min_u32_e32 v2, 1, v2
	v_or_b32_e32 v2, v3, v2
	v_cvt_f32_u32_e32 v2, v2
	v_sub_u32_e32 v0, 32, v0
	v_and_b32_e32 v25, 0xffff0000, v44
	v_lshlrev_b32_e32 v26, 16, v45
	v_ldexp_f32 v0, v2, v0
	v_mul_f32_e32 v0, 0x33800000, v0
	v_fmamk_f32 v0, v0, 0x3b800000, v226
	v_and_b32_e32 v27, 0xffff0000, v45
	s_nop 0
	s_waitcnt lgkmcnt(0)
	s_mov_b32 s2, 0x58000
	v_add3_u32 v28, v136, v230, s2
	v_add_u32_e32 v241, s2, v240
	v_rsq_f32_e32 v0, v0
	s_nop 0
	v_lshlrev_b32_e32 v2, 16, v42
	v_and_b32_e32 v3, 0xffff0000, v42
	v_lshlrev_b32_e32 v22, 16, v43
	v_and_b32_e32 v23, 0xffff0000, v43
	v_lshlrev_b32_e32 v24, 16, v44
	v_pk_mul_f32 v[18:19], v[18:19], v[0:1] op_sel_hi:[1,0]
	v_pk_mul_f32 v[20:21], v[20:21], v[0:1] op_sel_hi:[1,0]
	v_pk_mul_f32 v[12:13], v[12:13], v[0:1] op_sel_hi:[1,0]
	v_pk_mul_f32 v[14:15], v[14:15], v[0:1] op_sel_hi:[1,0]
	v_pk_fma_f32 v[20:21], v[84:85], v[20:21], v[22:23]
	v_pk_fma_f32 v[2:3], v[82:83], v[18:19], v[2:3]
	v_pk_fma_f32 v[22:23], v[78:79], v[12:13], v[24:25]
	v_cvt_pk_bf16_f32 v12, v2, v3
	v_cvt_pk_bf16_f32 v13, v20, v21
	v_pk_fma_f32 v[18:19], v[80:81], v[14:15], v[26:27]
	v_cvt_pk_bf16_f32 v14, v22, v23
	v_pk_mul_f32 v[26:27], v[202:203], v[22:23]
	v_cvt_pk_bf16_f32 v15, v18, v19
	global_store_dwordx4 v241, v[12:15], s[24:25]
	v_pk_mul_f32 v[24:25], v[198:199], v[18:19]
	v_pk_mul_f32 v[8:9], v[8:9], v[0:1] op_sel_hi:[1,0]
	v_pk_mul_f32 v[12:13], v[204:205], v[2:3]
	v_mul_f32_e32 v3, v3, v3
	v_fmac_f32_e32 v3, v2, v2
	v_mul_f32_e32 v2, v21, v21
	v_fmac_f32_e32 v2, v20, v20
	v_add_f32_e32 v2, v3, v2
	v_mul_f32_e32 v3, v23, v23
	v_fmac_f32_e32 v3, v22, v22
	v_pk_mul_f32 v[14:15], v[200:201], v[20:21]
	v_add_f32_e32 v2, v3, v2
	v_mul_f32_e32 v3, v19, v19
	v_cvt_pk_bf16_f32 v12, v12, v13
	v_cvt_pk_bf16_f32 v13, v14, v15
	v_cvt_pk_bf16_f32 v14, v26, v27
	v_cvt_pk_bf16_f32 v15, v24, v25
	v_fmac_f32_e32 v3, v18, v18
	global_store_dwordx4 v28, v[12:15], s[26:27]
	v_add_f32_e32 v20, v3, v2
	v_lshlrev_b32_e32 v2, 16, v38
	v_and_b32_e32 v3, 0xffff0000, v38
	v_lshlrev_b32_e32 v12, 16, v39
	v_and_b32_e32 v13, 0xffff0000, v39
	v_lshlrev_b32_e32 v14, 16, v40
	v_and_b32_e32 v15, 0xffff0000, v40
	v_pk_mul_f32 v[10:11], v[10:11], v[0:1] op_sel_hi:[1,0]
	v_pk_mul_f32 v[4:5], v[4:5], v[0:1] op_sel_hi:[1,0]
	v_lshlrev_b32_e32 v18, 16, v41
	v_and_b32_e32 v19, 0xffff0000, v41
	v_pk_mul_f32 v[6:7], v[6:7], v[0:1] op_sel_hi:[1,0]
	v_pk_fma_f32 v[10:11], v[76:77], v[10:11], v[12:13]
	v_pk_fma_f32 v[8:9], v[74:75], v[8:9], v[2:3]
	v_pk_fma_f32 v[12:13], v[70:71], v[4:5], v[14:15]
	v_cvt_pk_bf16_f32 v2, v8, v9
	v_cvt_pk_bf16_f32 v3, v10, v11
	v_pk_fma_f32 v[6:7], v[72:73], v[6:7], v[18:19]
	v_cvt_pk_bf16_f32 v4, v12, v13
	v_pk_mul_f32 v[14:15], v[196:197], v[10:11]
	v_cvt_pk_bf16_f32 v5, v6, v7
	global_store_dwordx4 v241, v[2:5], s[24:25] offset:1024
	v_mul_f32_e32 v0, v7, v7
	v_fmac_f32_e32 v0, v6, v6
	v_mul_f32_e32 v3, v9, v9
	v_mul_f32_e32 v4, v11, v11
	v_mul_f32_e32 v2, v13, v13
	v_fmac_f32_e32 v3, v8, v8
	v_fmac_f32_e32 v4, v10, v10
	v_fmac_f32_e32 v2, v12, v12
	v_add_f32_e32 v3, v3, v4
	v_add_f32_e32 v2, v2, v3
	v_add_f32_e32 v0, v0, v2
	v_add_f32_e32 v0, v20, v0
	ds_bpermute_b32 v5, v229, v0
	v_pk_mul_f32 v[2:3], v[174:175], v[8:9]
	v_pk_mul_f32 v[8:9], v[176:177], v[6:7]
	v_cvt_pk_bf16_f32 v4, v2, v3
	v_pk_mul_f32 v[6:7], v[194:195], v[12:13]
	s_waitcnt lgkmcnt(0)
	v_add_f32_e32 v0, v0, v5
	ds_bpermute_b32 v2, v228, v0
	v_cvt_pk_bf16_f32 v5, v14, v15
	v_cvt_pk_bf16_f32 v6, v6, v7
	v_cvt_pk_bf16_f32 v7, v8, v9
	global_store_dwordx4 v28, v[4:7], s[26:27] offset:256
	s_and_saveexec_b64 s[2:3], s[8:9]
	s_cbranch_execz .LBB0_1103
	s_waitcnt lgkmcnt(0)
	v_add_f32_e32 v0, v0, v2
	v_mul_f32_e32 v0, 0x4b800000, v0
	v_trunc_f32_e32 v0, v0
	v_mul_f32_e32 v2, 0x2f800000, v0
	v_floor_f32_e32 v3, v2
	v_fmac_f32_e32 v0, 0xcf800000, v3
	v_cvt_u32_f32_e32 v2, v0
	v_cvt_u32_f32_e32 v3, v3
	global_atomic_add_x2 v[134:135], v[2:3], off offset:1408

; #define PG8_LAS __attribute__((address_space(3)))
; __device__ __forceinline__ float ssq_val(ssq_t v) { return (float)v * SSQ_IFX; }
;     __device__ __forceinline__ void prefetch(const Unit& u, int par, PG8_LAS unsigned char* lds, int tid) const {
;         PG8_LAS float* rp = (PG8_LAS float*)(lds + STAGE_BYTES + 5120) + par * 512;
;         if (tid < BM) rp[tid] = 1.0f / sqrtf(ssq_val(ssqx[u.pm * BM + tid]) * (1.0f / DM) + EPS);
;         else rp[tid] = shw[(size_t)((u.pm * BM) >> 12) * 7680 + u.pn * BM + (tid - BM)];
.LBB0_1155:
	s_andn2_saveexec_b64 s[14:15], s[2:3]
	s_cbranch_execz .LBB0_1157
	v_lshl_add_u32 v4, s28, 8, v0
	v_ashrrev_i32_e32 v5, 31, v4
	v_lshl_add_u64 v[4:5], v[4:5], 3, s[10:11]
	global_load_dwordx2 v[4:5], v[4:5], off
	s_waitcnt vmcnt(0) lgkmcnt(0)
	v_ffbh_u32_e32 v3, v5
	v_min_u32_e32 v3, 32, v3
	v_lshlrev_b64 v[4:5], v3, v[4:5]
	v_min_u32_e32 v4, 1, v4
	v_or_b32_e32 v4, v5, v4
	v_cvt_f32_u32_e32 v4, v4
	v_sub_u32_e32 v3, 32, v3
	v_ldexp_f32 v3, v4, v3
	v_mul_f32_e32 v3, 0x33800000, v3
	v_fmamk_f32 v3, v3, 0x3a800000, v226
	v_rsq_f32_e32 v3, v3
	s_nop 0

; #define PG8_LAS __attribute__((address_space(3)))
; __device__ __forceinline__ float ssq_val(ssq_t v) { return (float)v * SSQ_IFX; }
;     __device__ __forceinline__ void prefetch(const Unit& u, int par, PG8_LAS unsigned char* lds, int tid) const {
;         PG8_LAS float* rp = (PG8_LAS float*)(lds + STAGE_BYTES + 5120) + par * 512;
;         if (tid < BM) rp[tid] = 1.0f / sqrtf(ssq_val(ssqx[u.pm * BM + tid]) * (1.0f / DM) + EPS);
;         else rp[tid] = shw[(size_t)((u.pm * BM) >> 12) * 7680 + u.pn * BM + (tid - BM)];
.LBB0_1171:
	s_andn2_saveexec_b64 s[4:5], s[2:3]
	s_cbranch_execz .LBB0_1173
	s_waitcnt vmcnt(0) lgkmcnt(0)
	v_lshl_add_u32 v90, s18, 8, v0
	v_ashrrev_i32_e32 v91, 31, v90
	v_lshl_add_u64 v[90:91], v[90:91], 3, s[10:11]
	global_load_dwordx2 v[90:91], v[90:91], off
	s_waitcnt vmcnt(0) lgkmcnt(0)
	v_ffbh_u32_e32 v92, v91
	v_min_u32_e32 v92, 32, v92
	v_lshlrev_b64 v[90:91], v92, v[90:91]
	v_min_u32_e32 v90, 1, v90
	v_or_b32_e32 v90, v91, v90
	v_cvt_f32_u32_e32 v90, v90
	v_sub_u32_e32 v91, 32, v92
	v_ldexp_f32 v90, v90, v91
	v_mul_f32_e32 v90, 0x33800000, v90
	v_fmamk_f32 v90, v90, 0x3a800000, v226
	v_rsq_f32_e32 v90, v90
	s_nop 0
